# pipelined resid epilogue: batched x and gate loads 3-deep, counted vmcnt, stores not waited, tile-uniform gate hoisted
# speedup vs baseline: 1.0228x; 1.0228x over previous
; #define MFMA16(a, b, c) __builtin_amdgcn_mfma_f32_16x16x32_bf16((a), (b), (c), 0, 0, 0)
;     ...
;   for (int kt = 0; kt < nk; ++kt) {
;     const int buf = kt & 1;
;     const char* cA = smem + buf * STAGE + (wm * 32 * MI + r16) * 128;
;     const char* cB = smem + buf * STAGE + 32768 + (wn * 64 + r16) * 128;
; #pragma unroll
;     for (int k2 = 0; k2 < 2; ++k2) {
;       if (k2 == 1 && kt + 1 < nk) STAGE_TILE(buf ^ 1, (kt + 1) * 64)
;       const int po = ((4 * k2 + q4) ^ swz) * 16;
;       bf16x8 bf[4];
; #pragma unroll
;       for (int nt = 0; nt < 4; ++nt) bf[nt] = *(const bf16x8*)(cB + nt * 16 * 128 + po);
;       bf16x8 afc = *(const bf16x8*)(cA + po);
; #pragma unroll
;       for (int a = 0; a < MT; ++a) {
;         bf16x8 afn = afc;
;         if (a + 1 < MT) afn = *(const bf16x8*)(cA + (a + 1) * 16 * 128 + po);
;         __builtin_amdgcn_sched_barrier(0);
; #pragma unroll
;         for (int nt = 0; nt < 4; ++nt) acc[a][nt] = MFMA16(bf[nt], afc, acc[a][nt]);
;         __builtin_amdgcn_sched_barrier(0);
;         afc = afn;
;       }
;     }
;     asm volatile("s_waitcnt vmcnt(0)" ::: "memory");
;     __syncthreads();
;   }
.LBB0_48:
	s_and_b32 s42, s41, 0x10000
	s_add_i32 s43, s42, 0
	v_add_u32_e32 v174, s43, v147
	v_add_u32_e32 v162, v174, v146
	v_add_u32_e32 v149, s43, v148
	ds_read_b128 v[150:153], v162 offset:32768
	ds_read_b128 v[154:157], v162 offset:34816
	ds_read_b128 v[158:161], v162 offset:36864
	ds_read_b128 v[162:165], v162 offset:38912
	v_add_u32_e32 v175, v149, v146
	ds_read_b128 v[166:169], v175
	ds_read_b128 v[170:173], v175 offset:2048
	s_waitcnt lgkmcnt(1)
	v_mfma_f32_16x16x32_bf16 v[126:129], v[150:153], v[166:169], v[126:129]
	v_mfma_f32_16x16x32_bf16 v[122:125], v[154:157], v[166:169], v[122:125]
	v_mfma_f32_16x16x32_bf16 v[118:121], v[158:161], v[166:169], v[118:121]
	v_mfma_f32_16x16x32_bf16 v[114:117], v[162:165], v[166:169], v[114:117]
	ds_read_b128 v[166:169], v175 offset:4096
	s_waitcnt lgkmcnt(1)
	v_mfma_f32_16x16x32_bf16 v[110:113], v[150:153], v[170:173], v[110:113]
	v_mfma_f32_16x16x32_bf16 v[106:109], v[154:157], v[170:173], v[106:109]
	v_mfma_f32_16x16x32_bf16 v[102:105], v[158:161], v[170:173], v[102:105]
	v_mfma_f32_16x16x32_bf16 v[98:101], v[162:165], v[170:173], v[98:101]
	ds_read_b128 v[170:173], v175 offset:6144
	s_waitcnt lgkmcnt(1)
	v_mfma_f32_16x16x32_bf16 v[94:97], v[150:153], v[166:169], v[94:97]
	v_mfma_f32_16x16x32_bf16 v[90:93], v[154:157], v[166:169], v[90:93]
	v_mfma_f32_16x16x32_bf16 v[86:89], v[158:161], v[166:169], v[86:89]
	v_mfma_f32_16x16x32_bf16 v[82:85], v[162:165], v[166:169], v[82:85]
	ds_read_b128 v[166:169], v175 offset:8192
	s_waitcnt lgkmcnt(1)
	v_mfma_f32_16x16x32_bf16 v[78:81], v[150:153], v[170:173], v[78:81]
	v_mfma_f32_16x16x32_bf16 v[74:77], v[154:157], v[170:173], v[74:77]
	v_mfma_f32_16x16x32_bf16 v[70:73], v[158:161], v[170:173], v[70:73]
	v_mfma_f32_16x16x32_bf16 v[66:69], v[162:165], v[170:173], v[66:69]
	ds_read_b128 v[170:173], v175 offset:10240
	s_waitcnt lgkmcnt(1)
	v_mfma_f32_16x16x32_bf16 v[62:65], v[150:153], v[166:169], v[62:65]
	v_mfma_f32_16x16x32_bf16 v[58:61], v[154:157], v[166:169], v[58:61]
	v_mfma_f32_16x16x32_bf16 v[54:57], v[158:161], v[166:169], v[54:57]
	v_mfma_f32_16x16x32_bf16 v[50:53], v[162:165], v[166:169], v[50:53]
	ds_read_b128 v[166:169], v175 offset:12288
	s_waitcnt lgkmcnt(1)
	v_mfma_f32_16x16x32_bf16 v[46:49], v[150:153], v[170:173], v[46:49]
	v_mfma_f32_16x16x32_bf16 v[42:45], v[154:157], v[170:173], v[42:45]
	v_mfma_f32_16x16x32_bf16 v[38:41], v[158:161], v[170:173], v[38:41]
	v_mfma_f32_16x16x32_bf16 v[34:37], v[162:165], v[170:173], v[34:37]
	ds_read_b128 v[170:173], v175 offset:14336
	s_waitcnt lgkmcnt(1)
	v_mfma_f32_16x16x32_bf16 v[30:33], v[150:153], v[166:169], v[30:33]
	v_mfma_f32_16x16x32_bf16 v[26:29], v[154:157], v[166:169], v[26:29]
	v_mfma_f32_16x16x32_bf16 v[22:25], v[158:161], v[166:169], v[22:25]
	v_mfma_f32_16x16x32_bf16 v[18:21], v[162:165], v[166:169], v[18:21]
	s_waitcnt lgkmcnt(0)
	v_mfma_f32_16x16x32_bf16 v[14:17], v[150:153], v[170:173], v[14:17]
	v_mfma_f32_16x16x32_bf16 v[10:13], v[154:157], v[170:173], v[10:13]
	v_mfma_f32_16x16x32_bf16 v[6:9], v[158:161], v[170:173], v[6:9]
	v_mfma_f32_16x16x32_bf16 v[2:5], v[162:165], v[170:173], v[2:5]
	s_xor_b32 s42, s42, 0x10000
	v_add_u32_e32 v166, s42, v145
	v_lshl_add_u64 v[158:159], v[130:131], 0, s[16:17]
	s_mov_b64 s[42:43], 0x108080
	v_lshl_add_u64 v[160:161], v[158:159], 0, s[42:43]
	s_mov_b64 s[42:43], 0xb0080
	v_lshl_add_u64 v[162:163], v[158:159], 0, s[42:43]
	s_mov_b64 s[42:43], 0x58080
	v_add_u32_e32 v173, 0x2000, v166
	v_lshl_add_u64 v[164:165], v[158:159], 0, s[42:43]
	v_readfirstlane_b32 s42, v166
	v_add_u32_e32 v172, 0x4000, v166
	v_lshl_add_u64 v[158:159], v[158:159], 0, s[24:25]
	s_mov_b32 m0, s42
	v_readfirstlane_b32 s42, v173
	v_add_u32_e32 v171, 0x6000, v166
	global_load_lds_dwordx4 v[158:159], off
	s_mov_b32 m0, s42
	v_readfirstlane_b32 s42, v172
	v_add_u32_e32 v170, 0x8000, v166
	global_load_lds_dwordx4 v[164:165], off
	s_mov_b32 m0, s42
	v_readfirstlane_b32 s42, v171
	v_add_u32_e32 v169, 0xa000, v166
	global_load_lds_dwordx4 v[162:163], off
	s_mov_b32 m0, s42
	v_readfirstlane_b32 s42, v170
	v_add_u32_e32 v168, 0xc000, v166
	v_lshl_add_u64 v[156:157], v[138:139], 0, s[16:17]
	global_load_lds_dwordx4 v[160:161], off
	s_mov_b32 m0, s42
	v_readfirstlane_b32 s42, v169
	v_add_u32_e32 v167, 0xe000, v166
	v_lshl_add_u64 v[154:155], v[136:137], 0, s[16:17]
	global_load_lds_dwordx4 v[156:157], off
	s_mov_b32 m0, s42
	v_readfirstlane_b32 s42, v168
	v_lshl_add_u64 v[152:153], v[134:135], 0, s[16:17]
	global_load_lds_dwordx4 v[154:155], off
	s_mov_b32 m0, s42
	v_readfirstlane_b32 s42, v167
	v_lshl_add_u64 v[150:151], v[132:133], 0, s[16:17]
	global_load_lds_dwordx4 v[152:153], off
	s_mov_b32 m0, s42
	v_add_u32_e32 v162, v174, v144
	global_load_lds_dwordx4 v[150:151], off
	ds_read_b128 v[150:153], v162 offset:32768
	ds_read_b128 v[154:157], v162 offset:34816
	ds_read_b128 v[158:161], v162 offset:36864
	ds_read_b128 v[162:165], v162 offset:38912
	v_add_u32_e32 v149, v149, v144
	ds_read_b128 v[166:169], v149
	ds_read_b128 v[170:173], v149 offset:2048
	s_waitcnt lgkmcnt(0)
	v_mfma_f32_16x16x32_bf16 v[126:129], v[150:153], v[166:169], v[126:129]
	v_mfma_f32_16x16x32_bf16 v[122:125], v[154:157], v[166:169], v[122:125]
	v_mfma_f32_16x16x32_bf16 v[118:121], v[158:161], v[166:169], v[118:121]
	v_mfma_f32_16x16x32_bf16 v[114:117], v[162:165], v[166:169], v[114:117]
	ds_read_b128 v[166:169], v149 offset:4096
	v_mfma_f32_16x16x32_bf16 v[110:113], v[150:153], v[170:173], v[110:113]
	v_mfma_f32_16x16x32_bf16 v[106:109], v[154:157], v[170:173], v[106:109]
	v_mfma_f32_16x16x32_bf16 v[102:105], v[158:161], v[170:173], v[102:105]
	v_mfma_f32_16x16x32_bf16 v[98:101], v[162:165], v[170:173], v[98:101]
	ds_read_b128 v[170:173], v149 offset:6144
	s_waitcnt lgkmcnt(0)
; #define MFMA16(a, b, c) __builtin_amdgcn_mfma_f32_16x16x32_bf16((a), (b), (c), 0, 0, 0)
;     ...
;   for (int kt = 0; kt < nk; ++kt) {
;     const int buf = kt & 1;
;     const char* cA = smem + buf * STAGE + (wm * 32 * MI + r16) * 128;
;     const char* cB = smem + buf * STAGE + 32768 + (wn * 64 + r16) * 128;
; #pragma unroll
;     for (int k2 = 0; k2 < 2; ++k2) {
;       if (k2 == 1 && kt + 1 < nk) STAGE_TILE(buf ^ 1, (kt + 1) * 64)
;       const int po = ((4 * k2 + q4) ^ swz) * 16;
;       bf16x8 bf[4];
; #pragma unroll
;       for (int nt = 0; nt < 4; ++nt) bf[nt] = *(const bf16x8*)(cB + nt * 16 * 128 + po);
;       bf16x8 afc = *(const bf16x8*)(cA + po);
; #pragma unroll
;       for (int a = 0; a < MT; ++a) {
;         bf16x8 afn = afc;
;         if (a + 1 < MT) afn = *(const bf16x8*)(cA + (a + 1) * 16 * 128 + po);
;         __builtin_amdgcn_sched_barrier(0);
; #pragma unroll
;         for (int nt = 0; nt < 4; ++nt) acc[a][nt] = MFMA16(bf[nt], afc, acc[a][nt]);
;         __builtin_amdgcn_sched_barrier(0);
;         afc = afn;
;       }
;     }
;     asm volatile("s_waitcnt vmcnt(0)" ::: "memory");
;     __syncthreads();
;   }
	v_mfma_f32_16x16x32_bf16 v[94:97], v[150:153], v[166:169], v[94:97]
	v_mfma_f32_16x16x32_bf16 v[90:93], v[154:157], v[166:169], v[90:93]
	v_mfma_f32_16x16x32_bf16 v[86:89], v[158:161], v[166:169], v[86:89]
	v_mfma_f32_16x16x32_bf16 v[82:85], v[162:165], v[166:169], v[82:85]
	ds_read_b128 v[166:169], v149 offset:8192
	v_mfma_f32_16x16x32_bf16 v[78:81], v[150:153], v[170:173], v[78:81]
	v_mfma_f32_16x16x32_bf16 v[74:77], v[154:157], v[170:173], v[74:77]
	v_mfma_f32_16x16x32_bf16 v[70:73], v[158:161], v[170:173], v[70:73]
	v_mfma_f32_16x16x32_bf16 v[66:69], v[162:165], v[170:173], v[66:69]
	ds_read_b128 v[170:173], v149 offset:10240
	s_waitcnt lgkmcnt(0)
	v_mfma_f32_16x16x32_bf16 v[62:65], v[150:153], v[166:169], v[62:65]
	v_mfma_f32_16x16x32_bf16 v[58:61], v[154:157], v[166:169], v[58:61]
	v_mfma_f32_16x16x32_bf16 v[54:57], v[158:161], v[166:169], v[54:57]
	v_mfma_f32_16x16x32_bf16 v[50:53], v[162:165], v[166:169], v[50:53]
	ds_read_b128 v[166:169], v149 offset:12288
	v_mfma_f32_16x16x32_bf16 v[46:49], v[150:153], v[170:173], v[46:49]
	v_mfma_f32_16x16x32_bf16 v[42:45], v[154:157], v[170:173], v[42:45]
	v_mfma_f32_16x16x32_bf16 v[38:41], v[158:161], v[170:173], v[38:41]
	v_mfma_f32_16x16x32_bf16 v[34:37], v[162:165], v[170:173], v[34:37]
	ds_read_b128 v[170:173], v149 offset:14336
	s_waitcnt lgkmcnt(0)
	v_mfma_f32_16x16x32_bf16 v[30:33], v[150:153], v[166:169], v[30:33]
	v_mfma_f32_16x16x32_bf16 v[26:29], v[154:157], v[166:169], v[26:29]
	v_mfma_f32_16x16x32_bf16 v[22:25], v[158:161], v[166:169], v[22:25]
	v_mfma_f32_16x16x32_bf16 v[18:21], v[162:165], v[166:169], v[18:21]
	v_mfma_f32_16x16x32_bf16 v[14:17], v[150:153], v[170:173], v[14:17]
	v_mfma_f32_16x16x32_bf16 v[10:13], v[154:157], v[170:173], v[10:13]
	v_mfma_f32_16x16x32_bf16 v[6:9], v[158:161], v[170:173], v[6:9]
	v_mfma_f32_16x16x32_bf16 v[2:5], v[162:165], v[170:173], v[2:5]
	s_waitcnt vmcnt(0)
	s_add_u32 s16, s16, 0x80
	s_addc_u32 s17, s17, 0
	s_add_i32 s41, s41, 0x10000
	s_cmpk_eq_i32 s16, 0x1580
	s_waitcnt vmcnt(0)
	s_barrier
	s_cbranch_scc0 .LBB0_48
	s_add_i32 s16, 0, 0x10000
	v_add_u32_e32 v138, s16, v148
	v_readlane_b32 s16, v254, 18
	s_nop 1
	v_add_u32_e32 v139, s16, v147
	v_add_u32_e32 v145, v139, v146
	ds_read_b128 v[130:133], v145
	ds_read_b128 v[134:137], v145 offset:2048
	ds_read_b128 v[148:151], v145 offset:4096
	ds_read_b128 v[152:155], v145 offset:6144
	v_add_u32_e32 v145, v138, v146
	ds_read_b128 v[156:159], v145
	ds_read_b128 v[160:163], v145 offset:2048
	s_waitcnt lgkmcnt(1)
	v_mfma_f32_16x16x32_bf16 v[126:129], v[130:133], v[156:159], v[126:129]
	v_mfma_f32_16x16x32_bf16 v[122:125], v[134:137], v[156:159], v[122:125]
	v_mfma_f32_16x16x32_bf16 v[118:121], v[148:151], v[156:159], v[118:121]
	v_mfma_f32_16x16x32_bf16 v[114:117], v[152:155], v[156:159], v[114:117]
	ds_read_b128 v[156:159], v145 offset:4096
	s_waitcnt lgkmcnt(1)
	v_mfma_f32_16x16x32_bf16 v[110:113], v[130:133], v[160:163], v[110:113]
	v_mfma_f32_16x16x32_bf16 v[106:109], v[134:137], v[160:163], v[106:109]
	v_mfma_f32_16x16x32_bf16 v[102:105], v[148:151], v[160:163], v[102:105]
	v_mfma_f32_16x16x32_bf16 v[98:101], v[152:155], v[160:163], v[98:101]
	ds_read_b128 v[160:163], v145 offset:6144
	s_waitcnt lgkmcnt(1)
	v_mfma_f32_16x16x32_bf16 v[94:97], v[130:133], v[156:159], v[94:97]
	v_mfma_f32_16x16x32_bf16 v[90:93], v[134:137], v[156:159], v[90:93]
	v_mfma_f32_16x16x32_bf16 v[86:89], v[148:151], v[156:159], v[86:89]
	v_mfma_f32_16x16x32_bf16 v[82:85], v[152:155], v[156:159], v[82:85]
	ds_read_b128 v[156:159], v145 offset:8192
	s_waitcnt lgkmcnt(1)
	v_mfma_f32_16x16x32_bf16 v[78:81], v[130:133], v[160:163], v[78:81]
	v_mfma_f32_16x16x32_bf16 v[74:77], v[134:137], v[160:163], v[74:77]
	v_mfma_f32_16x16x32_bf16 v[70:73], v[148:151], v[160:163], v[70:73]
	v_mfma_f32_16x16x32_bf16 v[66:69], v[152:155], v[160:163], v[66:69]
	ds_read_b128 v[160:163], v145 offset:10240
	s_waitcnt lgkmcnt(1)
	v_mfma_f32_16x16x32_bf16 v[62:65], v[130:133], v[156:159], v[62:65]
	v_mfma_f32_16x16x32_bf16 v[58:61], v[134:137], v[156:159], v[58:61]
	v_mfma_f32_16x16x32_bf16 v[54:57], v[148:151], v[156:159], v[54:57]
	v_mfma_f32_16x16x32_bf16 v[50:53], v[152:155], v[156:159], v[50:53]
	ds_read_b128 v[156:159], v145 offset:12288
	s_waitcnt lgkmcnt(1)
	v_mfma_f32_16x16x32_bf16 v[46:49], v[130:133], v[160:163], v[46:49]
	v_mfma_f32_16x16x32_bf16 v[42:45], v[134:137], v[160:163], v[42:45]
	v_mfma_f32_16x16x32_bf16 v[38:41], v[148:151], v[160:163], v[38:41]
	v_mfma_f32_16x16x32_bf16 v[34:37], v[152:155], v[160:163], v[34:37]
	ds_read_b128 v[160:163], v145 offset:14336
	s_waitcnt lgkmcnt(1)
	v_mfma_f32_16x16x32_bf16 v[30:33], v[130:133], v[156:159], v[30:33]
	v_mfma_f32_16x16x32_bf16 v[26:29], v[134:137], v[156:159], v[26:29]
	v_mfma_f32_16x16x32_bf16 v[22:25], v[148:151], v[156:159], v[22:25]
	v_mfma_f32_16x16x32_bf16 v[18:21], v[152:155], v[156:159], v[18:21]
	s_waitcnt lgkmcnt(0)
	v_mfma_f32_16x16x32_bf16 v[14:17], v[130:133], v[160:163], v[14:17]
	v_mfma_f32_16x16x32_bf16 v[10:13], v[134:137], v[160:163], v[10:13]
	v_mfma_f32_16x16x32_bf16 v[6:9], v[148:151], v[160:163], v[6:9]
	v_mfma_f32_16x16x32_bf16 v[2:5], v[152:155], v[160:163], v[2:5]
	v_add_u32_e32 v139, v139, v144
	ds_read_b128 v[130:133], v139
	ds_read_b128 v[134:137], v139 offset:2048
	ds_read_b128 v[146:149], v139 offset:4096
	ds_read_b128 v[150:153], v139 offset:6144
	v_add_u32_e32 v138, v138, v144
	ds_read_b128 v[154:157], v138
	ds_read_b128 v[158:161], v138 offset:2048
	s_waitcnt lgkmcnt(1)
; #define MFMA16(a, b, c) __builtin_amdgcn_mfma_f32_16x16x32_bf16((a), (b), (c), 0, 0, 0)
;     ...
;   for (int kt = 0; kt < nk; ++kt) {
;     const int buf = kt & 1;
;     const char* cA = smem + buf * STAGE + (wm * 32 * MI + r16) * 128;
;     const char* cB = smem + buf * STAGE + 32768 + (wn * 64 + r16) * 128;
; #pragma unroll
;     for (int k2 = 0; k2 < 2; ++k2) {
;       if (k2 == 1 && kt + 1 < nk) STAGE_TILE(buf ^ 1, (kt + 1) * 64)
;       const int po = ((4 * k2 + q4) ^ swz) * 16;
;       bf16x8 bf[4];
; #pragma unroll
;       for (int nt = 0; nt < 4; ++nt) bf[nt] = *(const bf16x8*)(cB + nt * 16 * 128 + po);
;       bf16x8 afc = *(const bf16x8*)(cA + po);
; #pragma unroll
;       for (int a = 0; a < MT; ++a) {
;         bf16x8 afn = afc;
;         if (a + 1 < MT) afn = *(const bf16x8*)(cA + (a + 1) * 16 * 128 + po);
;         __builtin_amdgcn_sched_barrier(0);
; #pragma unroll
;         for (int nt = 0; nt < 4; ++nt) acc[a][nt] = MFMA16(bf[nt], afc, acc[a][nt]);
;         __builtin_amdgcn_sched_barrier(0);
;         afc = afn;
;       }
;     }
;     asm volatile("s_waitcnt vmcnt(0)" ::: "memory");
;     __syncthreads();
;   }
; DI void phase_resid(char* smem, const Params& p, int layer, const bf16_t* A, int K, const bf16_t* W, int gate_idx, bool first) {
;     ...
;   auto ep = [&](int row, int col, float v0, float v1, float v2, float v3) {
;     const int b = row / TT, t = row - b * TT;
;     const float4 g = *(const float4*)(p.mod + (size_t)(layer * 5 + (t < CTXL ? 4 : b)) * 6144 + gate_idx * 1024 + col);
;     const float4 xo = *(const float4*)(xsrc_row(p, first, row) + col);
;     *(float4*)(xdst_row(p, row) + col) = make_float4(xo.x + g.x * v0, xo.y + g.y * v1, xo.z + g.z * v2, xo.w + g.w * v3);
;   };
	v_mfma_f32_16x16x32_bf16 v[126:129], v[130:133], v[154:157], v[126:129]
	v_mfma_f32_16x16x32_bf16 v[122:125], v[134:137], v[154:157], v[122:125]
	v_mfma_f32_16x16x32_bf16 v[118:121], v[146:149], v[154:157], v[118:121]
	v_mfma_f32_16x16x32_bf16 v[114:117], v[150:153], v[154:157], v[114:117]
	ds_read_b128 v[154:157], v138 offset:4096
	s_waitcnt lgkmcnt(1)
	v_mfma_f32_16x16x32_bf16 v[110:113], v[130:133], v[158:161], v[110:113]
	v_mfma_f32_16x16x32_bf16 v[106:109], v[134:137], v[158:161], v[106:109]
	v_mfma_f32_16x16x32_bf16 v[102:105], v[146:149], v[158:161], v[102:105]
	v_mfma_f32_16x16x32_bf16 v[98:101], v[150:153], v[158:161], v[98:101]
	ds_read_b128 v[158:161], v138 offset:6144
	s_waitcnt lgkmcnt(1)
	v_mfma_f32_16x16x32_bf16 v[94:97], v[130:133], v[154:157], v[94:97]
	v_mfma_f32_16x16x32_bf16 v[90:93], v[134:137], v[154:157], v[90:93]
	v_mfma_f32_16x16x32_bf16 v[86:89], v[146:149], v[154:157], v[86:89]
	v_mfma_f32_16x16x32_bf16 v[82:85], v[150:153], v[154:157], v[82:85]
	ds_read_b128 v[154:157], v138 offset:8192
	s_waitcnt lgkmcnt(1)
	v_mfma_f32_16x16x32_bf16 v[78:81], v[130:133], v[158:161], v[78:81]
	v_mfma_f32_16x16x32_bf16 v[74:77], v[134:137], v[158:161], v[74:77]
	v_mfma_f32_16x16x32_bf16 v[70:73], v[146:149], v[158:161], v[70:73]
	v_mfma_f32_16x16x32_bf16 v[66:69], v[150:153], v[158:161], v[66:69]
	ds_read_b128 v[158:161], v138 offset:10240
	s_waitcnt lgkmcnt(1)
	v_mfma_f32_16x16x32_bf16 v[62:65], v[130:133], v[154:157], v[62:65]
	v_mfma_f32_16x16x32_bf16 v[58:61], v[134:137], v[154:157], v[58:61]
	v_mfma_f32_16x16x32_bf16 v[54:57], v[146:149], v[154:157], v[54:57]
	v_mfma_f32_16x16x32_bf16 v[50:53], v[150:153], v[154:157], v[50:53]
	ds_read_b128 v[154:157], v138 offset:12288
	s_waitcnt lgkmcnt(1)
	v_mfma_f32_16x16x32_bf16 v[46:49], v[130:133], v[158:161], v[46:49]
	v_mfma_f32_16x16x32_bf16 v[42:45], v[134:137], v[158:161], v[42:45]
	v_mfma_f32_16x16x32_bf16 v[38:41], v[146:149], v[158:161], v[38:41]
	v_mfma_f32_16x16x32_bf16 v[34:37], v[150:153], v[158:161], v[34:37]
	ds_read_b128 v[158:161], v138 offset:14336
	s_waitcnt lgkmcnt(1)
	v_mfma_f32_16x16x32_bf16 v[30:33], v[130:133], v[154:157], v[30:33]
	v_mfma_f32_16x16x32_bf16 v[26:29], v[134:137], v[154:157], v[26:29]
	v_mfma_f32_16x16x32_bf16 v[22:25], v[146:149], v[154:157], v[22:25]
	v_mfma_f32_16x16x32_bf16 v[18:21], v[150:153], v[154:157], v[18:21]
	s_waitcnt lgkmcnt(0)
	v_mfma_f32_16x16x32_bf16 v[14:17], v[130:133], v[158:161], v[14:17]
	v_mfma_f32_16x16x32_bf16 v[10:13], v[134:137], v[158:161], v[10:13]
	v_mfma_f32_16x16x32_bf16 v[6:9], v[146:149], v[158:161], v[6:9]
	v_mfma_f32_16x16x32_bf16 v[2:5], v[150:153], v[158:161], v[2:5]
	v_or_b32_e32 v131, s40, v142
	v_lshlrev_b32_e32 v130, 6, v143
	v_lshl_add_u32 v142, v140, 7, v131
	v_lshlrev_b32_e32 v131, 2, v141
	v_or3_b32 v134, v130, v131, s39
	v_mul_hi_i32 v130, v142, s1
	v_lshrrev_b32_e32 v131, 31, v130
	v_ashrrev_i32_e32 v130, 11, v130
	v_add_u32_e32 v130, v130, v131
	v_mad_i32_i24 v131, v130, s90, v142
	s_movk_i32 s39, 0x100
	v_cmp_gt_i32_e32 vcc, s39, v131
	v_add_u32_e32 v132, 0xffffff00, v131
	v_ashrrev_i32_e32 v133, 31, v131
	v_readlane_b32 s40, v254, 1
	v_cndmask_b32_e64 v135, v130, 4, vcc
	v_cndmask_b32_e32 v133, 0, v133, vcc
	v_cndmask_b32_e32 v132, v132, v131, vcc
	v_ashrrev_i32_e32 v131, 31, v130
	v_cndmask_b32_e64 v136, 25, 20, vcc
	v_readlane_b32 s41, v254, 2
	v_lshlrev_b64 v[140:141], v136, v[130:131]
	v_lshlrev_b64 v[150:151], 12, v[132:133]
	v_add_u32_e32 v130, s37, v135
	v_mov_b64_e32 v[132:133], s[40:41]
	s_movk_i32 s40, 0x6000
	v_readlane_b32 s42, v254, 3
	v_readlane_b32 s43, v254, 4
	v_mad_i64_i32 v[130:131], s[16:17], v130, s40, v[132:133]
	s_mov_b64 s[42:43], 0x5000
	v_ashrrev_i32_e32 v135, 31, v134
	v_readlane_b32 s16, v252, 26
	v_lshl_add_u64 v[136:137], v[130:131], 0, s[42:43]
	v_lshlrev_b64 v[130:131], 2, v[134:135]
	v_mov_b32_e32 v135, s16
	v_readlane_b32 s16, v252, 28
	s_waitcnt vmcnt(0)
	s_barrier
	s_nop 0
	v_mov_b32_e32 v143, s16
	v_readlane_b32 s16, v252, 25
	v_cndmask_b32_e32 v139, v135, v143, vcc
	s_nop 0
	v_mov_b32_e32 v144, s16
	v_readlane_b32 s16, v252, 27
	v_readlane_b32 s68, v252, 5
	v_readlane_b32 s80, v252, 17
	v_mov_b32_e32 v145, s16
	v_cndmask_b32_e32 v138, v144, v145, vcc
	global_load_dwordx2 v[138:139], v[138:139], off
	v_readlane_b32 s81, v252, 18
	v_readlane_b32 s82, v252, 19
	v_readlane_b32 s83, v252, 20
	v_mov_b32_e32 v146, s81
	v_mov_b32_e32 v148, s80
	v_mov_b32_e32 v147, s83
	v_mov_b32_e32 v149, s82
	v_cndmask_b32_e32 v155, v146, v147, vcc
	v_cndmask_b32_e32 v154, v148, v149, vcc
	v_lshl_add_u64 v[152:153], v[136:137], 0, v[130:131]
	s_add_i32 s38, s38, s30
	s_cmp_gt_i32 s38, 31
	v_readlane_b32 s44, v254, 5
	v_readlane_b32 s45, v254, 6
	v_readlane_b32 s46, v254, 7
	v_readlane_b32 s47, v254, 8
	v_readlane_b32 s48, v254, 9
	v_readlane_b32 s49, v254, 10
	v_readlane_b32 s50, v254, 11
	v_readlane_b32 s51, v254, 12
	v_readlane_b32 s52, v254, 13
	v_readlane_b32 s53, v254, 14
	v_readlane_b32 s54, v254, 15
	v_readlane_b32 s55, v254, 16
	v_readlane_b32 s69, v252, 6
	v_readlane_b32 s70, v252, 7
	v_readlane_b32 s71, v252, 8
	v_readlane_b32 s72, v252, 9
	v_readlane_b32 s73, v252, 10
	v_readlane_b32 s74, v252, 11
	v_readlane_b32 s75, v252, 12
	v_readlane_b32 s76, v252, 13
	v_readlane_b32 s77, v252, 14
	v_readlane_b32 s78, v252, 15
	v_readlane_b32 s79, v252, 16
	s_waitcnt vmcnt(0)
;     ...
; #pragma unroll
;     for (int a = 0; a < MT; ++a)
; #pragma unroll
;       for (int nt = 0; nt < 4; ++nt)
;         ep(row0 + 16 * a, cbw + 16 * nt + 4 * q4, acc[a][nt][0], acc[a][nt][1], acc[a][nt][2], acc[a][nt][3]);
; DI void phase_resid(char* smem, const Params& p, int layer, const bf16_t* A, int K, const bf16_t* W, int gate_idx, bool first) {
;     ...
;   auto ep = [&](int row, int col, float v0, float v1, float v2, float v3) {
;     const int b = row / TT, t = row - b * TT;
;     const float4 g = *(const float4*)(p.mod + (size_t)(layer * 5 + (t < CTXL ? 4 : b)) * 6144 + gate_idx * 1024 + col);
;     const float4 xo = *(const float4*)(xsrc_row(p, first, row) + col);
;     *(float4*)(xdst_row(p, row) + col) = make_float4(xo.x + g.x * v0, xo.y + g.y * v1, xo.z + g.z * v2, xo.w + g.w * v3);
;   };
	v_lshl_add_u64 v[138:139], v[138:139], 0, v[140:141]
	v_lshl_add_u64 v[138:139], v[138:139], 0, v[150:151]
	v_lshl_add_u64 v[140:141], v[154:155], 0, v[140:141]
	v_lshl_add_u64 v[138:139], v[138:139], 0, v[130:131]
	v_lshl_add_u64 v[140:141], v[140:141], 0, v[150:151]
	v_lshl_add_u64 v[140:141], v[140:141], 0, v[130:131]
	s_cselect_b64 s[16:17], -1, 0
	global_load_dwordx4 v[156:159], v[152:153], off
	global_load_dwordx4 v[160:163], v[152:153], off offset:64
	global_load_dwordx4 v[164:167], v[152:153], off offset:128
	global_load_dwordx4 v[168:171], v[152:153], off offset:192
	global_load_dwordx4 v[172:175], v[138:139], off
	global_load_dwordx4 v[176:179], v[138:139], off offset:64
	global_load_dwordx4 v[180:183], v[138:139], off offset:128
	global_load_dwordx4 v[184:187], v[138:139], off offset:192
	v_add_co_u32_e32 v138, vcc, 0x10000, v138
	s_nop 1
	v_addc_co_u32_e32 v139, vcc, 0, v139, vcc
	global_load_dwordx4 v[198:201], v[138:139], off
	global_load_dwordx4 v[202:205], v[138:139], off offset:64
	global_load_dwordx4 v[206:209], v[138:139], off offset:128
	global_load_dwordx4 v[210:213], v[138:139], off offset:192
	v_add_co_u32_e32 v138, vcc, 0x10000, v138
	s_nop 1
	v_addc_co_u32_e32 v139, vcc, 0, v139, vcc
	global_load_dwordx4 v[214:217], v[138:139], off
	global_load_dwordx4 v[218:221], v[138:139], off offset:64
	global_load_dwordx4 v[222:225], v[138:139], off offset:128
	global_load_dwordx4 v[142:145], v[138:139], off offset:192
	v_add_co_u32_e32 v138, vcc, 0x10000, v138
	s_nop 1
	v_addc_co_u32_e32 v139, vcc, 0, v139, vcc
	s_waitcnt vmcnt(8)
	v_pk_fma_f32 v[126:127], v[126:127], v[156:157], v[172:173]
	v_pk_fma_f32 v[128:129], v[128:129], v[158:159], v[174:175]
	v_pk_fma_f32 v[122:123], v[122:123], v[160:161], v[176:177]
	v_pk_fma_f32 v[124:125], v[124:125], v[162:163], v[178:179]
	v_pk_fma_f32 v[118:119], v[118:119], v[164:165], v[180:181]
	v_pk_fma_f32 v[120:121], v[120:121], v[166:167], v[182:183]
	v_pk_fma_f32 v[114:115], v[114:115], v[168:169], v[184:185]
	v_pk_fma_f32 v[116:117], v[116:117], v[170:171], v[186:187]
	global_store_dwordx4 v[140:141], v[126:129], off
	global_store_dwordx4 v[140:141], v[122:125], off offset:64
	global_store_dwordx4 v[140:141], v[118:121], off offset:128
	global_store_dwordx4 v[140:141], v[114:117], off offset:192
	v_add_co_u32_e32 v140, vcc, 0x10000, v140
	s_nop 1
	v_addc_co_u32_e32 v141, vcc, 0, v141, vcc
	global_load_dwordx4 v[172:175], v[138:139], off
	global_load_dwordx4 v[176:179], v[138:139], off offset:64
	global_load_dwordx4 v[180:183], v[138:139], off offset:128
	global_load_dwordx4 v[184:187], v[138:139], off offset:192
	v_add_co_u32_e32 v138, vcc, 0x10000, v138
	s_nop 1
	v_addc_co_u32_e32 v139, vcc, 0, v139, vcc
	s_waitcnt vmcnt(12)
	v_pk_fma_f32 v[110:111], v[110:111], v[156:157], v[198:199]
	v_pk_fma_f32 v[112:113], v[112:113], v[158:159], v[200:201]
	v_pk_fma_f32 v[106:107], v[106:107], v[160:161], v[202:203]
	v_pk_fma_f32 v[108:109], v[108:109], v[162:163], v[204:205]
	v_pk_fma_f32 v[102:103], v[102:103], v[164:165], v[206:207]
	v_pk_fma_f32 v[104:105], v[104:105], v[166:167], v[208:209]
	v_pk_fma_f32 v[98:99], v[98:99], v[168:169], v[210:211]
	v_pk_fma_f32 v[100:101], v[100:101], v[170:171], v[212:213]
	global_store_dwordx4 v[140:141], v[110:113], off
	global_store_dwordx4 v[140:141], v[106:109], off offset:64
	global_store_dwordx4 v[140:141], v[102:105], off offset:128
	global_store_dwordx4 v[140:141], v[98:101], off offset:192
	v_add_co_u32_e32 v140, vcc, 0x10000, v140
	s_nop 1
	v_addc_co_u32_e32 v141, vcc, 0, v141, vcc
	global_load_dwordx4 v[198:201], v[138:139], off
	global_load_dwordx4 v[202:205], v[138:139], off offset:64
	global_load_dwordx4 v[206:209], v[138:139], off offset:128
	global_load_dwordx4 v[210:213], v[138:139], off offset:192
	v_add_co_u32_e32 v138, vcc, 0x10000, v138
	s_nop 1
	v_addc_co_u32_e32 v139, vcc, 0, v139, vcc
	s_waitcnt vmcnt(16)
	v_pk_fma_f32 v[94:95], v[94:95], v[156:157], v[214:215]
	v_pk_fma_f32 v[96:97], v[96:97], v[158:159], v[216:217]
	v_pk_fma_f32 v[90:91], v[90:91], v[160:161], v[218:219]
	v_pk_fma_f32 v[92:93], v[92:93], v[162:163], v[220:221]
	v_pk_fma_f32 v[86:87], v[86:87], v[164:165], v[222:223]
	v_pk_fma_f32 v[88:89], v[88:89], v[166:167], v[224:225]
	v_pk_fma_f32 v[82:83], v[82:83], v[168:169], v[142:143]
	v_pk_fma_f32 v[84:85], v[84:85], v[170:171], v[144:145]
	global_store_dwordx4 v[140:141], v[94:97], off
	global_store_dwordx4 v[140:141], v[90:93], off offset:64
	global_store_dwordx4 v[140:141], v[86:89], off offset:128
	global_store_dwordx4 v[140:141], v[82:85], off offset:192
	v_add_co_u32_e32 v140, vcc, 0x10000, v140
	s_nop 1
	v_addc_co_u32_e32 v141, vcc, 0, v141, vcc
	global_load_dwordx4 v[214:217], v[138:139], off
	global_load_dwordx4 v[218:221], v[138:139], off offset:64
	global_load_dwordx4 v[222:225], v[138:139], off offset:128
	global_load_dwordx4 v[142:145], v[138:139], off offset:192
	v_add_co_u32_e32 v138, vcc, 0x10000, v138
	s_nop 1
	v_addc_co_u32_e32 v139, vcc, 0, v139, vcc
	s_waitcnt vmcnt(16)
;     ...
; #pragma unroll
;     for (int a = 0; a < MT; ++a)
; #pragma unroll
;       for (int nt = 0; nt < 4; ++nt)
;         ep(row0 + 16 * a, cbw + 16 * nt + 4 * q4, acc[a][nt][0], acc[a][nt][1], acc[a][nt][2], acc[a][nt][3]);
; DI void phase_resid(char* smem, const Params& p, int layer, const bf16_t* A, int K, const bf16_t* W, int gate_idx, bool first) {
;     ...
;   auto ep = [&](int row, int col, float v0, float v1, float v2, float v3) {
;     const int b = row / TT, t = row - b * TT;
;     const float4 g = *(const float4*)(p.mod + (size_t)(layer * 5 + (t < CTXL ? 4 : b)) * 6144 + gate_idx * 1024 + col);
;     const float4 xo = *(const float4*)(xsrc_row(p, first, row) + col);
;     *(float4*)(xdst_row(p, row) + col) = make_float4(xo.x + g.x * v0, xo.y + g.y * v1, xo.z + g.z * v2, xo.w + g.w * v3);
;   };
	v_pk_fma_f32 v[78:79], v[78:79], v[156:157], v[172:173]
	v_pk_fma_f32 v[80:81], v[80:81], v[158:159], v[174:175]
	v_pk_fma_f32 v[74:75], v[74:75], v[160:161], v[176:177]
	v_pk_fma_f32 v[76:77], v[76:77], v[162:163], v[178:179]
	v_pk_fma_f32 v[70:71], v[70:71], v[164:165], v[180:181]
	v_pk_fma_f32 v[72:73], v[72:73], v[166:167], v[182:183]
	v_pk_fma_f32 v[66:67], v[66:67], v[168:169], v[184:185]
	v_pk_fma_f32 v[68:69], v[68:69], v[170:171], v[186:187]
	global_store_dwordx4 v[140:141], v[78:81], off
	global_store_dwordx4 v[140:141], v[74:77], off offset:64
	global_store_dwordx4 v[140:141], v[70:73], off offset:128
	global_store_dwordx4 v[140:141], v[66:69], off offset:192
	v_add_co_u32_e32 v140, vcc, 0x10000, v140
	s_nop 1
	v_addc_co_u32_e32 v141, vcc, 0, v141, vcc
	global_load_dwordx4 v[172:175], v[138:139], off
	global_load_dwordx4 v[176:179], v[138:139], off offset:64
	global_load_dwordx4 v[180:183], v[138:139], off offset:128
	global_load_dwordx4 v[184:187], v[138:139], off offset:192
	v_add_co_u32_e32 v138, vcc, 0x10000, v138
	s_nop 1
	v_addc_co_u32_e32 v139, vcc, 0, v139, vcc
	s_waitcnt vmcnt(16)
	v_pk_fma_f32 v[62:63], v[62:63], v[156:157], v[198:199]
	v_pk_fma_f32 v[64:65], v[64:65], v[158:159], v[200:201]
	v_pk_fma_f32 v[58:59], v[58:59], v[160:161], v[202:203]
	v_pk_fma_f32 v[60:61], v[60:61], v[162:163], v[204:205]
	v_pk_fma_f32 v[54:55], v[54:55], v[164:165], v[206:207]
	v_pk_fma_f32 v[56:57], v[56:57], v[166:167], v[208:209]
	v_pk_fma_f32 v[50:51], v[50:51], v[168:169], v[210:211]
	v_pk_fma_f32 v[52:53], v[52:53], v[170:171], v[212:213]
	global_store_dwordx4 v[140:141], v[62:65], off
	global_store_dwordx4 v[140:141], v[58:61], off offset:64
	global_store_dwordx4 v[140:141], v[54:57], off offset:128
	global_store_dwordx4 v[140:141], v[50:53], off offset:192
	v_add_co_u32_e32 v140, vcc, 0x10000, v140
	s_nop 1
	v_addc_co_u32_e32 v141, vcc, 0, v141, vcc
	global_load_dwordx4 v[198:201], v[138:139], off
	global_load_dwordx4 v[202:205], v[138:139], off offset:64
	global_load_dwordx4 v[206:209], v[138:139], off offset:128
	global_load_dwordx4 v[210:213], v[138:139], off offset:192
	s_waitcnt vmcnt(16)
	v_pk_fma_f32 v[46:47], v[46:47], v[156:157], v[214:215]
	v_pk_fma_f32 v[48:49], v[48:49], v[158:159], v[216:217]
	v_pk_fma_f32 v[42:43], v[42:43], v[160:161], v[218:219]
	v_pk_fma_f32 v[44:45], v[44:45], v[162:163], v[220:221]
	v_pk_fma_f32 v[38:39], v[38:39], v[164:165], v[222:223]
	v_pk_fma_f32 v[40:41], v[40:41], v[166:167], v[224:225]
	v_pk_fma_f32 v[34:35], v[34:35], v[168:169], v[142:143]
	v_pk_fma_f32 v[36:37], v[36:37], v[170:171], v[144:145]
	global_store_dwordx4 v[140:141], v[46:49], off
	global_store_dwordx4 v[140:141], v[42:45], off offset:64
	global_store_dwordx4 v[140:141], v[38:41], off offset:128
	global_store_dwordx4 v[140:141], v[34:37], off offset:192
	v_add_co_u32_e32 v140, vcc, 0x10000, v140
	s_nop 1
	v_addc_co_u32_e32 v141, vcc, 0, v141, vcc
	s_waitcnt vmcnt(12)
	v_pk_fma_f32 v[30:31], v[30:31], v[156:157], v[172:173]
	v_pk_fma_f32 v[32:33], v[32:33], v[158:159], v[174:175]
	v_pk_fma_f32 v[26:27], v[26:27], v[160:161], v[176:177]
	v_pk_fma_f32 v[28:29], v[28:29], v[162:163], v[178:179]
	v_pk_fma_f32 v[22:23], v[22:23], v[164:165], v[180:181]
	v_pk_fma_f32 v[24:25], v[24:25], v[166:167], v[182:183]
	v_pk_fma_f32 v[18:19], v[18:19], v[168:169], v[184:185]
	v_pk_fma_f32 v[20:21], v[20:21], v[170:171], v[186:187]
	global_store_dwordx4 v[140:141], v[30:33], off
	global_store_dwordx4 v[140:141], v[26:29], off offset:64
	global_store_dwordx4 v[140:141], v[22:25], off offset:128
	global_store_dwordx4 v[140:141], v[18:21], off offset:192
	v_add_co_u32_e32 v140, vcc, 0x10000, v140
	s_nop 1
	v_addc_co_u32_e32 v141, vcc, 0, v141, vcc
	s_waitcnt vmcnt(8)
	v_pk_fma_f32 v[14:15], v[14:15], v[156:157], v[198:199]
	v_pk_fma_f32 v[16:17], v[16:17], v[158:159], v[200:201]
	v_pk_fma_f32 v[10:11], v[10:11], v[160:161], v[202:203]
	v_pk_fma_f32 v[12:13], v[12:13], v[162:163], v[204:205]
	v_pk_fma_f32 v[6:7], v[6:7], v[164:165], v[206:207]
	v_pk_fma_f32 v[8:9], v[8:9], v[166:167], v[208:209]
	v_pk_fma_f32 v[2:3], v[2:3], v[168:169], v[210:211]
	v_pk_fma_f32 v[4:5], v[4:5], v[170:171], v[212:213]
	global_store_dwordx4 v[140:141], v[14:17], off
	global_store_dwordx4 v[140:141], v[10:13], off offset:64
	global_store_dwordx4 v[140:141], v[6:9], off offset:128
	global_store_dwordx4 v[140:141], v[2:5], off offset:192
	s_branch .LBB0_41

; #define MFMA16(a, b, c) __builtin_amdgcn_mfma_f32_16x16x32_bf16((a), (b), (c), 0, 0, 0)
;     ...
;   for (int kt = 0; kt < nk; ++kt) {
;     const int buf = kt & 1;
;     const char* cA = smem + buf * STAGE + (wm * 32 * MI + r16) * 128;
;     const char* cB = smem + buf * STAGE + 32768 + (wn * 64 + r16) * 128;
; #pragma unroll
;     for (int k2 = 0; k2 < 2; ++k2) {
;       if (k2 == 1 && kt + 1 < nk) STAGE_TILE(buf ^ 1, (kt + 1) * 64)
;       const int po = ((4 * k2 + q4) ^ swz) * 16;
;       bf16x8 bf[4];
; #pragma unroll
;       for (int nt = 0; nt < 4; ++nt) bf[nt] = *(const bf16x8*)(cB + nt * 16 * 128 + po);
;       bf16x8 afc = *(const bf16x8*)(cA + po);
; #pragma unroll
;       for (int a = 0; a < MT; ++a) {
;         bf16x8 afn = afc;
;         if (a + 1 < MT) afn = *(const bf16x8*)(cA + (a + 1) * 16 * 128 + po);
;         __builtin_amdgcn_sched_barrier(0);
; #pragma unroll
;         for (int nt = 0; nt < 4; ++nt) acc[a][nt] = MFMA16(bf[nt], afc, acc[a][nt]);
;         __builtin_amdgcn_sched_barrier(0);
;         afc = afn;
;       }
;     }
;     asm volatile("s_waitcnt vmcnt(0)" ::: "memory");
;     __syncthreads();
;   }
.LBB0_59:
	s_and_b32 s31, s30, 0x10000
	s_add_i32 s34, s31, 0
	v_add_u32_e32 v78, s34, v51
	v_add_u32_e32 v66, v78, v50
	v_add_u32_e32 v53, s34, v52
	ds_read_b128 v[54:57], v66 offset:32768
	ds_read_b128 v[58:61], v66 offset:34816
	ds_read_b128 v[62:65], v66 offset:36864
	ds_read_b128 v[66:69], v66 offset:38912
	v_add_u32_e32 v74, v53, v50
	ds_read_b128 v[70:73], v74
	ds_read_b128 v[74:77], v74 offset:2048
	s_waitcnt lgkmcnt(1)
	v_mfma_f32_16x16x32_bf16 v[30:33], v[54:57], v[70:73], v[30:33]
	v_mfma_f32_16x16x32_bf16 v[26:29], v[58:61], v[70:73], v[26:29]
	v_mfma_f32_16x16x32_bf16 v[22:25], v[62:65], v[70:73], v[22:25]
	v_mfma_f32_16x16x32_bf16 v[18:21], v[66:69], v[70:73], v[18:21]
	s_waitcnt lgkmcnt(0)
	v_mfma_f32_16x16x32_bf16 v[14:17], v[54:57], v[74:77], v[14:17]
	v_mfma_f32_16x16x32_bf16 v[10:13], v[58:61], v[74:77], v[10:13]
	v_mfma_f32_16x16x32_bf16 v[6:9], v[62:65], v[74:77], v[6:9]
	v_mfma_f32_16x16x32_bf16 v[2:5], v[66:69], v[74:77], v[2:5]
	s_xor_b32 s31, s31, 0x10000
	v_add_u32_e32 v64, s31, v48
	v_add_u32_e32 v68, 0x8000, v64
	v_readfirstlane_b32 s31, v64
	v_add_u32_e32 v67, 0xa000, v64
	v_lshl_add_u64 v[62:63], v[42:43], 0, s[14:15]
	s_mov_b32 m0, s31
	v_readfirstlane_b32 s31, v68
	v_add_u32_e32 v66, 0xc000, v64
	v_lshl_add_u64 v[60:61], v[40:41], 0, s[14:15]
	global_load_lds_dwordx4 v[62:63], off
	s_mov_b32 m0, s31
	v_readfirstlane_b32 s31, v67
	v_add_u32_e32 v65, 0xe000, v64
	v_lshl_add_u64 v[58:59], v[38:39], 0, s[14:15]
	global_load_lds_dwordx4 v[60:61], off
	s_mov_b32 m0, s31
	v_readfirstlane_b32 s31, v66
	v_lshl_add_u64 v[56:57], v[36:37], 0, s[14:15]
	global_load_lds_dwordx4 v[58:59], off
	s_mov_b32 m0, s31
	v_readfirstlane_b32 s31, v65
	v_lshl_add_u64 v[54:55], v[34:35], 0, s[14:15]
	global_load_lds_dwordx4 v[56:57], off
	s_mov_b32 m0, s31
	v_add_u32_e32 v66, v78, v49
	global_load_lds_dwordx4 v[54:55], off
	ds_read_b128 v[54:57], v66 offset:32768
	ds_read_b128 v[58:61], v66 offset:34816
	ds_read_b128 v[62:65], v66 offset:36864
	ds_read_b128 v[66:69], v66 offset:38912
	v_add_u32_e32 v53, v53, v49
	ds_read_b128 v[70:73], v53
	ds_read_b128 v[74:77], v53 offset:2048
	s_waitcnt lgkmcnt(0)
	v_mfma_f32_16x16x32_bf16 v[30:33], v[54:57], v[70:73], v[30:33]
	v_mfma_f32_16x16x32_bf16 v[26:29], v[58:61], v[70:73], v[26:29]
	v_mfma_f32_16x16x32_bf16 v[22:25], v[62:65], v[70:73], v[22:25]
	v_mfma_f32_16x16x32_bf16 v[18:21], v[66:69], v[70:73], v[18:21]
	v_mfma_f32_16x16x32_bf16 v[14:17], v[54:57], v[74:77], v[14:17]
	v_mfma_f32_16x16x32_bf16 v[10:13], v[58:61], v[74:77], v[10:13]
	v_mfma_f32_16x16x32_bf16 v[6:9], v[62:65], v[74:77], v[6:9]
	v_mfma_f32_16x16x32_bf16 v[2:5], v[66:69], v[74:77], v[2:5]
	s_waitcnt vmcnt(0)
	s_add_u32 s14, s14, 0x80
	s_addc_u32 s15, s15, 0
	s_add_i32 s30, s30, 0x10000
	s_cmpk_eq_i32 s14, 0x1580
	s_waitcnt vmcnt(0)
	s_barrier
	s_cbranch_scc0 .LBB0_59
	s_add_i32 s14, 0, 0x10000
	v_add_u32_e32 v42, s14, v52
	v_readlane_b32 s14, v254, 18
	s_nop 1
	v_add_u32_e32 v43, s14, v51
	v_add_u32_e32 v48, v43, v50
	ds_read_b128 v[34:37], v48
	ds_read_b128 v[38:41], v48 offset:2048
	ds_read_b128 v[52:55], v48 offset:4096
	ds_read_b128 v[56:59], v48 offset:6144
	v_add_u32_e32 v48, v42, v50
	ds_read_b128 v[60:63], v48
	ds_read_b128 v[64:67], v48 offset:2048
	s_waitcnt lgkmcnt(1)
	v_mfma_f32_16x16x32_bf16 v[30:33], v[34:37], v[60:63], v[30:33]
	v_mfma_f32_16x16x32_bf16 v[26:29], v[38:41], v[60:63], v[26:29]
	v_mfma_f32_16x16x32_bf16 v[22:25], v[52:55], v[60:63], v[22:25]
	v_mfma_f32_16x16x32_bf16 v[18:21], v[56:59], v[60:63], v[18:21]
	s_waitcnt lgkmcnt(0)
	v_mfma_f32_16x16x32_bf16 v[14:17], v[34:37], v[64:67], v[14:17]
	v_mfma_f32_16x16x32_bf16 v[10:13], v[38:41], v[64:67], v[10:13]
	v_mfma_f32_16x16x32_bf16 v[6:9], v[52:55], v[64:67], v[6:9]
	v_mfma_f32_16x16x32_bf16 v[2:5], v[56:59], v[64:67], v[2:5]
	v_add_u32_e32 v43, v43, v49
	ds_read_b128 v[34:37], v43
	ds_read_b128 v[38:41], v43 offset:2048
	ds_read_b128 v[50:53], v43 offset:4096
	ds_read_b128 v[54:57], v43 offset:6144
	v_add_u32_e32 v42, v42, v49
	ds_read_b128 v[58:61], v42
	ds_read_b128 v[62:65], v42 offset:2048
	s_waitcnt lgkmcnt(1)
	v_mfma_f32_16x16x32_bf16 v[30:33], v[34:37], v[58:61], v[30:33]
	v_mfma_f32_16x16x32_bf16 v[26:29], v[38:41], v[58:61], v[26:29]
	v_mfma_f32_16x16x32_bf16 v[22:25], v[50:53], v[58:61], v[22:25]
	v_mfma_f32_16x16x32_bf16 v[18:21], v[54:57], v[58:61], v[18:21]
	s_waitcnt lgkmcnt(0)
	v_mfma_f32_16x16x32_bf16 v[14:17], v[34:37], v[62:65], v[14:17]
	v_mfma_f32_16x16x32_bf16 v[10:13], v[38:41], v[62:65], v[10:13]
	v_mfma_f32_16x16x32_bf16 v[6:9], v[50:53], v[62:65], v[6:9]
	v_mfma_f32_16x16x32_bf16 v[2:5], v[54:57], v[62:65], v[2:5]
	v_or_b32_e32 v35, s27, v46
	v_lshlrev_b32_e32 v34, 6, v47
	v_lshl_add_u32 v54, v44, 5, v35
	v_lshlrev_b32_e32 v35, 2, v45
	v_or3_b32 v38, v34, v35, s23
	v_mul_hi_i32 v34, v54, s1
	v_lshrrev_b32_e32 v35, 31, v34
	v_ashrrev_i32_e32 v34, 11, v34
	v_add_u32_e32 v34, v34, v35
	v_mad_i32_i24 v35, v34, s90, v54
	s_movk_i32 s23, 0x100
	v_cmp_gt_i32_e32 vcc, s23, v35
	v_add_u32_e32 v36, 0xffffff00, v35
	v_ashrrev_i32_e32 v37, 31, v35
	v_readlane_b32 s36, v254, 1
	v_cndmask_b32_e64 v39, v34, 4, vcc
	v_cndmask_b32_e32 v37, 0, v37, vcc
	v_cndmask_b32_e32 v36, v36, v35, vcc
	v_ashrrev_i32_e32 v35, 31, v34
	v_cndmask_b32_e64 v40, 25, 20, vcc
	v_readlane_b32 s37, v254, 2
	v_lshlrev_b64 v[44:45], v40, v[34:35]
	v_lshlrev_b64 v[46:47], 12, v[36:37]
	v_add_u32_e32 v34, s17, v39
	v_mov_b64_e32 v[36:37], s[36:37]
	s_movk_i32 s27, 0x6000
	v_mad_i64_i32 v[34:35], s[14:15], v34, s27, v[36:37]
	v_readlane_b32 s14, v252, 26
	s_waitcnt vmcnt(0)
	s_barrier
;     ...
; #pragma unroll
;     for (int a = 0; a < MT; ++a)
; #pragma unroll
;       for (int nt = 0; nt < 4; ++nt)
;         ep(row0 + 16 * a, cbw + 16 * nt + 4 * q4, acc[a][nt][0], acc[a][nt][1], acc[a][nt][2], acc[a][nt][3]);
; DI void phase_resid(char* smem, const Params& p, int layer, const bf16_t* A, int K, const bf16_t* W, int gate_idx, bool first) {
;     ...
;   auto ep = [&](int row, int col, float v0, float v1, float v2, float v3) {
;     const int b = row / TT, t = row - b * TT;
;     const float4 g = *(const float4*)(p.mod + (size_t)(layer * 5 + (t < CTXL ? 4 : b)) * 6144 + gate_idx * 1024 + col);
;     const float4 xo = *(const float4*)(xsrc_row(p, first, row) + col);
;     *(float4*)(xdst_row(p, row) + col) = make_float4(xo.x + g.x * v0, xo.y + g.y * v1, xo.z + g.z * v2, xo.w + g.w * v3);
;   };
	s_nop 0
	v_mov_b32_e32 v55, s14
	v_readlane_b32 s14, v252, 28
	v_readlane_b32 s68, v252, 5
	s_nop 0
	v_mov_b32_e32 v56, s14
	v_readlane_b32 s14, v252, 25
	v_cndmask_b32_e32 v43, v55, v56, vcc
	v_readlane_b32 s80, v252, 17
	v_mov_b32_e32 v57, s14
	v_readlane_b32 s14, v252, 27
	v_readlane_b32 s81, v252, 18
	v_readlane_b32 s82, v252, 19
	v_mov_b32_e32 v58, s14
	v_cndmask_b32_e32 v42, v57, v58, vcc
	global_load_dwordx2 v[42:43], v[42:43], off
	v_readlane_b32 s83, v252, 20
	s_mov_b64 s[30:31], 0x5000
	v_ashrrev_i32_e32 v39, 31, v38
	v_mov_b32_e32 v59, s81
	v_mov_b32_e32 v60, s83
	v_mov_b32_e32 v61, s80
	v_mov_b32_e32 v62, s82
	v_lshl_add_u64 v[40:41], v[34:35], 0, s[30:31]
	v_lshlrev_b64 v[34:35], 2, v[38:39]
	v_cndmask_b32_e32 v51, v59, v60, vcc
	v_cndmask_b32_e32 v50, v61, v62, vcc
	v_lshl_add_u64 v[48:49], v[40:41], 0, v[34:35]
	v_readlane_b32 s38, v254, 3
	v_readlane_b32 s39, v254, 4
	v_readlane_b32 s40, v254, 5
	v_readlane_b32 s41, v254, 6
	v_readlane_b32 s42, v254, 7
	v_readlane_b32 s43, v254, 8
	v_readlane_b32 s44, v254, 9
	v_readlane_b32 s45, v254, 10
	v_readlane_b32 s46, v254, 11
	v_readlane_b32 s47, v254, 12
	v_readlane_b32 s48, v254, 13
	v_readlane_b32 s49, v254, 14
	v_readlane_b32 s50, v254, 15
	v_readlane_b32 s51, v254, 16
	s_add_i32 s21, s21, s20
	s_cmp_ge_i32 s21, s16
	v_readlane_b32 s36, v255, 12
	v_readlane_b32 s69, v252, 6
	v_readlane_b32 s70, v252, 7
	v_readlane_b32 s71, v252, 8
	v_readlane_b32 s72, v252, 9
	v_readlane_b32 s73, v252, 10
	v_readlane_b32 s74, v252, 11
	v_readlane_b32 s75, v252, 12
	v_readlane_b32 s76, v252, 13
	v_readlane_b32 s77, v252, 14
	v_readlane_b32 s78, v252, 15
	v_readlane_b32 s79, v252, 16
	v_readlane_b32 s37, v255, 13
	v_readlane_b32 s38, v255, 14
	v_readlane_b32 s39, v255, 15
	v_readlane_b32 s40, v255, 16
	v_readlane_b32 s41, v255, 17
	v_readlane_b32 s42, v255, 18
	v_readlane_b32 s43, v255, 19
	v_readlane_b32 s44, v255, 20
	v_readlane_b32 s45, v255, 21
	v_readlane_b32 s46, v255, 22
	v_readlane_b32 s47, v255, 23
	v_readlane_b32 s48, v255, 24
	v_readlane_b32 s49, v255, 25
	v_readlane_b32 s50, v255, 26
	v_readlane_b32 s51, v255, 27
	s_waitcnt vmcnt(0)
	v_lshl_add_u64 v[42:43], v[42:43], 0, v[44:45]
	v_lshl_add_u64 v[42:43], v[42:43], 0, v[46:47]
	v_lshl_add_u64 v[44:45], v[50:51], 0, v[44:45]
	v_lshl_add_u64 v[42:43], v[42:43], 0, v[34:35]
	v_lshl_add_u64 v[44:45], v[44:45], 0, v[46:47]
	v_lshl_add_u64 v[44:45], v[44:45], 0, v[34:35]
	global_load_dwordx4 v[156:159], v[48:49], off
	global_load_dwordx4 v[160:163], v[48:49], off offset:64
	global_load_dwordx4 v[164:167], v[48:49], off offset:128
	global_load_dwordx4 v[168:171], v[48:49], off offset:192
	global_load_dwordx4 v[172:175], v[42:43], off
	global_load_dwordx4 v[176:179], v[42:43], off offset:64
	global_load_dwordx4 v[180:183], v[42:43], off offset:128
	global_load_dwordx4 v[184:187], v[42:43], off offset:192
	v_add_co_u32_e32 v42, vcc, 0x10000, v42
	s_nop 1
	v_addc_co_u32_e32 v43, vcc, 0, v43, vcc
	global_load_dwordx4 v[198:201], v[42:43], off
	global_load_dwordx4 v[202:205], v[42:43], off offset:64
	global_load_dwordx4 v[206:209], v[42:43], off offset:128
	global_load_dwordx4 v[210:213], v[42:43], off offset:192
	s_waitcnt vmcnt(4)
	v_pk_fma_f32 v[30:31], v[30:31], v[156:157], v[172:173]
	v_pk_fma_f32 v[32:33], v[32:33], v[158:159], v[174:175]
	v_pk_fma_f32 v[26:27], v[26:27], v[160:161], v[176:177]
	v_pk_fma_f32 v[28:29], v[28:29], v[162:163], v[178:179]
	v_pk_fma_f32 v[22:23], v[22:23], v[164:165], v[180:181]
	v_pk_fma_f32 v[24:25], v[24:25], v[166:167], v[182:183]
	v_pk_fma_f32 v[18:19], v[18:19], v[168:169], v[184:185]
	v_pk_fma_f32 v[20:21], v[20:21], v[170:171], v[186:187]
	global_store_dwordx4 v[44:45], v[30:33], off
	global_store_dwordx4 v[44:45], v[26:29], off offset:64
	global_store_dwordx4 v[44:45], v[22:25], off offset:128
	global_store_dwordx4 v[44:45], v[18:21], off offset:192
	v_add_co_u32_e32 v44, vcc, 0x10000, v44
	s_nop 1
	v_addc_co_u32_e32 v45, vcc, 0, v45, vcc
	s_waitcnt vmcnt(4)
	v_pk_fma_f32 v[14:15], v[14:15], v[156:157], v[198:199]
	v_pk_fma_f32 v[16:17], v[16:17], v[158:159], v[200:201]
	v_pk_fma_f32 v[10:11], v[10:11], v[160:161], v[202:203]
	v_pk_fma_f32 v[12:13], v[12:13], v[162:163], v[204:205]
	v_pk_fma_f32 v[6:7], v[6:7], v[164:165], v[206:207]
	v_pk_fma_f32 v[8:9], v[8:9], v[166:167], v[208:209]
	v_pk_fma_f32 v[2:3], v[2:3], v[168:169], v[210:211]
	v_pk_fma_f32 v[4:5], v[4:5], v[170:171], v[212:213]
	global_store_dwordx4 v[44:45], v[14:17], off
	global_store_dwordx4 v[44:45], v[10:13], off offset:64
	global_store_dwordx4 v[44:45], v[6:9], off offset:128
	global_store_dwordx4 v[44:45], v[2:5], off offset:192
	s_cbranch_scc0 .LBB0_54

; #define MFMA16(a, b, c) __builtin_amdgcn_mfma_f32_16x16x32_bf16((a), (b), (c), 0, 0, 0)
;     ...
;   for (int kt = 0; kt < nk; ++kt) {
;     const int buf = kt & 1;
;     const char* cA = smem + buf * STAGE + (wm * 32 * MI + r16) * 128;
;     const char* cB = smem + buf * STAGE + 32768 + (wn * 64 + r16) * 128;
; #pragma unroll
;     for (int k2 = 0; k2 < 2; ++k2) {
;       if (k2 == 1 && kt + 1 < nk) STAGE_TILE(buf ^ 1, (kt + 1) * 64)
;       const int po = ((4 * k2 + q4) ^ swz) * 16;
;       bf16x8 bf[4];
; #pragma unroll
;       for (int nt = 0; nt < 4; ++nt) bf[nt] = *(const bf16x8*)(cB + nt * 16 * 128 + po);
;       bf16x8 afc = *(const bf16x8*)(cA + po);
; #pragma unroll
;       for (int a = 0; a < MT; ++a) {
;         bf16x8 afn = afc;
;         if (a + 1 < MT) afn = *(const bf16x8*)(cA + (a + 1) * 16 * 128 + po);
;         __builtin_amdgcn_sched_barrier(0);
; #pragma unroll
;         for (int nt = 0; nt < 4; ++nt) acc[a][nt] = MFMA16(bf[nt], afc, acc[a][nt]);
;         __builtin_amdgcn_sched_barrier(0);
;         afc = afn;
;       }
;     }
;     asm volatile("s_waitcnt vmcnt(0)" ::: "memory");
;     __syncthreads();
;   }
.LBB0_75:
	s_and_b32 s41, s40, 0x10000
	s_add_i32 s42, s41, 0
	v_add_u32_e32 v190, s42, v147
	v_lshl_add_u64 v[150:151], v[130:131], 0, s[16:17]
	v_add_u32_e32 v162, v190, v146
	v_add_u32_e32 v149, s42, v148
	v_lshl_add_u64 v[174:175], v[150:151], 0, s[24:25]
	v_lshl_add_u64 v[176:177], v[150:151], 0, s[84:85]
	v_lshl_add_u64 v[178:179], v[150:151], 0, s[28:29]
	v_lshl_add_u64 v[180:181], v[150:151], 0, s[18:19]
	ds_read_b128 v[150:153], v162 offset:32768
	ds_read_b128 v[154:157], v162 offset:34816
	ds_read_b128 v[158:161], v162 offset:36864
	ds_read_b128 v[162:165], v162 offset:38912
	v_add_u32_e32 v202, v149, v146
	ds_read_b128 v[166:169], v202
	ds_read_b128 v[170:173], v202 offset:2048
	s_xor_b32 s41, s41, 0x10000
	v_add_u32_e32 v192, s41, v145
	v_add_u32_e32 v193, 0x2000, v192
	v_add_u32_e32 v198, 0x4000, v192
	v_add_u32_e32 v199, 0x6000, v192
	v_lshl_add_u64 v[182:183], v[138:139], 0, s[16:17]
	v_add_u32_e32 v200, 0x8000, v192
	v_lshl_add_u64 v[184:185], v[136:137], 0, s[16:17]
	v_add_u32_e32 v201, 0xa000, v192
	v_lshl_add_u64 v[186:187], v[134:135], 0, s[16:17]
	v_add_u32_e32 v203, 0xc000, v192
	v_lshl_add_u64 v[188:189], v[132:133], 0, s[16:17]
	v_add_u32_e32 v204, 0xe000, v192
	s_waitcnt lgkmcnt(1)
	v_mfma_f32_16x16x32_bf16 v[126:129], v[150:153], v[166:169], v[126:129]
	v_mfma_f32_16x16x32_bf16 v[122:125], v[154:157], v[166:169], v[122:125]
	v_mfma_f32_16x16x32_bf16 v[118:121], v[158:161], v[166:169], v[118:121]
	v_mfma_f32_16x16x32_bf16 v[114:117], v[162:165], v[166:169], v[114:117]
	ds_read_b128 v[166:169], v202 offset:4096
	s_waitcnt lgkmcnt(1)
	v_mfma_f32_16x16x32_bf16 v[110:113], v[150:153], v[170:173], v[110:113]
	v_mfma_f32_16x16x32_bf16 v[106:109], v[154:157], v[170:173], v[106:109]
	v_mfma_f32_16x16x32_bf16 v[102:105], v[158:161], v[170:173], v[102:105]
	v_mfma_f32_16x16x32_bf16 v[98:101], v[162:165], v[170:173], v[98:101]
	ds_read_b128 v[170:173], v202 offset:6144
	s_waitcnt lgkmcnt(1)
	v_mfma_f32_16x16x32_bf16 v[94:97], v[150:153], v[166:169], v[94:97]
	v_mfma_f32_16x16x32_bf16 v[90:93], v[154:157], v[166:169], v[90:93]
	v_mfma_f32_16x16x32_bf16 v[86:89], v[158:161], v[166:169], v[86:89]
	v_mfma_f32_16x16x32_bf16 v[82:85], v[162:165], v[166:169], v[82:85]
	ds_read_b128 v[166:169], v202 offset:8192
	s_waitcnt lgkmcnt(1)
	v_mfma_f32_16x16x32_bf16 v[78:81], v[150:153], v[170:173], v[78:81]
	v_mfma_f32_16x16x32_bf16 v[74:77], v[154:157], v[170:173], v[74:77]
	v_mfma_f32_16x16x32_bf16 v[70:73], v[158:161], v[170:173], v[70:73]
	v_mfma_f32_16x16x32_bf16 v[66:69], v[162:165], v[170:173], v[66:69]
	ds_read_b128 v[170:173], v202 offset:10240
	s_waitcnt lgkmcnt(1)
	v_mfma_f32_16x16x32_bf16 v[62:65], v[150:153], v[166:169], v[62:65]
	v_mfma_f32_16x16x32_bf16 v[58:61], v[154:157], v[166:169], v[58:61]
	v_mfma_f32_16x16x32_bf16 v[54:57], v[158:161], v[166:169], v[54:57]
	v_mfma_f32_16x16x32_bf16 v[50:53], v[162:165], v[166:169], v[50:53]
	ds_read_b128 v[166:169], v202 offset:12288
	s_waitcnt lgkmcnt(1)
	v_mfma_f32_16x16x32_bf16 v[46:49], v[150:153], v[170:173], v[46:49]
	v_mfma_f32_16x16x32_bf16 v[42:45], v[154:157], v[170:173], v[42:45]
	v_mfma_f32_16x16x32_bf16 v[38:41], v[158:161], v[170:173], v[38:41]
	v_mfma_f32_16x16x32_bf16 v[34:37], v[162:165], v[170:173], v[34:37]
	ds_read_b128 v[170:173], v202 offset:14336
	s_waitcnt lgkmcnt(1)
	v_mfma_f32_16x16x32_bf16 v[30:33], v[150:153], v[166:169], v[30:33]
	v_mfma_f32_16x16x32_bf16 v[26:29], v[154:157], v[166:169], v[26:29]
	v_mfma_f32_16x16x32_bf16 v[22:25], v[158:161], v[166:169], v[22:25]
	v_mfma_f32_16x16x32_bf16 v[18:21], v[162:165], v[166:169], v[18:21]
	s_waitcnt lgkmcnt(0)
	v_mfma_f32_16x16x32_bf16 v[14:17], v[150:153], v[170:173], v[14:17]
	v_mfma_f32_16x16x32_bf16 v[10:13], v[154:157], v[170:173], v[10:13]
	v_mfma_f32_16x16x32_bf16 v[6:9], v[158:161], v[170:173], v[6:9]
	v_mfma_f32_16x16x32_bf16 v[2:5], v[162:165], v[170:173], v[2:5]
	v_readfirstlane_b32 s41, v192
	s_mov_b32 m0, s41
	v_readfirstlane_b32 s41, v193
	global_load_lds_dwordx4 v[174:175], off
	s_mov_b32 m0, s41
	v_readfirstlane_b32 s41, v198
	global_load_lds_dwordx4 v[176:177], off
	s_mov_b32 m0, s41
	v_readfirstlane_b32 s41, v199
	global_load_lds_dwordx4 v[178:179], off
	s_mov_b32 m0, s41
	v_readfirstlane_b32 s41, v200
	global_load_lds_dwordx4 v[180:181], off
	s_mov_b32 m0, s41
	v_readfirstlane_b32 s41, v201
	global_load_lds_dwordx4 v[182:183], off
	s_mov_b32 m0, s41
	v_readfirstlane_b32 s41, v203
	global_load_lds_dwordx4 v[184:185], off
	s_mov_b32 m0, s41
	v_readfirstlane_b32 s41, v204
	global_load_lds_dwordx4 v[186:187], off
	s_mov_b32 m0, s41
	v_add_u32_e32 v162, v190, v144
	global_load_lds_dwordx4 v[188:189], off
	ds_read_b128 v[150:153], v162 offset:32768
	ds_read_b128 v[154:157], v162 offset:34816
	ds_read_b128 v[158:161], v162 offset:36864
	ds_read_b128 v[162:165], v162 offset:38912
	v_add_u32_e32 v149, v149, v144
	ds_read_b128 v[166:169], v149
	ds_read_b128 v[170:173], v149 offset:2048
	s_waitcnt lgkmcnt(0)
	v_mfma_f32_16x16x32_bf16 v[126:129], v[150:153], v[166:169], v[126:129]
	v_mfma_f32_16x16x32_bf16 v[122:125], v[154:157], v[166:169], v[122:125]
	v_mfma_f32_16x16x32_bf16 v[118:121], v[158:161], v[166:169], v[118:121]
	v_mfma_f32_16x16x32_bf16 v[114:117], v[162:165], v[166:169], v[114:117]
	ds_read_b128 v[166:169], v149 offset:4096
	v_mfma_f32_16x16x32_bf16 v[110:113], v[150:153], v[170:173], v[110:113]
	v_mfma_f32_16x16x32_bf16 v[106:109], v[154:157], v[170:173], v[106:109]
	v_mfma_f32_16x16x32_bf16 v[102:105], v[158:161], v[170:173], v[102:105]
	v_mfma_f32_16x16x32_bf16 v[98:101], v[162:165], v[170:173], v[98:101]
	ds_read_b128 v[170:173], v149 offset:6144
	s_waitcnt lgkmcnt(0)
; #define MFMA16(a, b, c) __builtin_amdgcn_mfma_f32_16x16x32_bf16((a), (b), (c), 0, 0, 0)
;     ...
;   for (int kt = 0; kt < nk; ++kt) {
;     const int buf = kt & 1;
;     const char* cA = smem + buf * STAGE + (wm * 32 * MI + r16) * 128;
;     const char* cB = smem + buf * STAGE + 32768 + (wn * 64 + r16) * 128;
; #pragma unroll
;     for (int k2 = 0; k2 < 2; ++k2) {
;       if (k2 == 1 && kt + 1 < nk) STAGE_TILE(buf ^ 1, (kt + 1) * 64)
;       const int po = ((4 * k2 + q4) ^ swz) * 16;
;       bf16x8 bf[4];
; #pragma unroll
;       for (int nt = 0; nt < 4; ++nt) bf[nt] = *(const bf16x8*)(cB + nt * 16 * 128 + po);
;       bf16x8 afc = *(const bf16x8*)(cA + po);
; #pragma unroll
;       for (int a = 0; a < MT; ++a) {
;         bf16x8 afn = afc;
;         if (a + 1 < MT) afn = *(const bf16x8*)(cA + (a + 1) * 16 * 128 + po);
;         __builtin_amdgcn_sched_barrier(0);
; #pragma unroll
;         for (int nt = 0; nt < 4; ++nt) acc[a][nt] = MFMA16(bf[nt], afc, acc[a][nt]);
;         __builtin_amdgcn_sched_barrier(0);
;         afc = afn;
;       }
;     }
;     asm volatile("s_waitcnt vmcnt(0)" ::: "memory");
;     __syncthreads();
;   }
	v_mfma_f32_16x16x32_bf16 v[94:97], v[150:153], v[166:169], v[94:97]
	v_mfma_f32_16x16x32_bf16 v[90:93], v[154:157], v[166:169], v[90:93]
	v_mfma_f32_16x16x32_bf16 v[86:89], v[158:161], v[166:169], v[86:89]
	v_mfma_f32_16x16x32_bf16 v[82:85], v[162:165], v[166:169], v[82:85]
	ds_read_b128 v[166:169], v149 offset:8192
	v_mfma_f32_16x16x32_bf16 v[78:81], v[150:153], v[170:173], v[78:81]
	v_mfma_f32_16x16x32_bf16 v[74:77], v[154:157], v[170:173], v[74:77]
	v_mfma_f32_16x16x32_bf16 v[70:73], v[158:161], v[170:173], v[70:73]
	v_mfma_f32_16x16x32_bf16 v[66:69], v[162:165], v[170:173], v[66:69]
	ds_read_b128 v[170:173], v149 offset:10240
	s_waitcnt lgkmcnt(0)
	v_mfma_f32_16x16x32_bf16 v[62:65], v[150:153], v[166:169], v[62:65]
	v_mfma_f32_16x16x32_bf16 v[58:61], v[154:157], v[166:169], v[58:61]
	v_mfma_f32_16x16x32_bf16 v[54:57], v[158:161], v[166:169], v[54:57]
	v_mfma_f32_16x16x32_bf16 v[50:53], v[162:165], v[166:169], v[50:53]
	ds_read_b128 v[166:169], v149 offset:12288
	v_mfma_f32_16x16x32_bf16 v[46:49], v[150:153], v[170:173], v[46:49]
	v_mfma_f32_16x16x32_bf16 v[42:45], v[154:157], v[170:173], v[42:45]
	v_mfma_f32_16x16x32_bf16 v[38:41], v[158:161], v[170:173], v[38:41]
	v_mfma_f32_16x16x32_bf16 v[34:37], v[162:165], v[170:173], v[34:37]
	ds_read_b128 v[170:173], v149 offset:14336
	s_waitcnt lgkmcnt(0)
	v_mfma_f32_16x16x32_bf16 v[30:33], v[150:153], v[166:169], v[30:33]
	v_mfma_f32_16x16x32_bf16 v[26:29], v[154:157], v[166:169], v[26:29]
	v_mfma_f32_16x16x32_bf16 v[22:25], v[158:161], v[166:169], v[22:25]
	v_mfma_f32_16x16x32_bf16 v[18:21], v[162:165], v[166:169], v[18:21]
	v_mfma_f32_16x16x32_bf16 v[14:17], v[150:153], v[170:173], v[14:17]
	v_mfma_f32_16x16x32_bf16 v[10:13], v[154:157], v[170:173], v[10:13]
	v_mfma_f32_16x16x32_bf16 v[6:9], v[158:161], v[170:173], v[6:9]
	v_mfma_f32_16x16x32_bf16 v[2:5], v[162:165], v[170:173], v[2:5]
	s_waitcnt vmcnt(0)
	s_add_u32 s16, s16, 0x80
	s_addc_u32 s17, s17, 0
	s_add_i32 s40, s40, 0x10000
	s_cmpk_lg_i32 s16, 0x780
	s_waitcnt vmcnt(0)
	s_barrier
	s_cbranch_scc1 .LBB0_75
	s_add_i32 s16, 0, 0x10000
	v_add_u32_e32 v138, s16, v148
	v_readlane_b32 s16, v254, 18
	s_nop 1
	v_add_u32_e32 v139, s16, v147
	v_add_u32_e32 v145, v139, v146
	ds_read_b128 v[130:133], v145
	ds_read_b128 v[134:137], v145 offset:2048
	ds_read_b128 v[148:151], v145 offset:4096
	ds_read_b128 v[152:155], v145 offset:6144
	v_add_u32_e32 v145, v138, v146
	ds_read_b128 v[156:159], v145
	ds_read_b128 v[160:163], v145 offset:2048
	s_waitcnt lgkmcnt(1)
	v_mfma_f32_16x16x32_bf16 v[126:129], v[130:133], v[156:159], v[126:129]
	v_mfma_f32_16x16x32_bf16 v[122:125], v[134:137], v[156:159], v[122:125]
	v_mfma_f32_16x16x32_bf16 v[118:121], v[148:151], v[156:159], v[118:121]
	v_mfma_f32_16x16x32_bf16 v[114:117], v[152:155], v[156:159], v[114:117]
	ds_read_b128 v[156:159], v145 offset:4096
	s_waitcnt lgkmcnt(1)
	v_mfma_f32_16x16x32_bf16 v[110:113], v[130:133], v[160:163], v[110:113]
	v_mfma_f32_16x16x32_bf16 v[106:109], v[134:137], v[160:163], v[106:109]
	v_mfma_f32_16x16x32_bf16 v[102:105], v[148:151], v[160:163], v[102:105]
	v_mfma_f32_16x16x32_bf16 v[98:101], v[152:155], v[160:163], v[98:101]
	ds_read_b128 v[160:163], v145 offset:6144
	s_waitcnt lgkmcnt(1)
	v_mfma_f32_16x16x32_bf16 v[94:97], v[130:133], v[156:159], v[94:97]
	v_mfma_f32_16x16x32_bf16 v[90:93], v[134:137], v[156:159], v[90:93]
	v_mfma_f32_16x16x32_bf16 v[86:89], v[148:151], v[156:159], v[86:89]
	v_mfma_f32_16x16x32_bf16 v[82:85], v[152:155], v[156:159], v[82:85]
	ds_read_b128 v[156:159], v145 offset:8192
	s_waitcnt lgkmcnt(1)
	v_mfma_f32_16x16x32_bf16 v[78:81], v[130:133], v[160:163], v[78:81]
	v_mfma_f32_16x16x32_bf16 v[74:77], v[134:137], v[160:163], v[74:77]
	v_mfma_f32_16x16x32_bf16 v[70:73], v[148:151], v[160:163], v[70:73]
	v_mfma_f32_16x16x32_bf16 v[66:69], v[152:155], v[160:163], v[66:69]
	ds_read_b128 v[160:163], v145 offset:10240
	s_waitcnt lgkmcnt(1)
	v_mfma_f32_16x16x32_bf16 v[62:65], v[130:133], v[156:159], v[62:65]
	v_mfma_f32_16x16x32_bf16 v[58:61], v[134:137], v[156:159], v[58:61]
	v_mfma_f32_16x16x32_bf16 v[54:57], v[148:151], v[156:159], v[54:57]
	v_mfma_f32_16x16x32_bf16 v[50:53], v[152:155], v[156:159], v[50:53]
	ds_read_b128 v[156:159], v145 offset:12288
	s_waitcnt lgkmcnt(1)
	v_mfma_f32_16x16x32_bf16 v[46:49], v[130:133], v[160:163], v[46:49]
	v_mfma_f32_16x16x32_bf16 v[42:45], v[134:137], v[160:163], v[42:45]
	v_mfma_f32_16x16x32_bf16 v[38:41], v[148:151], v[160:163], v[38:41]
	v_mfma_f32_16x16x32_bf16 v[34:37], v[152:155], v[160:163], v[34:37]
	ds_read_b128 v[160:163], v145 offset:14336
	s_waitcnt lgkmcnt(1)
	v_mfma_f32_16x16x32_bf16 v[30:33], v[130:133], v[156:159], v[30:33]
	v_mfma_f32_16x16x32_bf16 v[26:29], v[134:137], v[156:159], v[26:29]
	v_mfma_f32_16x16x32_bf16 v[22:25], v[148:151], v[156:159], v[22:25]
	v_mfma_f32_16x16x32_bf16 v[18:21], v[152:155], v[156:159], v[18:21]
	s_waitcnt lgkmcnt(0)
	v_mfma_f32_16x16x32_bf16 v[14:17], v[130:133], v[160:163], v[14:17]
	v_mfma_f32_16x16x32_bf16 v[10:13], v[134:137], v[160:163], v[10:13]
	v_mfma_f32_16x16x32_bf16 v[6:9], v[148:151], v[160:163], v[6:9]
	v_mfma_f32_16x16x32_bf16 v[2:5], v[152:155], v[160:163], v[2:5]
	v_add_u32_e32 v139, v139, v144
	ds_read_b128 v[130:133], v139
	ds_read_b128 v[134:137], v139 offset:2048
	ds_read_b128 v[146:149], v139 offset:4096
	ds_read_b128 v[150:153], v139 offset:6144
	v_add_u32_e32 v138, v138, v144
	ds_read_b128 v[154:157], v138
	ds_read_b128 v[158:161], v138 offset:2048
	s_waitcnt lgkmcnt(1)
	v_mfma_f32_16x16x32_bf16 v[126:129], v[130:133], v[154:157], v[126:129]
	v_mfma_f32_16x16x32_bf16 v[122:125], v[134:137], v[154:157], v[122:125]
	v_mfma_f32_16x16x32_bf16 v[118:121], v[146:149], v[154:157], v[118:121]
	v_mfma_f32_16x16x32_bf16 v[114:117], v[150:153], v[154:157], v[114:117]
	ds_read_b128 v[154:157], v138 offset:4096
	s_waitcnt lgkmcnt(1)
; #define MFMA16(a, b, c) __builtin_amdgcn_mfma_f32_16x16x32_bf16((a), (b), (c), 0, 0, 0)
; DI unsigned pack2(float a, float b) { hwf2_t f = {a, b}; return __builtin_bit_cast(unsigned, __builtin_convertvector(f, hwbf2_t)); }
; DI float fsigmoid(float x) { return __builtin_amdgcn_rcpf(1.f + __expf(-x)); }
;     ...
;   for (int kt = 0; kt < nk; ++kt) {
;     const int buf = kt & 1;
;     const char* cA = smem + buf * STAGE + (wm * 32 * MI + r16) * 128;
;     const char* cB = smem + buf * STAGE + 32768 + (wn * 64 + r16) * 128;
; #pragma unroll
;     for (int k2 = 0; k2 < 2; ++k2) {
;       if (k2 == 1 && kt + 1 < nk) STAGE_TILE(buf ^ 1, (kt + 1) * 64)
;       const int po = ((4 * k2 + q4) ^ swz) * 16;
;       bf16x8 bf[4];
; #pragma unroll
;       for (int nt = 0; nt < 4; ++nt) bf[nt] = *(const bf16x8*)(cB + nt * 16 * 128 + po);
;       bf16x8 afc = *(const bf16x8*)(cA + po);
; #pragma unroll
;       for (int a = 0; a < MT; ++a) {
;         bf16x8 afn = afc;
;         if (a + 1 < MT) afn = *(const bf16x8*)(cA + (a + 1) * 16 * 128 + po);
;         __builtin_amdgcn_sched_barrier(0);
; #pragma unroll
;         for (int nt = 0; nt < 4; ++nt) acc[a][nt] = MFMA16(bf[nt], afc, acc[a][nt]);
;         __builtin_amdgcn_sched_barrier(0);
;         afc = afn;
;       }
;     }
;     asm volatile("s_waitcnt vmcnt(0)" ::: "memory");
;     __syncthreads();
;   }
; DI void phase_ffn_up(char* smem, const Params& p, int layer) {
;     ...
;   auto ep = [=](int row, int cb, int q4, const f32x4& c0, const f32x4& c1, const f32x4& c2, const f32x4& c3) {
;     const uint4 o = make_uint4(pack2(c0[0] * fsigmoid(c0[0]) * c0[1], c0[2] * fsigmoid(c0[2]) * c0[3]),
;                                pack2(c1[0] * fsigmoid(c1[0]) * c1[1], c1[2] * fsigmoid(c1[2]) * c1[3]),
;                                pack2(c2[0] * fsigmoid(c2[0]) * c2[1], c2[2] * fsigmoid(c2[2]) * c2[3]),
;                                pack2(c3[0] * fsigmoid(c3[0]) * c3[1], c3[2] * fsigmoid(c3[2]) * c3[3]));
;     *(uint4*)(Hh + (size_t)row * FH + (cb >> 1) + q4 * 8) = o;
	v_mfma_f32_16x16x32_bf16 v[162:165], v[130:133], v[158:161], v[110:113]
	v_mfma_f32_16x16x32_bf16 v[166:169], v[134:137], v[158:161], v[106:109]
	v_mfma_f32_16x16x32_bf16 v[102:105], v[146:149], v[158:161], v[102:105]
	v_mfma_f32_16x16x32_bf16 v[98:101], v[150:153], v[158:161], v[98:101]
	s_nop 0
	ds_read_b128 v[106:109], v138 offset:6144
	s_waitcnt lgkmcnt(1)
	v_mfma_f32_16x16x32_bf16 v[94:97], v[130:133], v[154:157], v[94:97]
	v_mfma_f32_16x16x32_bf16 v[90:93], v[134:137], v[154:157], v[90:93]
	v_mfma_f32_16x16x32_bf16 v[86:89], v[146:149], v[154:157], v[86:89]
	v_mfma_f32_16x16x32_bf16 v[82:85], v[150:153], v[154:157], v[82:85]
	ds_read_b128 v[110:113], v138 offset:8192
	s_waitcnt lgkmcnt(1)
	v_mfma_f32_16x16x32_bf16 v[78:81], v[130:133], v[106:109], v[78:81]
	v_mfma_f32_16x16x32_bf16 v[74:77], v[134:137], v[106:109], v[74:77]
	v_mfma_f32_16x16x32_bf16 v[70:73], v[146:149], v[106:109], v[70:73]
	v_mfma_f32_16x16x32_bf16 v[66:69], v[150:153], v[106:109], v[66:69]
	ds_read_b128 v[106:109], v138 offset:10240
	s_waitcnt lgkmcnt(1)
	v_mfma_f32_16x16x32_bf16 v[62:65], v[130:133], v[110:113], v[62:65]
	v_mfma_f32_16x16x32_bf16 v[58:61], v[134:137], v[110:113], v[58:61]
	v_mfma_f32_16x16x32_bf16 v[54:57], v[146:149], v[110:113], v[54:57]
	v_mfma_f32_16x16x32_bf16 v[50:53], v[150:153], v[110:113], v[50:53]
	ds_read_b128 v[110:113], v138 offset:12288
	s_waitcnt lgkmcnt(1)
	v_mfma_f32_16x16x32_bf16 v[46:49], v[130:133], v[106:109], v[46:49]
	v_mfma_f32_16x16x32_bf16 v[42:45], v[134:137], v[106:109], v[42:45]
	v_mfma_f32_16x16x32_bf16 v[38:41], v[146:149], v[106:109], v[38:41]
	v_mfma_f32_16x16x32_bf16 v[34:37], v[150:153], v[106:109], v[34:37]
	ds_read_b128 v[106:109], v138 offset:14336
	s_waitcnt lgkmcnt(1)
	v_mfma_f32_16x16x32_bf16 v[30:33], v[130:133], v[110:113], v[30:33]
	v_mfma_f32_16x16x32_bf16 v[26:29], v[134:137], v[110:113], v[26:29]
	v_mfma_f32_16x16x32_bf16 v[22:25], v[146:149], v[110:113], v[22:25]
	v_mfma_f32_16x16x32_bf16 v[18:21], v[150:153], v[110:113], v[18:21]
	s_waitcnt lgkmcnt(0)
	v_mfma_f32_16x16x32_bf16 v[14:17], v[130:133], v[106:109], v[14:17]
	v_mfma_f32_16x16x32_bf16 v[10:13], v[134:137], v[106:109], v[10:13]
	v_mfma_f32_16x16x32_bf16 v[6:9], v[146:149], v[106:109], v[6:9]
	v_mfma_f32_16x16x32_bf16 v[2:5], v[150:153], v[106:109], v[2:5]
	v_or_b32_e32 v107, s38, v142
	v_lshl_add_u32 v110, v141, 7, v107
	v_mul_f32_e32 v107, 0xbfb8aa3b, v126
	v_mul_f32_e32 v108, 0xbfb8aa3b, v128
	v_exp_f32_e32 v107, v107
	v_exp_f32_e32 v109, v108
	v_lshl_or_b32 v106, v143, 6, s39
	v_ashrrev_i32_e32 v108, 1, v106
	v_add_f32_e32 v106, 1.0, v107
	v_add_f32_e32 v107, 1.0, v109
	v_rcp_f32_e32 v106, v106
	v_rcp_f32_e32 v107, v107
	v_mov_b32_e32 v112, v126
	v_mov_b32_e32 v113, v128
	v_mul_f32_e32 v111, 0xbfb8aa3b, v122
	v_pk_mul_f32 v[106:107], v[112:113], v[106:107]
	v_exp_f32_e32 v111, v111
	v_mul_f32_e32 v112, 0xbfb8aa3b, v124
	v_exp_f32_e32 v113, v112
	v_mov_b32_e32 v128, v127
	v_add_f32_e32 v111, 1.0, v111
	v_rcp_f32_e32 v112, v111
	v_add_f32_e32 v111, 1.0, v113
	v_rcp_f32_e32 v113, v111
	v_pk_mul_f32 v[106:107], v[128:129], v[106:107]
	v_mul_f32_e32 v111, 0xbfb8aa3b, v118
	v_cvt_pk_bf16_f32 v126, v106, v107
	v_mov_b32_e32 v106, v122
	v_mov_b32_e32 v107, v124
	v_pk_mul_f32 v[106:107], v[106:107], v[112:113]
	v_exp_f32_e32 v111, v111
	v_mul_f32_e32 v112, 0xbfb8aa3b, v120
	v_exp_f32_e32 v113, v112
	v_mov_b32_e32 v124, v123
	v_add_f32_e32 v111, 1.0, v111
	v_rcp_f32_e32 v112, v111
	v_add_f32_e32 v111, 1.0, v113
	v_rcp_f32_e32 v113, v111
	v_pk_mul_f32 v[106:107], v[124:125], v[106:107]
	v_mul_f32_e32 v111, 0xbfb8aa3b, v114
	v_cvt_pk_bf16_f32 v127, v106, v107
	v_mov_b32_e32 v106, v118
	v_mov_b32_e32 v107, v120
	v_pk_mul_f32 v[106:107], v[106:107], v[112:113]
	v_exp_f32_e32 v111, v111
	v_mul_f32_e32 v112, 0xbfb8aa3b, v116
	v_exp_f32_e32 v113, v112
	v_mov_b32_e32 v120, v119
	v_add_f32_e32 v111, 1.0, v111
	v_rcp_f32_e32 v112, v111
	v_add_f32_e32 v111, 1.0, v113
	v_rcp_f32_e32 v113, v111
	v_pk_mul_f32 v[106:107], v[120:121], v[106:107]
	v_readlane_b32 s52, v253, 40
	v_cvt_pk_bf16_f32 v128, v106, v107
	v_mov_b32_e32 v106, v114
	v_mov_b32_e32 v107, v116
	v_pk_mul_f32 v[106:107], v[106:107], v[112:113]
	v_mov_b32_e32 v116, v115
	v_mul_f32_e32 v111, 0xbfb8aa3b, v162
	v_pk_mul_f32 v[106:107], v[116:117], v[106:107]
	v_readlane_b32 s54, v253, 42
	v_readlane_b32 s55, v253, 43
	v_exp_f32_e32 v111, v111
	v_mul_f32_e32 v114, 0xbfb8aa3b, v164
	v_ashrrev_i32_e32 v109, 31, v108
	v_cvt_pk_bf16_f32 v129, v106, v107
	v_mov_b64_e32 v[106:107], s[54:55]
	s_movk_i32 s38, 0x1600
	v_exp_f32_e32 v114, v114
	v_mad_i64_i32 v[112:113], s[16:17], v110, s38, v[106:107]
	v_lshlrev_b64 v[108:109], 1, v[108:109]
	v_lshl_add_u64 v[112:113], v[112:113], 0, v[108:109]
	v_lshlrev_b32_e32 v190, 4, v140
	v_lshl_add_u64 v[112:113], v[112:113], 0, v[190:191]
	v_add_f32_e32 v111, 1.0, v111
	s_waitcnt vmcnt(0)
	s_barrier
; DI unsigned pack2(float a, float b) { hwf2_t f = {a, b}; return __builtin_bit_cast(unsigned, __builtin_convertvector(f, hwbf2_t)); }
; DI float fsigmoid(float x) { return __builtin_amdgcn_rcpf(1.f + __expf(-x)); }
; DI void phase_ffn_up(char* smem, const Params& p, int layer) {
;     ...
;   auto ep = [=](int row, int cb, int q4, const f32x4& c0, const f32x4& c1, const f32x4& c2, const f32x4& c3) {
;     const uint4 o = make_uint4(pack2(c0[0] * fsigmoid(c0[0]) * c0[1], c0[2] * fsigmoid(c0[2]) * c0[3]),
;                                pack2(c1[0] * fsigmoid(c1[0]) * c1[1], c1[2] * fsigmoid(c1[2]) * c1[3]),
;                                pack2(c2[0] * fsigmoid(c2[0]) * c2[1], c2[2] * fsigmoid(c2[2]) * c2[3]),
;                                pack2(c3[0] * fsigmoid(c3[0]) * c3[1], c3[2] * fsigmoid(c3[2]) * c3[3]));
;     *(uint4*)(Hh + (size_t)row * FH + (cb >> 1) + q4 * 8) = o;
	global_store_dwordx4 v[112:113], v[126:129], off
	v_rcp_f32_e32 v112, v111
	v_add_f32_e32 v111, 1.0, v114
	v_rcp_f32_e32 v113, v111
	v_mov_b32_e32 v114, v162
	v_mov_b32_e32 v115, v164
	v_mov_b32_e32 v164, v163
	v_pk_mul_f32 v[112:113], v[114:115], v[112:113]
	v_mul_f32_e32 v114, 0xbfb8aa3b, v166
	v_mul_f32_e32 v115, 0xbfb8aa3b, v168
	v_exp_f32_e32 v114, v114
	v_exp_f32_e32 v115, v115
	v_pk_mul_f32 v[112:113], v[164:165], v[112:113]
	v_mov_b32_e32 v116, v166
	v_add_f32_e32 v114, 1.0, v114
	v_add_f32_e32 v115, 1.0, v115
	v_rcp_f32_e32 v114, v114
	v_rcp_f32_e32 v115, v115
	v_cvt_pk_bf16_f32 v112, v112, v113
	v_mov_b32_e32 v117, v168
	v_mul_f32_e32 v113, 0xbfb8aa3b, v102
	v_pk_mul_f32 v[114:115], v[116:117], v[114:115]
	v_exp_f32_e32 v113, v113
	v_mul_f32_e32 v116, 0xbfb8aa3b, v104
	v_exp_f32_e32 v117, v116
	v_mov_b32_e32 v168, v167
	v_add_f32_e32 v113, 1.0, v113
	v_rcp_f32_e32 v116, v113
	v_add_f32_e32 v113, 1.0, v117
	v_rcp_f32_e32 v117, v113
	v_pk_mul_f32 v[114:115], v[168:169], v[114:115]
	v_or_b32_e32 v111, 16, v110
	v_cvt_pk_bf16_f32 v113, v114, v115
	v_mov_b32_e32 v114, v102
	v_mov_b32_e32 v115, v104
	v_mul_f32_e32 v102, 0xbfb8aa3b, v98
	v_pk_mul_f32 v[114:115], v[114:115], v[116:117]
	v_exp_f32_e32 v116, v102
	v_mul_f32_e32 v102, 0xbfb8aa3b, v100
	v_exp_f32_e32 v117, v102
	v_mov_b32_e32 v104, v103
	v_pk_mul_f32 v[102:103], v[104:105], v[114:115]
	v_add_f32_e32 v104, 1.0, v116
	v_add_f32_e32 v105, 1.0, v117
	v_rcp_f32_e32 v104, v104
	v_rcp_f32_e32 v105, v105
	v_cvt_pk_bf16_f32 v114, v102, v103
	v_mov_b32_e32 v102, v98
	v_mov_b32_e32 v103, v100
	v_pk_mul_f32 v[102:103], v[102:103], v[104:105]
	v_mov_b32_e32 v100, v99
	v_pk_mul_f32 v[98:99], v[100:101], v[102:103]
	v_mul_f32_e32 v100, 0xbfb8aa3b, v94
	v_mul_f32_e32 v101, 0xbfb8aa3b, v96
	v_exp_f32_e32 v100, v100
	v_exp_f32_e32 v101, v101
	v_cvt_pk_bf16_f32 v115, v98, v99
	v_mad_i64_i32 v[98:99], s[16:17], v111, s38, v[106:107]
	v_lshl_add_u64 v[98:99], v[98:99], 0, v[108:109]
	v_lshl_add_u64 v[98:99], v[98:99], 0, v[190:191]
	global_store_dwordx4 v[98:99], v[112:115], off
	v_add_f32_e32 v98, 1.0, v100
	v_add_f32_e32 v99, 1.0, v101
	v_rcp_f32_e32 v98, v98
	v_rcp_f32_e32 v99, v99
	v_mov_b32_e32 v100, v94
	v_mov_b32_e32 v101, v96
	v_mul_f32_e32 v94, 0xbfb8aa3b, v90
	v_pk_mul_f32 v[98:99], v[100:101], v[98:99]
	v_exp_f32_e32 v100, v94
	v_mul_f32_e32 v94, 0xbfb8aa3b, v92
	v_exp_f32_e32 v101, v94
	v_mov_b32_e32 v96, v95
	v_pk_mul_f32 v[94:95], v[96:97], v[98:99]
	v_add_f32_e32 v96, 1.0, v100
	v_add_f32_e32 v97, 1.0, v101
	v_rcp_f32_e32 v96, v96
	v_rcp_f32_e32 v97, v97
	v_mov_b32_e32 v98, v90
	v_mul_f32_e32 v90, 0xbfb8aa3b, v86
	v_cvt_pk_bf16_f32 v94, v94, v95
	v_mov_b32_e32 v99, v92
	v_exp_f32_e32 v95, v90
	v_mul_f32_e32 v90, 0xbfb8aa3b, v88
	v_pk_mul_f32 v[96:97], v[98:99], v[96:97]
	v_exp_f32_e32 v98, v90
	v_mov_b32_e32 v92, v91
	v_pk_mul_f32 v[90:91], v[92:93], v[96:97]
	v_add_f32_e32 v92, 1.0, v95
	v_add_f32_e32 v93, 1.0, v98
	v_rcp_f32_e32 v92, v92
	v_rcp_f32_e32 v93, v93
	v_cvt_pk_bf16_f32 v95, v90, v91
	v_mov_b32_e32 v90, v86
	v_mov_b32_e32 v91, v88
	v_mul_f32_e32 v86, 0xbfb8aa3b, v82
	v_pk_mul_f32 v[90:91], v[90:91], v[92:93]
	v_exp_f32_e32 v92, v86
	v_mul_f32_e32 v86, 0xbfb8aa3b, v84
	v_exp_f32_e32 v93, v86
	v_mov_b32_e32 v88, v87
	v_pk_mul_f32 v[86:87], v[88:89], v[90:91]
	v_add_f32_e32 v88, 1.0, v92
	v_add_f32_e32 v89, 1.0, v93
	v_rcp_f32_e32 v88, v88
	v_rcp_f32_e32 v89, v89
	v_cvt_pk_bf16_f32 v96, v86, v87
	v_mov_b32_e32 v86, v82
	v_mov_b32_e32 v87, v84
	v_pk_mul_f32 v[86:87], v[86:87], v[88:89]
	v_mov_b32_e32 v84, v83
	v_pk_mul_f32 v[82:83], v[84:85], v[86:87]
	v_mul_f32_e32 v84, 0xbfb8aa3b, v78
	v_mul_f32_e32 v85, 0xbfb8aa3b, v80
	v_or_b32_e32 v102, 32, v110
	v_exp_f32_e32 v84, v84
	v_exp_f32_e32 v85, v85
	v_cvt_pk_bf16_f32 v97, v82, v83
	v_mad_i64_i32 v[82:83], s[16:17], v102, s38, v[106:107]
	v_lshl_add_u64 v[82:83], v[82:83], 0, v[108:109]
	v_lshl_add_u64 v[82:83], v[82:83], 0, v[190:191]
	global_store_dwordx4 v[82:83], v[94:97], off
	v_add_f32_e32 v82, 1.0, v84
	v_add_f32_e32 v83, 1.0, v85
	v_rcp_f32_e32 v82, v82
	v_rcp_f32_e32 v83, v83
	v_mov_b32_e32 v84, v78
	v_mov_b32_e32 v85, v80
	v_mul_f32_e32 v78, 0xbfb8aa3b, v74
	v_pk_mul_f32 v[82:83], v[84:85], v[82:83]
	v_exp_f32_e32 v84, v78
	v_mul_f32_e32 v78, 0xbfb8aa3b, v76
	v_exp_f32_e32 v85, v78
	v_mov_b32_e32 v80, v79
	v_pk_mul_f32 v[78:79], v[80:81], v[82:83]
	v_add_f32_e32 v80, 1.0, v84
	v_add_f32_e32 v81, 1.0, v85
	v_rcp_f32_e32 v80, v80
	v_rcp_f32_e32 v81, v81
	v_mov_b32_e32 v82, v74
	v_mul_f32_e32 v74, 0xbfb8aa3b, v70
	v_cvt_pk_bf16_f32 v78, v78, v79
	v_mov_b32_e32 v83, v76
	v_exp_f32_e32 v79, v74
	v_mul_f32_e32 v74, 0xbfb8aa3b, v72
	v_pk_mul_f32 v[80:81], v[82:83], v[80:81]
	v_exp_f32_e32 v82, v74
	v_mov_b32_e32 v76, v75
	v_pk_mul_f32 v[74:75], v[76:77], v[80:81]
	v_add_f32_e32 v76, 1.0, v79
	v_add_f32_e32 v77, 1.0, v82
	v_rcp_f32_e32 v76, v76
	v_rcp_f32_e32 v77, v77
	v_cvt_pk_bf16_f32 v79, v74, v75
	v_mov_b32_e32 v74, v70
	v_mov_b32_e32 v75, v72
	v_mul_f32_e32 v70, 0xbfb8aa3b, v66
	v_pk_mul_f32 v[74:75], v[74:75], v[76:77]
	v_exp_f32_e32 v76, v70
	v_mul_f32_e32 v70, 0xbfb8aa3b, v68
	v_exp_f32_e32 v77, v70
	v_mov_b32_e32 v72, v71
	v_pk_mul_f32 v[70:71], v[72:73], v[74:75]
	v_add_f32_e32 v72, 1.0, v76
	v_add_f32_e32 v73, 1.0, v77
	v_rcp_f32_e32 v72, v72
	v_rcp_f32_e32 v73, v73
	v_cvt_pk_bf16_f32 v80, v70, v71
	v_mov_b32_e32 v70, v66
	v_mov_b32_e32 v71, v68
	v_pk_mul_f32 v[70:71], v[70:71], v[72:73]
	v_mov_b32_e32 v68, v67
	v_pk_mul_f32 v[66:67], v[68:69], v[70:71]
	v_mul_f32_e32 v68, 0xbfb8aa3b, v62
	v_mul_f32_e32 v69, 0xbfb8aa3b, v64
	v_or_b32_e32 v86, 48, v110
	v_exp_f32_e32 v68, v68
	v_exp_f32_e32 v69, v69
; DI unsigned pack2(float a, float b) { hwf2_t f = {a, b}; return __builtin_bit_cast(unsigned, __builtin_convertvector(f, hwbf2_t)); }
; DI float fsigmoid(float x) { return __builtin_amdgcn_rcpf(1.f + __expf(-x)); }
; DI void phase_ffn_up(char* smem, const Params& p, int layer) {
;     ...
;   auto ep = [=](int row, int cb, int q4, const f32x4& c0, const f32x4& c1, const f32x4& c2, const f32x4& c3) {
;     const uint4 o = make_uint4(pack2(c0[0] * fsigmoid(c0[0]) * c0[1], c0[2] * fsigmoid(c0[2]) * c0[3]),
;                                pack2(c1[0] * fsigmoid(c1[0]) * c1[1], c1[2] * fsigmoid(c1[2]) * c1[3]),
;                                pack2(c2[0] * fsigmoid(c2[0]) * c2[1], c2[2] * fsigmoid(c2[2]) * c2[3]),
;                                pack2(c3[0] * fsigmoid(c3[0]) * c3[1], c3[2] * fsigmoid(c3[2]) * c3[3]));
;     *(uint4*)(Hh + (size_t)row * FH + (cb >> 1) + q4 * 8) = o;
	v_cvt_pk_bf16_f32 v81, v66, v67
	v_mad_i64_i32 v[66:67], s[16:17], v86, s38, v[106:107]
	v_lshl_add_u64 v[66:67], v[66:67], 0, v[108:109]
	v_lshl_add_u64 v[66:67], v[66:67], 0, v[190:191]
	global_store_dwordx4 v[66:67], v[78:81], off
	v_add_f32_e32 v66, 1.0, v68
	v_add_f32_e32 v67, 1.0, v69
	v_rcp_f32_e32 v66, v66
	v_rcp_f32_e32 v67, v67
	v_mov_b32_e32 v68, v62
	v_mov_b32_e32 v69, v64
	v_mul_f32_e32 v62, 0xbfb8aa3b, v58
	v_pk_mul_f32 v[66:67], v[68:69], v[66:67]
	v_exp_f32_e32 v68, v62
	v_mul_f32_e32 v62, 0xbfb8aa3b, v60
	v_exp_f32_e32 v69, v62
	v_mov_b32_e32 v64, v63
	v_pk_mul_f32 v[62:63], v[64:65], v[66:67]
	v_add_f32_e32 v64, 1.0, v68
	v_add_f32_e32 v65, 1.0, v69
	v_rcp_f32_e32 v64, v64
	v_rcp_f32_e32 v65, v65
	v_mov_b32_e32 v66, v58
	v_mul_f32_e32 v58, 0xbfb8aa3b, v54
	v_cvt_pk_bf16_f32 v62, v62, v63
	v_mov_b32_e32 v67, v60
	v_exp_f32_e32 v63, v58
	v_mul_f32_e32 v58, 0xbfb8aa3b, v56
	v_pk_mul_f32 v[64:65], v[66:67], v[64:65]
	v_exp_f32_e32 v66, v58
	v_mov_b32_e32 v60, v59
	v_pk_mul_f32 v[58:59], v[60:61], v[64:65]
	v_add_f32_e32 v60, 1.0, v63
	v_add_f32_e32 v61, 1.0, v66
	v_rcp_f32_e32 v60, v60
	v_rcp_f32_e32 v61, v61
	v_cvt_pk_bf16_f32 v63, v58, v59
	v_mov_b32_e32 v58, v54
	v_mov_b32_e32 v59, v56
	v_mul_f32_e32 v54, 0xbfb8aa3b, v50
	v_pk_mul_f32 v[58:59], v[58:59], v[60:61]
	v_exp_f32_e32 v60, v54
	v_mul_f32_e32 v54, 0xbfb8aa3b, v52
	v_exp_f32_e32 v61, v54
	v_mov_b32_e32 v56, v55
	v_pk_mul_f32 v[54:55], v[56:57], v[58:59]
	v_add_f32_e32 v56, 1.0, v60
	v_add_f32_e32 v57, 1.0, v61
	v_rcp_f32_e32 v56, v56
	v_rcp_f32_e32 v57, v57
	v_cvt_pk_bf16_f32 v64, v54, v55
	v_mov_b32_e32 v54, v50
	v_mov_b32_e32 v55, v52
	v_pk_mul_f32 v[54:55], v[54:55], v[56:57]
	v_mov_b32_e32 v52, v51
	v_pk_mul_f32 v[50:51], v[52:53], v[54:55]
	v_mul_f32_e32 v52, 0xbfb8aa3b, v46
	v_mul_f32_e32 v53, 0xbfb8aa3b, v48
	v_or_b32_e32 v70, 64, v110
	v_exp_f32_e32 v52, v52
	v_exp_f32_e32 v53, v53
	v_cvt_pk_bf16_f32 v65, v50, v51
	v_mad_i64_i32 v[50:51], s[16:17], v70, s38, v[106:107]
	v_lshl_add_u64 v[50:51], v[50:51], 0, v[108:109]
	v_lshl_add_u64 v[50:51], v[50:51], 0, v[190:191]
	global_store_dwordx4 v[50:51], v[62:65], off
	v_add_f32_e32 v50, 1.0, v52
	v_add_f32_e32 v51, 1.0, v53
	v_rcp_f32_e32 v50, v50
	v_rcp_f32_e32 v51, v51
	v_mov_b32_e32 v52, v46
	v_mov_b32_e32 v53, v48
	v_mul_f32_e32 v46, 0xbfb8aa3b, v42
	v_pk_mul_f32 v[50:51], v[52:53], v[50:51]
	v_exp_f32_e32 v52, v46
	v_mul_f32_e32 v46, 0xbfb8aa3b, v44
	v_exp_f32_e32 v53, v46
	v_mov_b32_e32 v48, v47
	v_pk_mul_f32 v[46:47], v[48:49], v[50:51]
	v_add_f32_e32 v48, 1.0, v52
	v_add_f32_e32 v49, 1.0, v53
	v_rcp_f32_e32 v48, v48
	v_rcp_f32_e32 v49, v49
	v_mov_b32_e32 v50, v42
	v_mul_f32_e32 v42, 0xbfb8aa3b, v38
	v_cvt_pk_bf16_f32 v46, v46, v47
	v_mov_b32_e32 v51, v44
	v_exp_f32_e32 v47, v42
	v_mul_f32_e32 v42, 0xbfb8aa3b, v40
	v_pk_mul_f32 v[48:49], v[50:51], v[48:49]
	v_exp_f32_e32 v50, v42
	v_mov_b32_e32 v44, v43
	v_pk_mul_f32 v[42:43], v[44:45], v[48:49]
	v_add_f32_e32 v44, 1.0, v47
	v_add_f32_e32 v45, 1.0, v50
	v_rcp_f32_e32 v44, v44
	v_rcp_f32_e32 v45, v45
	v_cvt_pk_bf16_f32 v47, v42, v43
	v_mov_b32_e32 v42, v38
	v_mov_b32_e32 v43, v40
	v_mul_f32_e32 v38, 0xbfb8aa3b, v34
	v_pk_mul_f32 v[42:43], v[42:43], v[44:45]
	v_exp_f32_e32 v44, v38
	v_mul_f32_e32 v38, 0xbfb8aa3b, v36
	v_exp_f32_e32 v45, v38
	v_mov_b32_e32 v40, v39
	v_pk_mul_f32 v[38:39], v[40:41], v[42:43]
	v_add_f32_e32 v40, 1.0, v44
	v_add_f32_e32 v41, 1.0, v45
	v_rcp_f32_e32 v40, v40
	v_rcp_f32_e32 v41, v41
	v_cvt_pk_bf16_f32 v48, v38, v39
	v_mov_b32_e32 v38, v34
	v_mov_b32_e32 v39, v36
	v_pk_mul_f32 v[38:39], v[38:39], v[40:41]
	v_mov_b32_e32 v36, v35
	v_pk_mul_f32 v[34:35], v[36:37], v[38:39]
	v_mul_f32_e32 v36, 0xbfb8aa3b, v30
	v_mul_f32_e32 v37, 0xbfb8aa3b, v32
	v_or_b32_e32 v54, 0x50, v110
	v_exp_f32_e32 v36, v36
	v_exp_f32_e32 v37, v37
	v_cvt_pk_bf16_f32 v49, v34, v35
	v_mad_i64_i32 v[34:35], s[16:17], v54, s38, v[106:107]
	v_lshl_add_u64 v[34:35], v[34:35], 0, v[108:109]
	v_lshl_add_u64 v[34:35], v[34:35], 0, v[190:191]
	global_store_dwordx4 v[34:35], v[46:49], off
	v_add_f32_e32 v34, 1.0, v36
; DI unsigned pack2(float a, float b) { hwf2_t f = {a, b}; return __builtin_bit_cast(unsigned, __builtin_convertvector(f, hwbf2_t)); }
; DI float fsigmoid(float x) { return __builtin_amdgcn_rcpf(1.f + __expf(-x)); }
; DI void phase_ffn_up(char* smem, const Params& p, int layer) {
;     ...
;   auto ep = [=](int row, int cb, int q4, const f32x4& c0, const f32x4& c1, const f32x4& c2, const f32x4& c3) {
;     const uint4 o = make_uint4(pack2(c0[0] * fsigmoid(c0[0]) * c0[1], c0[2] * fsigmoid(c0[2]) * c0[3]),
;                                pack2(c1[0] * fsigmoid(c1[0]) * c1[1], c1[2] * fsigmoid(c1[2]) * c1[3]),
;                                pack2(c2[0] * fsigmoid(c2[0]) * c2[1], c2[2] * fsigmoid(c2[2]) * c2[3]),
;                                pack2(c3[0] * fsigmoid(c3[0]) * c3[1], c3[2] * fsigmoid(c3[2]) * c3[3]));
;     *(uint4*)(Hh + (size_t)row * FH + (cb >> 1) + q4 * 8) = o;
	v_add_f32_e32 v35, 1.0, v37
	v_rcp_f32_e32 v34, v34
	v_rcp_f32_e32 v35, v35
	v_mov_b32_e32 v36, v30
	v_mov_b32_e32 v37, v32
	v_mul_f32_e32 v30, 0xbfb8aa3b, v26
	v_pk_mul_f32 v[34:35], v[36:37], v[34:35]
	v_exp_f32_e32 v36, v30
	v_mul_f32_e32 v30, 0xbfb8aa3b, v28
	v_exp_f32_e32 v37, v30
	v_mov_b32_e32 v32, v31
	v_pk_mul_f32 v[30:31], v[32:33], v[34:35]
	v_add_f32_e32 v32, 1.0, v36
	v_add_f32_e32 v33, 1.0, v37
	v_rcp_f32_e32 v32, v32
	v_rcp_f32_e32 v33, v33
	v_mov_b32_e32 v34, v26
	v_mul_f32_e32 v26, 0xbfb8aa3b, v22
	v_cvt_pk_bf16_f32 v30, v30, v31
	v_mov_b32_e32 v35, v28
	v_exp_f32_e32 v31, v26
	v_mul_f32_e32 v26, 0xbfb8aa3b, v24
	v_pk_mul_f32 v[32:33], v[34:35], v[32:33]
	v_exp_f32_e32 v34, v26
	v_mov_b32_e32 v28, v27
	v_pk_mul_f32 v[26:27], v[28:29], v[32:33]
	v_add_f32_e32 v28, 1.0, v31
	v_add_f32_e32 v29, 1.0, v34
	v_rcp_f32_e32 v28, v28
	v_rcp_f32_e32 v29, v29
	v_cvt_pk_bf16_f32 v31, v26, v27
	v_mov_b32_e32 v26, v22
	v_mov_b32_e32 v27, v24
	v_mul_f32_e32 v22, 0xbfb8aa3b, v18
	v_pk_mul_f32 v[26:27], v[26:27], v[28:29]
	v_exp_f32_e32 v28, v22
	v_mul_f32_e32 v22, 0xbfb8aa3b, v20
	v_exp_f32_e32 v29, v22
	v_mov_b32_e32 v24, v23
	v_pk_mul_f32 v[22:23], v[24:25], v[26:27]
	v_add_f32_e32 v24, 1.0, v28
	v_add_f32_e32 v25, 1.0, v29
	v_rcp_f32_e32 v24, v24
	v_rcp_f32_e32 v25, v25
	v_cvt_pk_bf16_f32 v32, v22, v23
	v_mov_b32_e32 v22, v18
	v_mov_b32_e32 v23, v20
	v_pk_mul_f32 v[22:23], v[22:23], v[24:25]
	v_mov_b32_e32 v20, v19
	v_pk_mul_f32 v[18:19], v[20:21], v[22:23]
	v_mul_f32_e32 v20, 0xbfb8aa3b, v14
	v_mul_f32_e32 v21, 0xbfb8aa3b, v16
	v_or_b32_e32 v38, 0x60, v110
	v_exp_f32_e32 v20, v20
	v_exp_f32_e32 v21, v21
	v_cvt_pk_bf16_f32 v33, v18, v19
	v_mad_i64_i32 v[18:19], s[16:17], v38, s38, v[106:107]
	v_lshl_add_u64 v[18:19], v[18:19], 0, v[108:109]
	v_lshl_add_u64 v[18:19], v[18:19], 0, v[190:191]
	global_store_dwordx4 v[18:19], v[30:33], off
	v_add_f32_e32 v18, 1.0, v20
	v_add_f32_e32 v19, 1.0, v21
	v_rcp_f32_e32 v18, v18
	v_rcp_f32_e32 v19, v19
	v_mov_b32_e32 v20, v14
	v_mov_b32_e32 v21, v16
	v_mul_f32_e32 v14, 0xbfb8aa3b, v10
	v_pk_mul_f32 v[18:19], v[20:21], v[18:19]
	v_exp_f32_e32 v20, v14
	v_mul_f32_e32 v14, 0xbfb8aa3b, v12
	v_exp_f32_e32 v21, v14
	v_mov_b32_e32 v16, v15
	v_pk_mul_f32 v[14:15], v[16:17], v[18:19]
	v_add_f32_e32 v16, 1.0, v20
	v_add_f32_e32 v17, 1.0, v21
	v_rcp_f32_e32 v16, v16
	v_rcp_f32_e32 v17, v17
	v_mov_b32_e32 v18, v10
	v_mul_f32_e32 v10, 0xbfb8aa3b, v6
	v_cvt_pk_bf16_f32 v14, v14, v15
	v_mov_b32_e32 v19, v12
	v_exp_f32_e32 v15, v10
	v_mul_f32_e32 v10, 0xbfb8aa3b, v8
	v_pk_mul_f32 v[16:17], v[18:19], v[16:17]
	v_exp_f32_e32 v18, v10
	v_mov_b32_e32 v12, v11
	v_pk_mul_f32 v[10:11], v[12:13], v[16:17]
	v_add_f32_e32 v12, 1.0, v15
	v_add_f32_e32 v13, 1.0, v18
	v_rcp_f32_e32 v12, v12
	v_rcp_f32_e32 v13, v13
	v_cvt_pk_bf16_f32 v15, v10, v11
	v_mov_b32_e32 v10, v6
	v_mov_b32_e32 v11, v8
	v_mul_f32_e32 v6, 0xbfb8aa3b, v2
	v_pk_mul_f32 v[10:11], v[10:11], v[12:13]
	v_exp_f32_e32 v12, v6
	v_mul_f32_e32 v6, 0xbfb8aa3b, v4
	v_exp_f32_e32 v13, v6
	v_mov_b32_e32 v8, v7
	v_pk_mul_f32 v[6:7], v[8:9], v[10:11]
	v_add_f32_e32 v8, 1.0, v12
	v_add_f32_e32 v9, 1.0, v13
	v_rcp_f32_e32 v8, v8
	v_rcp_f32_e32 v9, v9
	v_cvt_pk_bf16_f32 v16, v6, v7
	v_mov_b32_e32 v6, v2
	v_mov_b32_e32 v7, v4
	v_pk_mul_f32 v[6:7], v[6:7], v[8:9]
	v_mov_b32_e32 v4, v3
	v_or_b32_e32 v22, 0x70, v110
	v_pk_mul_f32 v[2:3], v[4:5], v[6:7]
	s_add_i32 s37, s37, s30
	v_cvt_pk_bf16_f32 v17, v2, v3
	v_mad_i64_i32 v[2:3], s[16:17], v22, s38, v[106:107]
	v_lshl_add_u64 v[2:3], v[2:3], 0, v[108:109]
	s_cmp_gt_i32 s37, 31
	v_lshl_add_u64 v[2:3], v[2:3], 0, v[190:191]
	s_cselect_b64 s[16:17], -1, 0
	v_readlane_b32 s53, v253, 41
	v_readlane_b32 s56, v253, 44
	v_readlane_b32 s57, v253, 45
	v_readlane_b32 s58, v253, 46
	v_readlane_b32 s59, v253, 47
	v_readlane_b32 s60, v253, 48
	v_readlane_b32 s61, v253, 49
	v_readlane_b32 s62, v253, 50
	v_readlane_b32 s63, v253, 51
	v_readlane_b32 s64, v253, 52
	v_readlane_b32 s65, v253, 53
	v_readlane_b32 s66, v253, 54
	v_readlane_b32 s67, v253, 55
	global_store_dwordx4 v[2:3], v[14:17], off
	s_branch .LBB0_68

; #define MFMA16(a, b, c) __builtin_amdgcn_mfma_f32_16x16x32_bf16((a), (b), (c), 0, 0, 0)
;     ...
;   for (int kt = 0; kt < nk; ++kt) {
;     const int buf = kt & 1;
;     const char* cA = smem + buf * STAGE + (wm * 32 * MI + r16) * 128;
;     const char* cB = smem + buf * STAGE + 32768 + (wn * 64 + r16) * 128;
; #pragma unroll
;     for (int k2 = 0; k2 < 2; ++k2) {
;       if (k2 == 1 && kt + 1 < nk) STAGE_TILE(buf ^ 1, (kt + 1) * 64)
;       const int po = ((4 * k2 + q4) ^ swz) * 16;
;       bf16x8 bf[4];
; #pragma unroll
;       for (int nt = 0; nt < 4; ++nt) bf[nt] = *(const bf16x8*)(cB + nt * 16 * 128 + po);
;       bf16x8 afc = *(const bf16x8*)(cA + po);
; #pragma unroll
;       for (int a = 0; a < MT; ++a) {
;         bf16x8 afn = afc;
;         if (a + 1 < MT) afn = *(const bf16x8*)(cA + (a + 1) * 16 * 128 + po);
;         __builtin_amdgcn_sched_barrier(0);
; #pragma unroll
;         for (int nt = 0; nt < 4; ++nt) acc[a][nt] = MFMA16(bf[nt], afc, acc[a][nt]);
;         __builtin_amdgcn_sched_barrier(0);
;         afc = afn;
;       }
;     }
;     asm volatile("s_waitcnt vmcnt(0)" ::: "memory");
;     __syncthreads();
;   }
.LBB0_84:
	s_and_b32 s30, s27, 0x10000
	s_add_i32 s31, s30, 0
	v_add_u32_e32 v122, s31, v83
	v_lshl_add_u64 v[86:87], v[74:75], 0, s[14:15]
	v_add_u32_e32 v98, v122, v82
	v_add_u32_e32 v85, s31, v84
	v_lshl_add_u64 v[110:111], v[86:87], 0, s[24:25]
	v_lshl_add_u64 v[112:113], v[86:87], 0, s[84:85]
	ds_read_b128 v[86:89], v98 offset:32768
	ds_read_b128 v[90:93], v98 offset:34816
	ds_read_b128 v[94:97], v98 offset:36864
	ds_read_b128 v[98:101], v98 offset:38912
	v_add_u32_e32 v127, v85, v82
	ds_read_b128 v[102:105], v127
	ds_read_b128 v[106:109], v127 offset:2048
	s_xor_b32 s30, s30, 0x10000
	v_add_u32_e32 v123, s30, v81
	v_add_u32_e32 v124, 0x2000, v123
	v_lshl_add_u64 v[114:115], v[72:73], 0, s[14:15]
	v_add_u32_e32 v125, 0x8000, v123
	v_lshl_add_u64 v[116:117], v[70:71], 0, s[14:15]
	v_add_u32_e32 v126, 0xa000, v123
	v_lshl_add_u64 v[118:119], v[68:69], 0, s[14:15]
	v_add_u32_e32 v128, 0xc000, v123
	v_lshl_add_u64 v[120:121], v[66:67], 0, s[14:15]
	v_add_u32_e32 v129, 0xe000, v123
	s_waitcnt lgkmcnt(1)
	v_mfma_f32_16x16x32_bf16 v[62:65], v[86:89], v[102:105], v[62:65]
	v_mfma_f32_16x16x32_bf16 v[58:61], v[90:93], v[102:105], v[58:61]
	v_mfma_f32_16x16x32_bf16 v[54:57], v[94:97], v[102:105], v[54:57]
	v_mfma_f32_16x16x32_bf16 v[50:53], v[98:101], v[102:105], v[50:53]
	ds_read_b128 v[102:105], v127 offset:4096
	s_waitcnt lgkmcnt(1)
	v_mfma_f32_16x16x32_bf16 v[46:49], v[86:89], v[106:109], v[46:49]
	v_mfma_f32_16x16x32_bf16 v[42:45], v[90:93], v[106:109], v[42:45]
	v_mfma_f32_16x16x32_bf16 v[38:41], v[94:97], v[106:109], v[38:41]
	v_mfma_f32_16x16x32_bf16 v[34:37], v[98:101], v[106:109], v[34:37]
	ds_read_b128 v[106:109], v127 offset:6144
	s_waitcnt lgkmcnt(1)
	v_mfma_f32_16x16x32_bf16 v[30:33], v[86:89], v[102:105], v[30:33]
	v_mfma_f32_16x16x32_bf16 v[26:29], v[90:93], v[102:105], v[26:29]
	v_mfma_f32_16x16x32_bf16 v[22:25], v[94:97], v[102:105], v[22:25]
	v_mfma_f32_16x16x32_bf16 v[18:21], v[98:101], v[102:105], v[18:21]
	s_waitcnt lgkmcnt(0)
	v_mfma_f32_16x16x32_bf16 v[14:17], v[86:89], v[106:109], v[14:17]
	v_mfma_f32_16x16x32_bf16 v[10:13], v[90:93], v[106:109], v[10:13]
	v_mfma_f32_16x16x32_bf16 v[6:9], v[94:97], v[106:109], v[6:9]
	v_mfma_f32_16x16x32_bf16 v[2:5], v[98:101], v[106:109], v[2:5]
	v_readfirstlane_b32 s30, v123
	s_mov_b32 m0, s30
	v_readfirstlane_b32 s30, v124
	global_load_lds_dwordx4 v[110:111], off
	s_mov_b32 m0, s30
	v_readfirstlane_b32 s30, v125
	global_load_lds_dwordx4 v[112:113], off
	s_mov_b32 m0, s30
	v_readfirstlane_b32 s30, v126
	global_load_lds_dwordx4 v[114:115], off
	s_mov_b32 m0, s30
	v_readfirstlane_b32 s30, v128
	global_load_lds_dwordx4 v[116:117], off
	s_mov_b32 m0, s30
	v_readfirstlane_b32 s30, v129
	global_load_lds_dwordx4 v[118:119], off
	s_mov_b32 m0, s30
	v_add_u32_e32 v98, v122, v80
	global_load_lds_dwordx4 v[120:121], off
	ds_read_b128 v[86:89], v98 offset:32768
	ds_read_b128 v[90:93], v98 offset:34816
	ds_read_b128 v[94:97], v98 offset:36864
	ds_read_b128 v[98:101], v98 offset:38912
	v_add_u32_e32 v85, v85, v80
	ds_read_b128 v[102:105], v85
	ds_read_b128 v[106:109], v85 offset:2048
	s_waitcnt lgkmcnt(0)
	v_mfma_f32_16x16x32_bf16 v[62:65], v[86:89], v[102:105], v[62:65]
	v_mfma_f32_16x16x32_bf16 v[58:61], v[90:93], v[102:105], v[58:61]
	v_mfma_f32_16x16x32_bf16 v[54:57], v[94:97], v[102:105], v[54:57]
	v_mfma_f32_16x16x32_bf16 v[50:53], v[98:101], v[102:105], v[50:53]
	ds_read_b128 v[102:105], v85 offset:4096
	v_mfma_f32_16x16x32_bf16 v[46:49], v[86:89], v[106:109], v[46:49]
	v_mfma_f32_16x16x32_bf16 v[42:45], v[90:93], v[106:109], v[42:45]
	v_mfma_f32_16x16x32_bf16 v[38:41], v[94:97], v[106:109], v[38:41]
	v_mfma_f32_16x16x32_bf16 v[34:37], v[98:101], v[106:109], v[34:37]
	ds_read_b128 v[106:109], v85 offset:6144
	s_waitcnt lgkmcnt(0)
	v_mfma_f32_16x16x32_bf16 v[30:33], v[86:89], v[102:105], v[30:33]
	v_mfma_f32_16x16x32_bf16 v[26:29], v[90:93], v[102:105], v[26:29]
	v_mfma_f32_16x16x32_bf16 v[22:25], v[94:97], v[102:105], v[22:25]
	v_mfma_f32_16x16x32_bf16 v[18:21], v[98:101], v[102:105], v[18:21]
	v_mfma_f32_16x16x32_bf16 v[14:17], v[86:89], v[106:109], v[14:17]
	v_mfma_f32_16x16x32_bf16 v[10:13], v[90:93], v[106:109], v[10:13]
	v_mfma_f32_16x16x32_bf16 v[6:9], v[94:97], v[106:109], v[6:9]
	v_mfma_f32_16x16x32_bf16 v[2:5], v[98:101], v[106:109], v[2:5]
	s_waitcnt vmcnt(0)
	s_add_u32 s14, s14, 0x80
	s_addc_u32 s15, s15, 0
	s_add_i32 s27, s27, 0x10000
	s_cmpk_lg_i32 s14, 0x780
	s_waitcnt vmcnt(0)
	s_barrier
	s_cbranch_scc1 .LBB0_84
; #define MFMA16(a, b, c) __builtin_amdgcn_mfma_f32_16x16x32_bf16((a), (b), (c), 0, 0, 0)
; DI unsigned pack2(float a, float b) { hwf2_t f = {a, b}; return __builtin_bit_cast(unsigned, __builtin_convertvector(f, hwbf2_t)); }
; DI float fsigmoid(float x) { return __builtin_amdgcn_rcpf(1.f + __expf(-x)); }
;     ...
;   for (int kt = 0; kt < nk; ++kt) {
;     const int buf = kt & 1;
;     const char* cA = smem + buf * STAGE + (wm * 32 * MI + r16) * 128;
;     const char* cB = smem + buf * STAGE + 32768 + (wn * 64 + r16) * 128;
; #pragma unroll
;     for (int k2 = 0; k2 < 2; ++k2) {
;       if (k2 == 1 && kt + 1 < nk) STAGE_TILE(buf ^ 1, (kt + 1) * 64)
;       const int po = ((4 * k2 + q4) ^ swz) * 16;
;       bf16x8 bf[4];
; #pragma unroll
;       for (int nt = 0; nt < 4; ++nt) bf[nt] = *(const bf16x8*)(cB + nt * 16 * 128 + po);
;       bf16x8 afc = *(const bf16x8*)(cA + po);
; #pragma unroll
;       for (int a = 0; a < MT; ++a) {
;         bf16x8 afn = afc;
;         if (a + 1 < MT) afn = *(const bf16x8*)(cA + (a + 1) * 16 * 128 + po);
;         __builtin_amdgcn_sched_barrier(0);
; #pragma unroll
;         for (int nt = 0; nt < 4; ++nt) acc[a][nt] = MFMA16(bf[nt], afc, acc[a][nt]);
;         __builtin_amdgcn_sched_barrier(0);
;         afc = afn;
;       }
;     }
;     asm volatile("s_waitcnt vmcnt(0)" ::: "memory");
;     __syncthreads();
;   }
; DI void phase_ffn_up(char* smem, const Params& p, int layer) {
;     ...
;   auto ep = [=](int row, int cb, int q4, const f32x4& c0, const f32x4& c1, const f32x4& c2, const f32x4& c3) {
;     const uint4 o = make_uint4(pack2(c0[0] * fsigmoid(c0[0]) * c0[1], c0[2] * fsigmoid(c0[2]) * c0[3]),
;                                pack2(c1[0] * fsigmoid(c1[0]) * c1[1], c1[2] * fsigmoid(c1[2]) * c1[3]),
;                                pack2(c2[0] * fsigmoid(c2[0]) * c2[1], c2[2] * fsigmoid(c2[2]) * c2[3]),
;                                pack2(c3[0] * fsigmoid(c3[0]) * c3[1], c3[2] * fsigmoid(c3[2]) * c3[3]));
;     *(uint4*)(Hh + (size_t)row * FH + (cb >> 1) + q4 * 8) = o;
	s_add_i32 s14, 0, 0x10000
	v_add_u32_e32 v74, s14, v84
	v_readlane_b32 s14, v254, 18
	s_nop 1
	v_add_u32_e32 v75, s14, v83
	v_add_u32_e32 v81, v75, v82
	ds_read_b128 v[66:69], v81
	ds_read_b128 v[70:73], v81 offset:2048
	ds_read_b128 v[84:87], v81 offset:4096
	ds_read_b128 v[88:91], v81 offset:6144
	v_add_u32_e32 v81, v74, v82
	ds_read_b128 v[92:95], v81
	ds_read_b128 v[96:99], v81 offset:2048
	s_waitcnt lgkmcnt(1)
	v_mfma_f32_16x16x32_bf16 v[62:65], v[66:69], v[92:95], v[62:65]
	v_mfma_f32_16x16x32_bf16 v[58:61], v[70:73], v[92:95], v[58:61]
	v_mfma_f32_16x16x32_bf16 v[54:57], v[84:87], v[92:95], v[54:57]
	v_mfma_f32_16x16x32_bf16 v[50:53], v[88:91], v[92:95], v[50:53]
	ds_read_b128 v[92:95], v81 offset:4096
	s_waitcnt lgkmcnt(1)
	v_mfma_f32_16x16x32_bf16 v[46:49], v[66:69], v[96:99], v[46:49]
	v_mfma_f32_16x16x32_bf16 v[42:45], v[70:73], v[96:99], v[42:45]
	v_mfma_f32_16x16x32_bf16 v[38:41], v[84:87], v[96:99], v[38:41]
	v_mfma_f32_16x16x32_bf16 v[34:37], v[88:91], v[96:99], v[34:37]
	ds_read_b128 v[96:99], v81 offset:6144
	s_waitcnt lgkmcnt(1)
	v_mfma_f32_16x16x32_bf16 v[30:33], v[66:69], v[92:95], v[30:33]
	v_mfma_f32_16x16x32_bf16 v[26:29], v[70:73], v[92:95], v[26:29]
	v_mfma_f32_16x16x32_bf16 v[22:25], v[84:87], v[92:95], v[22:25]
	v_mfma_f32_16x16x32_bf16 v[18:21], v[88:91], v[92:95], v[18:21]
	s_waitcnt lgkmcnt(0)
	v_mfma_f32_16x16x32_bf16 v[14:17], v[66:69], v[96:99], v[14:17]
	v_mfma_f32_16x16x32_bf16 v[10:13], v[70:73], v[96:99], v[10:13]
	v_mfma_f32_16x16x32_bf16 v[6:9], v[84:87], v[96:99], v[6:9]
	v_mfma_f32_16x16x32_bf16 v[2:5], v[88:91], v[96:99], v[2:5]
	v_add_u32_e32 v75, v75, v80
	ds_read_b128 v[66:69], v75
	ds_read_b128 v[70:73], v75 offset:2048
	ds_read_b128 v[82:85], v75 offset:4096
	ds_read_b128 v[86:89], v75 offset:6144
	v_add_u32_e32 v74, v74, v80
	ds_read_b128 v[90:93], v74
	ds_read_b128 v[94:97], v74 offset:2048
	s_waitcnt lgkmcnt(1)
	v_mfma_f32_16x16x32_bf16 v[62:65], v[66:69], v[90:93], v[62:65]
	v_mfma_f32_16x16x32_bf16 v[58:61], v[70:73], v[90:93], v[58:61]
	v_mfma_f32_16x16x32_bf16 v[54:57], v[82:85], v[90:93], v[54:57]
	v_mfma_f32_16x16x32_bf16 v[50:53], v[86:89], v[90:93], v[50:53]
	ds_read_b128 v[90:93], v74 offset:4096
	s_waitcnt lgkmcnt(1)
	v_mfma_f32_16x16x32_bf16 v[46:49], v[66:69], v[94:97], v[46:49]
	v_mfma_f32_16x16x32_bf16 v[42:45], v[70:73], v[94:97], v[42:45]
	v_mfma_f32_16x16x32_bf16 v[38:41], v[82:85], v[94:97], v[38:41]
	v_mfma_f32_16x16x32_bf16 v[94:97], v[86:89], v[94:97], v[34:37]
	s_nop 2
	ds_read_b128 v[34:37], v74 offset:6144
	s_waitcnt lgkmcnt(1)
	v_mfma_f32_16x16x32_bf16 v[30:33], v[66:69], v[90:93], v[30:33]
	v_mfma_f32_16x16x32_bf16 v[26:29], v[70:73], v[90:93], v[26:29]
	v_mfma_f32_16x16x32_bf16 v[22:25], v[82:85], v[90:93], v[22:25]
	v_mfma_f32_16x16x32_bf16 v[18:21], v[86:89], v[90:93], v[18:21]
	s_waitcnt lgkmcnt(0)
	v_mfma_f32_16x16x32_bf16 v[14:17], v[66:69], v[34:37], v[14:17]
	v_mfma_f32_16x16x32_bf16 v[10:13], v[70:73], v[34:37], v[10:13]
	v_mfma_f32_16x16x32_bf16 v[6:9], v[82:85], v[34:37], v[6:9]
	v_mfma_f32_16x16x32_bf16 v[2:5], v[86:89], v[34:37], v[2:5]
	v_or_b32_e32 v35, s17, v78
	v_lshl_add_u32 v68, v77, 6, v35
	v_mul_f32_e32 v35, 0xbfb8aa3b, v62
	v_mul_f32_e32 v36, 0xbfb8aa3b, v64
	v_exp_f32_e32 v35, v35
	v_exp_f32_e32 v37, v36
	v_lshl_or_b32 v34, v79, 6, s23
	v_ashrrev_i32_e32 v36, 1, v34
	v_add_f32_e32 v34, 1.0, v35
	v_add_f32_e32 v35, 1.0, v37
	v_mov_b32_e32 v66, v62
	v_mul_f32_e32 v62, 0xbfb8aa3b, v58
	v_rcp_f32_e32 v34, v34
	v_rcp_f32_e32 v35, v35
	v_mov_b32_e32 v67, v64
	v_mov_b32_e32 v64, v63
	v_exp_f32_e32 v62, v62
	v_mul_f32_e32 v63, 0xbfb8aa3b, v60
	v_exp_f32_e32 v63, v63
	v_pk_mul_f32 v[34:35], v[66:67], v[34:35]
	v_add_f32_e32 v62, 1.0, v62
	v_pk_mul_f32 v[34:35], v[64:65], v[34:35]
	v_rcp_f32_e32 v64, v62
	v_add_f32_e32 v62, 1.0, v63
	v_rcp_f32_e32 v65, v62
	v_cvt_pk_bf16_f32 v62, v34, v35
	v_mov_b32_e32 v34, v58
	v_mov_b32_e32 v35, v60
	v_mov_b32_e32 v60, v59
	v_mul_f32_e32 v58, 0xbfb8aa3b, v54
	v_mul_f32_e32 v59, 0xbfb8aa3b, v56
	v_pk_mul_f32 v[34:35], v[34:35], v[64:65]
	v_exp_f32_e32 v58, v58
	v_exp_f32_e32 v59, v59
	v_pk_mul_f32 v[34:35], v[60:61], v[34:35]
	v_readlane_b32 s52, v253, 40
	v_cvt_pk_bf16_f32 v63, v34, v35
	v_mov_b32_e32 v34, v54
	v_mov_b32_e32 v35, v56
	v_mov_b32_e32 v56, v55
	v_mul_f32_e32 v54, 0xbfb8aa3b, v50
	v_mul_f32_e32 v55, 0xbfb8aa3b, v52
	v_exp_f32_e32 v54, v54
	v_exp_f32_e32 v55, v55
	v_add_f32_e32 v58, 1.0, v58
	v_add_f32_e32 v59, 1.0, v59
	v_rcp_f32_e32 v58, v58
	v_rcp_f32_e32 v59, v59
	v_add_f32_e32 v54, 1.0, v54
	v_add_f32_e32 v55, 1.0, v55
	v_rcp_f32_e32 v54, v54
	v_rcp_f32_e32 v55, v55
	v_pk_mul_f32 v[34:35], v[34:35], v[58:59]
	v_readlane_b32 s54, v253, 42
	v_pk_mul_f32 v[34:35], v[56:57], v[34:35]
	v_readlane_b32 s55, v253, 43
	v_cvt_pk_bf16_f32 v64, v34, v35
	v_mov_b32_e32 v34, v50
	v_mov_b32_e32 v35, v52
	v_pk_mul_f32 v[34:35], v[34:35], v[54:55]
	v_mov_b32_e32 v52, v51
	v_pk_mul_f32 v[34:35], v[52:53], v[34:35]
	v_mul_f32_e32 v52, 0xbfb8aa3b, v46
	v_mul_f32_e32 v53, 0xbfb8aa3b, v48
	v_ashrrev_i32_e32 v37, 31, v36
	v_cvt_pk_bf16_f32 v65, v34, v35
	v_mov_b64_e32 v[34:35], s[54:55]
	s_movk_i32 s17, 0x1600
	v_exp_f32_e32 v52, v52
	v_exp_f32_e32 v53, v53
	v_mad_i64_i32 v[50:51], s[14:15], v68, s17, v[34:35]
	v_lshlrev_b64 v[36:37], 1, v[36:37]
	v_lshl_add_u64 v[50:51], v[50:51], 0, v[36:37]
	v_lshlrev_b32_e32 v190, 4, v76
	v_lshl_add_u64 v[50:51], v[50:51], 0, v[190:191]
	s_waitcnt vmcnt(0)
	s_barrier
; DI unsigned pack2(float a, float b) { hwf2_t f = {a, b}; return __builtin_bit_cast(unsigned, __builtin_convertvector(f, hwbf2_t)); }
; DI float fsigmoid(float x) { return __builtin_amdgcn_rcpf(1.f + __expf(-x)); }
; DI void phase_ffn_up(char* smem, const Params& p, int layer) {
;     ...
;   auto ep = [=](int row, int cb, int q4, const f32x4& c0, const f32x4& c1, const f32x4& c2, const f32x4& c3) {
;     const uint4 o = make_uint4(pack2(c0[0] * fsigmoid(c0[0]) * c0[1], c0[2] * fsigmoid(c0[2]) * c0[3]),
;                                pack2(c1[0] * fsigmoid(c1[0]) * c1[1], c1[2] * fsigmoid(c1[2]) * c1[3]),
;                                pack2(c2[0] * fsigmoid(c2[0]) * c2[1], c2[2] * fsigmoid(c2[2]) * c2[3]),
;                                pack2(c3[0] * fsigmoid(c3[0]) * c3[1], c3[2] * fsigmoid(c3[2]) * c3[3]));
;     *(uint4*)(Hh + (size_t)row * FH + (cb >> 1) + q4 * 8) = o;
	global_store_dwordx4 v[50:51], v[62:65], off
	v_add_f32_e32 v50, 1.0, v52
	v_add_f32_e32 v51, 1.0, v53
	v_rcp_f32_e32 v50, v50
	v_rcp_f32_e32 v51, v51
	v_mov_b32_e32 v52, v46
	v_mov_b32_e32 v53, v48
	v_mul_f32_e32 v46, 0xbfb8aa3b, v42
	v_pk_mul_f32 v[50:51], v[52:53], v[50:51]
	v_exp_f32_e32 v52, v46
	v_mul_f32_e32 v46, 0xbfb8aa3b, v44
	v_exp_f32_e32 v53, v46
	v_mov_b32_e32 v48, v47
	v_pk_mul_f32 v[46:47], v[48:49], v[50:51]
	v_add_f32_e32 v48, 1.0, v52
	v_add_f32_e32 v49, 1.0, v53
	v_rcp_f32_e32 v48, v48
	v_rcp_f32_e32 v49, v49
	v_mov_b32_e32 v50, v42
	v_mul_f32_e32 v42, 0xbfb8aa3b, v38
	v_cvt_pk_bf16_f32 v46, v46, v47
	v_mov_b32_e32 v51, v44
	v_exp_f32_e32 v47, v42
	v_mul_f32_e32 v42, 0xbfb8aa3b, v40
	v_pk_mul_f32 v[48:49], v[50:51], v[48:49]
	v_exp_f32_e32 v50, v42
	v_mov_b32_e32 v44, v43
	v_pk_mul_f32 v[42:43], v[44:45], v[48:49]
	v_add_f32_e32 v44, 1.0, v47
	v_add_f32_e32 v45, 1.0, v50
	v_rcp_f32_e32 v44, v44
	v_rcp_f32_e32 v45, v45
	v_cvt_pk_bf16_f32 v47, v42, v43
	v_mov_b32_e32 v42, v38
	v_mov_b32_e32 v43, v40
	v_mul_f32_e32 v38, 0xbfb8aa3b, v94
	v_pk_mul_f32 v[42:43], v[42:43], v[44:45]
	v_exp_f32_e32 v44, v38
	v_mul_f32_e32 v38, 0xbfb8aa3b, v96
	v_exp_f32_e32 v45, v38
	v_mov_b32_e32 v40, v39
	v_pk_mul_f32 v[38:39], v[40:41], v[42:43]
	v_add_f32_e32 v40, 1.0, v44
	v_add_f32_e32 v41, 1.0, v45
	v_rcp_f32_e32 v40, v40
	v_rcp_f32_e32 v41, v41
	v_cvt_pk_bf16_f32 v48, v38, v39
	v_mov_b32_e32 v38, v94
	v_mov_b32_e32 v39, v96
	v_pk_mul_f32 v[38:39], v[38:39], v[40:41]
	v_mov_b32_e32 v96, v95
	v_mul_f32_e32 v40, 0xbfb8aa3b, v30
	v_mul_f32_e32 v41, 0xbfb8aa3b, v32
	v_or_b32_e32 v54, 16, v68
	v_pk_mul_f32 v[38:39], v[96:97], v[38:39]
	v_exp_f32_e32 v40, v40
	v_exp_f32_e32 v41, v41
	v_cvt_pk_bf16_f32 v49, v38, v39
	v_mad_i64_i32 v[38:39], s[14:15], v54, s17, v[34:35]
	v_lshl_add_u64 v[38:39], v[38:39], 0, v[36:37]
	v_lshl_add_u64 v[38:39], v[38:39], 0, v[190:191]
	global_store_dwordx4 v[38:39], v[46:49], off
	v_add_f32_e32 v38, 1.0, v40
	v_add_f32_e32 v39, 1.0, v41
	v_rcp_f32_e32 v38, v38
	v_rcp_f32_e32 v39, v39
	v_mov_b32_e32 v40, v30
	v_mov_b32_e32 v41, v32
	v_mul_f32_e32 v30, 0xbfb8aa3b, v26
	v_pk_mul_f32 v[38:39], v[40:41], v[38:39]
	v_exp_f32_e32 v40, v30
	v_mul_f32_e32 v30, 0xbfb8aa3b, v28
	v_exp_f32_e32 v41, v30
	v_mov_b32_e32 v32, v31
	v_pk_mul_f32 v[30:31], v[32:33], v[38:39]
	v_add_f32_e32 v32, 1.0, v40
	v_add_f32_e32 v33, 1.0, v41
	v_rcp_f32_e32 v32, v32
	v_rcp_f32_e32 v33, v33
	v_mov_b32_e32 v38, v26
	v_mul_f32_e32 v26, 0xbfb8aa3b, v22
	v_cvt_pk_bf16_f32 v30, v30, v31
	v_mov_b32_e32 v39, v28
	v_exp_f32_e32 v31, v26
	v_mul_f32_e32 v26, 0xbfb8aa3b, v24
	v_pk_mul_f32 v[32:33], v[38:39], v[32:33]
	v_exp_f32_e32 v38, v26
	v_mov_b32_e32 v28, v27
	v_pk_mul_f32 v[26:27], v[28:29], v[32:33]
	v_add_f32_e32 v28, 1.0, v31
	v_add_f32_e32 v29, 1.0, v38
	v_rcp_f32_e32 v28, v28
	v_rcp_f32_e32 v29, v29
	v_cvt_pk_bf16_f32 v31, v26, v27
	v_mov_b32_e32 v26, v22
	v_mov_b32_e32 v27, v24
	v_mul_f32_e32 v22, 0xbfb8aa3b, v18
	v_pk_mul_f32 v[26:27], v[26:27], v[28:29]
	v_exp_f32_e32 v28, v22
	v_mul_f32_e32 v22, 0xbfb8aa3b, v20
	v_exp_f32_e32 v29, v22
	v_mov_b32_e32 v24, v23
	v_pk_mul_f32 v[22:23], v[24:25], v[26:27]
	v_add_f32_e32 v24, 1.0, v28
	v_add_f32_e32 v25, 1.0, v29
	v_rcp_f32_e32 v24, v24
	v_rcp_f32_e32 v25, v25
	v_cvt_pk_bf16_f32 v32, v22, v23
	v_mov_b32_e32 v22, v18
	v_mov_b32_e32 v23, v20
	v_pk_mul_f32 v[22:23], v[22:23], v[24:25]
	v_mov_b32_e32 v20, v19
	v_pk_mul_f32 v[18:19], v[20:21], v[22:23]
	v_mul_f32_e32 v20, 0xbfb8aa3b, v14
	v_mul_f32_e32 v21, 0xbfb8aa3b, v16
	v_or_b32_e32 v42, 32, v68
	v_exp_f32_e32 v20, v20
	v_exp_f32_e32 v21, v21
	v_cvt_pk_bf16_f32 v33, v18, v19
	v_mad_i64_i32 v[18:19], s[14:15], v42, s17, v[34:35]
	v_lshl_add_u64 v[18:19], v[18:19], 0, v[36:37]
	v_lshl_add_u64 v[18:19], v[18:19], 0, v[190:191]
	global_store_dwordx4 v[18:19], v[30:33], off
	v_add_f32_e32 v18, 1.0, v20
	v_add_f32_e32 v19, 1.0, v21
	v_rcp_f32_e32 v18, v18
	v_rcp_f32_e32 v19, v19
	v_mov_b32_e32 v20, v14
	v_mov_b32_e32 v21, v16
	v_mul_f32_e32 v14, 0xbfb8aa3b, v10
	v_pk_mul_f32 v[18:19], v[20:21], v[18:19]
	v_exp_f32_e32 v20, v14
	v_mul_f32_e32 v14, 0xbfb8aa3b, v12
	v_exp_f32_e32 v21, v14
	v_mov_b32_e32 v16, v15
	v_pk_mul_f32 v[14:15], v[16:17], v[18:19]
	v_add_f32_e32 v16, 1.0, v20
	v_add_f32_e32 v17, 1.0, v21
	v_rcp_f32_e32 v16, v16
	v_rcp_f32_e32 v17, v17
	v_mov_b32_e32 v18, v10
	v_mul_f32_e32 v10, 0xbfb8aa3b, v6
	v_cvt_pk_bf16_f32 v14, v14, v15
	v_mov_b32_e32 v19, v12
	v_exp_f32_e32 v15, v10
	v_mul_f32_e32 v10, 0xbfb8aa3b, v8
	v_pk_mul_f32 v[16:17], v[18:19], v[16:17]
	v_exp_f32_e32 v18, v10
	v_mov_b32_e32 v12, v11
	v_pk_mul_f32 v[10:11], v[12:13], v[16:17]
	v_add_f32_e32 v12, 1.0, v15
	v_add_f32_e32 v13, 1.0, v18
	v_rcp_f32_e32 v12, v12
	v_rcp_f32_e32 v13, v13
	v_cvt_pk_bf16_f32 v15, v10, v11
	v_mov_b32_e32 v10, v6
	v_mov_b32_e32 v11, v8
	v_mul_f32_e32 v6, 0xbfb8aa3b, v2
	v_pk_mul_f32 v[10:11], v[10:11], v[12:13]
	v_exp_f32_e32 v12, v6
	v_mul_f32_e32 v6, 0xbfb8aa3b, v4
	v_exp_f32_e32 v13, v6
	v_mov_b32_e32 v8, v7
	v_pk_mul_f32 v[6:7], v[8:9], v[10:11]
	v_add_f32_e32 v8, 1.0, v12
	v_add_f32_e32 v9, 1.0, v13
	v_rcp_f32_e32 v8, v8
	v_rcp_f32_e32 v9, v9
	v_cvt_pk_bf16_f32 v16, v6, v7
	v_mov_b32_e32 v6, v2
	v_mov_b32_e32 v7, v4
	v_pk_mul_f32 v[6:7], v[6:7], v[8:9]
	v_mov_b32_e32 v4, v3
	v_or_b32_e32 v22, 48, v68
	v_pk_mul_f32 v[2:3], v[4:5], v[6:7]
	s_add_i32 s21, s21, s20
	v_cvt_pk_bf16_f32 v17, v2, v3
	v_mad_i64_i32 v[2:3], s[14:15], v22, s17, v[34:35]
	v_lshl_add_u64 v[2:3], v[2:3], 0, v[36:37]
	v_lshl_add_u64 v[2:3], v[2:3], 0, v[190:191]
	s_cmp_ge_i32 s21, s16
	v_readlane_b32 s53, v253, 41
	v_readlane_b32 s56, v253, 44
	v_readlane_b32 s57, v253, 45
	v_readlane_b32 s58, v253, 46
	v_readlane_b32 s59, v253, 47
	v_readlane_b32 s60, v253, 48
	v_readlane_b32 s61, v253, 49
	v_readlane_b32 s62, v253, 50
	v_readlane_b32 s63, v253, 51
	v_readlane_b32 s64, v253, 52
	v_readlane_b32 s65, v253, 53
	v_readlane_b32 s66, v253, 54
	v_readlane_b32 s67, v253, 55
	global_store_dwordx4 v[2:3], v[14:17], off
	s_cbranch_scc0 .LBB0_79

; #define MFMA16(a, b, c) __builtin_amdgcn_mfma_f32_16x16x32_bf16((a), (b), (c), 0, 0, 0)
;     ...
;   for (int kt = 0; kt < nk; ++kt) {
;     const int buf = kt & 1;
;     const char* cA = smem + buf * STAGE + (wm * 32 * MI + r16) * 128;
;     const char* cB = smem + buf * STAGE + 32768 + (wn * 64 + r16) * 128;
; #pragma unroll
;     for (int k2 = 0; k2 < 2; ++k2) {
;       if (k2 == 1 && kt + 1 < nk) STAGE_TILE(buf ^ 1, (kt + 1) * 64)
;       const int po = ((4 * k2 + q4) ^ swz) * 16;
;       bf16x8 bf[4];
; #pragma unroll
;       for (int nt = 0; nt < 4; ++nt) bf[nt] = *(const bf16x8*)(cB + nt * 16 * 128 + po);
;       bf16x8 afc = *(const bf16x8*)(cA + po);
; #pragma unroll
;       for (int a = 0; a < MT; ++a) {
;         bf16x8 afn = afc;
;         if (a + 1 < MT) afn = *(const bf16x8*)(cA + (a + 1) * 16 * 128 + po);
;         __builtin_amdgcn_sched_barrier(0);
; #pragma unroll
;         for (int nt = 0; nt < 4; ++nt) acc[a][nt] = MFMA16(bf[nt], afc, acc[a][nt]);
;         __builtin_amdgcn_sched_barrier(0);
;         afc = afn;
;       }
;     }
;     asm volatile("s_waitcnt vmcnt(0)" ::: "memory");
;     __syncthreads();
;   }
.LBB0_99:
	s_add_i32 s22, 0, 0x10000
	v_add_u32_e32 v138, s22, v148
	v_readlane_b32 s22, v254, 18
	s_nop 1
	v_add_u32_e32 v139, s22, v147
	v_add_u32_e32 v145, v139, v146
	ds_read_b128 v[130:133], v145
	ds_read_b128 v[134:137], v145 offset:2048
	ds_read_b128 v[148:151], v145 offset:4096
	ds_read_b128 v[152:155], v145 offset:6144
	v_add_u32_e32 v145, v138, v146
	ds_read_b128 v[156:159], v145
	ds_read_b128 v[160:163], v145 offset:2048
	s_waitcnt lgkmcnt(1)
	v_mfma_f32_16x16x32_bf16 v[126:129], v[130:133], v[156:159], v[126:129]
	v_mfma_f32_16x16x32_bf16 v[122:125], v[134:137], v[156:159], v[122:125]
	v_mfma_f32_16x16x32_bf16 v[118:121], v[148:151], v[156:159], v[118:121]
	v_mfma_f32_16x16x32_bf16 v[114:117], v[152:155], v[156:159], v[114:117]
	ds_read_b128 v[156:159], v145 offset:4096
	s_waitcnt lgkmcnt(1)
	v_mfma_f32_16x16x32_bf16 v[110:113], v[130:133], v[160:163], v[110:113]
	v_mfma_f32_16x16x32_bf16 v[106:109], v[134:137], v[160:163], v[106:109]
	v_mfma_f32_16x16x32_bf16 v[102:105], v[148:151], v[160:163], v[102:105]
	v_mfma_f32_16x16x32_bf16 v[98:101], v[152:155], v[160:163], v[98:101]
	ds_read_b128 v[160:163], v145 offset:6144
	s_waitcnt lgkmcnt(1)
	v_mfma_f32_16x16x32_bf16 v[94:97], v[130:133], v[156:159], v[94:97]
	v_mfma_f32_16x16x32_bf16 v[90:93], v[134:137], v[156:159], v[90:93]
	v_mfma_f32_16x16x32_bf16 v[86:89], v[148:151], v[156:159], v[86:89]
	v_mfma_f32_16x16x32_bf16 v[82:85], v[152:155], v[156:159], v[82:85]
	ds_read_b128 v[156:159], v145 offset:8192
	s_waitcnt lgkmcnt(1)
	v_mfma_f32_16x16x32_bf16 v[78:81], v[130:133], v[160:163], v[78:81]
	v_mfma_f32_16x16x32_bf16 v[74:77], v[134:137], v[160:163], v[74:77]
	v_mfma_f32_16x16x32_bf16 v[70:73], v[148:151], v[160:163], v[70:73]
	v_mfma_f32_16x16x32_bf16 v[66:69], v[152:155], v[160:163], v[66:69]
	ds_read_b128 v[160:163], v145 offset:10240
	s_waitcnt lgkmcnt(1)
	v_mfma_f32_16x16x32_bf16 v[62:65], v[130:133], v[156:159], v[62:65]
	v_mfma_f32_16x16x32_bf16 v[58:61], v[134:137], v[156:159], v[58:61]
	v_mfma_f32_16x16x32_bf16 v[54:57], v[148:151], v[156:159], v[54:57]
	v_mfma_f32_16x16x32_bf16 v[50:53], v[152:155], v[156:159], v[50:53]
	ds_read_b128 v[156:159], v145 offset:12288
	s_waitcnt lgkmcnt(1)
	v_mfma_f32_16x16x32_bf16 v[46:49], v[130:133], v[160:163], v[46:49]
	v_mfma_f32_16x16x32_bf16 v[42:45], v[134:137], v[160:163], v[42:45]
	v_mfma_f32_16x16x32_bf16 v[38:41], v[148:151], v[160:163], v[38:41]
	v_mfma_f32_16x16x32_bf16 v[34:37], v[152:155], v[160:163], v[34:37]
	ds_read_b128 v[160:163], v145 offset:14336
	s_waitcnt lgkmcnt(1)
	v_mfma_f32_16x16x32_bf16 v[30:33], v[130:133], v[156:159], v[30:33]
	v_mfma_f32_16x16x32_bf16 v[26:29], v[134:137], v[156:159], v[26:29]
	v_mfma_f32_16x16x32_bf16 v[22:25], v[148:151], v[156:159], v[22:25]
	v_mfma_f32_16x16x32_bf16 v[18:21], v[152:155], v[156:159], v[18:21]
	s_waitcnt lgkmcnt(0)
	v_mfma_f32_16x16x32_bf16 v[14:17], v[130:133], v[160:163], v[14:17]
	v_mfma_f32_16x16x32_bf16 v[10:13], v[134:137], v[160:163], v[10:13]
	v_mfma_f32_16x16x32_bf16 v[6:9], v[148:151], v[160:163], v[6:9]
	v_mfma_f32_16x16x32_bf16 v[2:5], v[152:155], v[160:163], v[2:5]
	v_add_u32_e32 v139, v139, v144
	ds_read_b128 v[130:133], v139
	ds_read_b128 v[134:137], v139 offset:2048
	ds_read_b128 v[146:149], v139 offset:4096
	ds_read_b128 v[150:153], v139 offset:6144
	v_add_u32_e32 v138, v138, v144
	ds_read_b128 v[154:157], v138
	ds_read_b128 v[158:161], v138 offset:2048
	s_waitcnt lgkmcnt(1)
	v_mfma_f32_16x16x32_bf16 v[126:129], v[130:133], v[154:157], v[126:129]
	v_mfma_f32_16x16x32_bf16 v[122:125], v[134:137], v[154:157], v[122:125]
	v_mfma_f32_16x16x32_bf16 v[118:121], v[146:149], v[154:157], v[118:121]
	v_mfma_f32_16x16x32_bf16 v[114:117], v[150:153], v[154:157], v[114:117]
	ds_read_b128 v[154:157], v138 offset:4096
	s_waitcnt lgkmcnt(1)
	v_mfma_f32_16x16x32_bf16 v[110:113], v[130:133], v[158:161], v[110:113]
	v_mfma_f32_16x16x32_bf16 v[106:109], v[134:137], v[158:161], v[106:109]
	v_mfma_f32_16x16x32_bf16 v[102:105], v[146:149], v[158:161], v[102:105]
	v_mfma_f32_16x16x32_bf16 v[98:101], v[150:153], v[158:161], v[98:101]
	ds_read_b128 v[158:161], v138 offset:6144
	s_waitcnt lgkmcnt(1)
	v_mfma_f32_16x16x32_bf16 v[94:97], v[130:133], v[154:157], v[94:97]
	v_mfma_f32_16x16x32_bf16 v[90:93], v[134:137], v[154:157], v[90:93]
	v_mfma_f32_16x16x32_bf16 v[86:89], v[146:149], v[154:157], v[86:89]
	v_mfma_f32_16x16x32_bf16 v[82:85], v[150:153], v[154:157], v[82:85]
	ds_read_b128 v[154:157], v138 offset:8192
	s_waitcnt lgkmcnt(1)
	v_mfma_f32_16x16x32_bf16 v[78:81], v[130:133], v[158:161], v[78:81]
	v_mfma_f32_16x16x32_bf16 v[74:77], v[134:137], v[158:161], v[74:77]
	v_mfma_f32_16x16x32_bf16 v[70:73], v[146:149], v[158:161], v[70:73]
	v_mfma_f32_16x16x32_bf16 v[66:69], v[150:153], v[158:161], v[66:69]
	ds_read_b128 v[158:161], v138 offset:10240
	s_waitcnt lgkmcnt(1)
	v_mfma_f32_16x16x32_bf16 v[62:65], v[130:133], v[154:157], v[62:65]
	v_mfma_f32_16x16x32_bf16 v[58:61], v[134:137], v[154:157], v[58:61]
	v_mfma_f32_16x16x32_bf16 v[54:57], v[146:149], v[154:157], v[54:57]
	v_mfma_f32_16x16x32_bf16 v[50:53], v[150:153], v[154:157], v[50:53]
	ds_read_b128 v[154:157], v138 offset:12288
	s_waitcnt lgkmcnt(1)
	v_mfma_f32_16x16x32_bf16 v[46:49], v[130:133], v[158:161], v[46:49]
	v_mfma_f32_16x16x32_bf16 v[42:45], v[134:137], v[158:161], v[42:45]
	v_mfma_f32_16x16x32_bf16 v[38:41], v[146:149], v[158:161], v[38:41]
	v_mfma_f32_16x16x32_bf16 v[34:37], v[150:153], v[158:161], v[34:37]
	ds_read_b128 v[158:161], v138 offset:14336
	s_waitcnt lgkmcnt(1)
;     ...
; #pragma unroll
;     for (int a = 0; a < MT; ++a)
; #pragma unroll
;       for (int nt = 0; nt < 4; ++nt)
;         ep(row0 + 16 * a, cbw + 16 * nt + 4 * q4, acc[a][nt][0], acc[a][nt][1], acc[a][nt][2], acc[a][nt][3]);
; DI void phase_resid(char* smem, const Params& p, int layer, const bf16_t* A, int K, const bf16_t* W, int gate_idx, bool first) {
;     ...
;   auto ep = [&](int row, int col, float v0, float v1, float v2, float v3) {
;     const int b = row / TT, t = row - b * TT;
;     const float4 g = *(const float4*)(p.mod + (size_t)(layer * 5 + (t < CTXL ? 4 : b)) * 6144 + gate_idx * 1024 + col);
;     const float4 xo = *(const float4*)(xsrc_row(p, first, row) + col);
;     *(float4*)(xdst_row(p, row) + col) = make_float4(xo.x + g.x * v0, xo.y + g.y * v1, xo.z + g.z * v2, xo.w + g.w * v3);
;   };
	v_mfma_f32_16x16x32_bf16 v[30:33], v[130:133], v[154:157], v[30:33]
	v_mfma_f32_16x16x32_bf16 v[26:29], v[134:137], v[154:157], v[26:29]
	v_mfma_f32_16x16x32_bf16 v[22:25], v[146:149], v[154:157], v[22:25]
	v_mfma_f32_16x16x32_bf16 v[18:21], v[150:153], v[154:157], v[18:21]
	s_waitcnt lgkmcnt(0)
	v_mfma_f32_16x16x32_bf16 v[14:17], v[130:133], v[158:161], v[14:17]
	v_mfma_f32_16x16x32_bf16 v[10:13], v[134:137], v[158:161], v[10:13]
	v_mfma_f32_16x16x32_bf16 v[6:9], v[146:149], v[158:161], v[6:9]
	v_mfma_f32_16x16x32_bf16 v[2:5], v[150:153], v[158:161], v[2:5]
	v_or_b32_e32 v131, s44, v142
	v_lshlrev_b32_e32 v130, 6, v143
	v_lshl_add_u32 v142, v140, 7, v131
	v_lshlrev_b32_e32 v131, 2, v141
	v_or3_b32 v134, v130, v131, s43
	v_mul_hi_i32 v130, v142, s1
	v_lshrrev_b32_e32 v131, 31, v130
	v_ashrrev_i32_e32 v130, 11, v130
	v_add_u32_e32 v130, v130, v131
	v_mad_i32_i24 v131, v130, s90, v142
	s_movk_i32 s43, 0x100
	v_cmp_gt_i32_e32 vcc, s43, v131
	v_add_u32_e32 v132, 0xffffff00, v131
	v_ashrrev_i32_e32 v133, 31, v131
	v_readlane_b32 s44, v254, 1
	v_cndmask_b32_e64 v135, v130, 4, vcc
	v_cndmask_b32_e32 v133, 0, v133, vcc
	v_cndmask_b32_e32 v132, v132, v131, vcc
	v_ashrrev_i32_e32 v131, 31, v130
	v_cndmask_b32_e64 v136, 25, 20, vcc
	v_readlane_b32 s45, v254, 2
	v_readlane_b32 s46, v254, 3
	v_lshlrev_b64 v[140:141], v136, v[130:131]
	v_lshlrev_b64 v[148:149], 12, v[132:133]
	v_add_u32_e32 v130, s39, v135
	v_readlane_b32 s48, v254, 5
	v_readlane_b32 s49, v254, 6
	v_mov_b64_e32 v[132:133], s[44:45]
	s_movk_i32 s46, 0x6000
	v_mad_i64_i32 v[130:131], s[22:23], v130, s46, v[132:133]
	s_mov_b64 s[48:49], 0x2000
	v_ashrrev_i32_e32 v135, 31, v134
	v_lshl_add_u64 v[136:137], v[130:131], 0, s[48:49]
	v_lshlrev_b64 v[130:131], 2, v[134:135]
	v_mov_b32_e32 v135, s40
	v_mov_b32_e32 v143, s41
	v_readlane_b32 s44, v252, 1
	v_cndmask_b32_e32 v190, v135, v143, vcc
	v_readlane_b32 s45, v252, 2
	s_waitcnt vmcnt(0)
	s_barrier
	s_nop 0
	v_lshl_add_u64 v[138:139], s[44:45], 0, v[190:191]
	global_load_dwordx2 v[138:139], v[138:139], off
	v_readlane_b32 s68, v252, 5
	v_readlane_b32 s80, v252, 17
	v_readlane_b32 s81, v252, 18
	v_readlane_b32 s82, v252, 19
	v_readlane_b32 s83, v252, 20
	v_mov_b32_e32 v144, s81
	v_mov_b32_e32 v146, s80
	v_mov_b32_e32 v145, s83
	v_mov_b32_e32 v147, s82
	v_cndmask_b32_e32 v153, v144, v145, vcc
	v_cndmask_b32_e32 v152, v146, v147, vcc
	v_lshl_add_u64 v[150:151], v[136:137], 0, v[130:131]
	s_add_i32 s42, s42, s34
	s_cmp_gt_i32 s42, 31
	v_readlane_b32 s47, v254, 4
	v_readlane_b32 s50, v254, 7
	v_readlane_b32 s51, v254, 8
	v_readlane_b32 s52, v254, 9
	v_readlane_b32 s53, v254, 10
	v_readlane_b32 s54, v254, 11
	v_readlane_b32 s55, v254, 12
	v_readlane_b32 s56, v254, 13
	v_readlane_b32 s57, v254, 14
	v_readlane_b32 s58, v254, 15
	v_readlane_b32 s59, v254, 16
	v_readlane_b32 s69, v252, 6
	v_readlane_b32 s70, v252, 7
	v_readlane_b32 s71, v252, 8
	v_readlane_b32 s72, v252, 9
	v_readlane_b32 s73, v252, 10
	v_readlane_b32 s74, v252, 11
	v_readlane_b32 s75, v252, 12
	v_readlane_b32 s76, v252, 13
	v_readlane_b32 s77, v252, 14
	v_readlane_b32 s78, v252, 15
	v_readlane_b32 s79, v252, 16
	s_waitcnt vmcnt(0)
	v_lshl_add_u64 v[138:139], v[138:139], 0, v[140:141]
	v_lshl_add_u64 v[138:139], v[138:139], 0, v[148:149]
	v_lshl_add_u64 v[140:141], v[152:153], 0, v[140:141]
	v_lshl_add_u64 v[138:139], v[138:139], 0, v[130:131]
	v_lshl_add_u64 v[140:141], v[140:141], 0, v[148:149]
	v_lshl_add_u64 v[140:141], v[140:141], 0, v[130:131]
	s_cselect_b64 s[22:23], -1, 0
	global_load_dwordx4 v[156:159], v[150:151], off
	global_load_dwordx4 v[160:163], v[150:151], off offset:64
	global_load_dwordx4 v[164:167], v[150:151], off offset:128
	global_load_dwordx4 v[168:171], v[150:151], off offset:192
	global_load_dwordx4 v[172:175], v[138:139], off
	global_load_dwordx4 v[176:179], v[138:139], off offset:64
	global_load_dwordx4 v[180:183], v[138:139], off offset:128
	global_load_dwordx4 v[184:187], v[138:139], off offset:192
	v_add_co_u32_e32 v138, vcc, 0x10000, v138
	s_nop 1
	v_addc_co_u32_e32 v139, vcc, 0, v139, vcc
	global_load_dwordx4 v[198:201], v[138:139], off
	global_load_dwordx4 v[202:205], v[138:139], off offset:64
	global_load_dwordx4 v[206:209], v[138:139], off offset:128
	global_load_dwordx4 v[210:213], v[138:139], off offset:192
	v_add_co_u32_e32 v138, vcc, 0x10000, v138
	s_nop 1
	v_addc_co_u32_e32 v139, vcc, 0, v139, vcc
	global_load_dwordx4 v[214:217], v[138:139], off
	global_load_dwordx4 v[218:221], v[138:139], off offset:64
	global_load_dwordx4 v[222:225], v[138:139], off offset:128
	global_load_dwordx4 v[142:145], v[138:139], off offset:192
	v_add_co_u32_e32 v138, vcc, 0x10000, v138
	s_nop 1
	v_addc_co_u32_e32 v139, vcc, 0, v139, vcc
	s_waitcnt vmcnt(8)
	v_pk_fma_f32 v[126:127], v[126:127], v[156:157], v[172:173]
	v_pk_fma_f32 v[128:129], v[128:129], v[158:159], v[174:175]
	v_pk_fma_f32 v[122:123], v[122:123], v[160:161], v[176:177]
	v_pk_fma_f32 v[124:125], v[124:125], v[162:163], v[178:179]
	v_pk_fma_f32 v[118:119], v[118:119], v[164:165], v[180:181]
	v_pk_fma_f32 v[120:121], v[120:121], v[166:167], v[182:183]
	v_pk_fma_f32 v[114:115], v[114:115], v[168:169], v[184:185]
	v_pk_fma_f32 v[116:117], v[116:117], v[170:171], v[186:187]
	global_store_dwordx4 v[140:141], v[126:129], off
	global_store_dwordx4 v[140:141], v[122:125], off offset:64
	global_store_dwordx4 v[140:141], v[118:121], off offset:128
	global_store_dwordx4 v[140:141], v[114:117], off offset:192
	v_add_co_u32_e32 v140, vcc, 0x10000, v140
	s_nop 1
	v_addc_co_u32_e32 v141, vcc, 0, v141, vcc
	global_load_dwordx4 v[172:175], v[138:139], off
	global_load_dwordx4 v[176:179], v[138:139], off offset:64
	global_load_dwordx4 v[180:183], v[138:139], off offset:128
	global_load_dwordx4 v[184:187], v[138:139], off offset:192
	v_add_co_u32_e32 v138, vcc, 0x10000, v138
	s_nop 1
	v_addc_co_u32_e32 v139, vcc, 0, v139, vcc
	s_waitcnt vmcnt(12)
;     ...
; #pragma unroll
;     for (int a = 0; a < MT; ++a)
; #pragma unroll
;       for (int nt = 0; nt < 4; ++nt)
;         ep(row0 + 16 * a, cbw + 16 * nt + 4 * q4, acc[a][nt][0], acc[a][nt][1], acc[a][nt][2], acc[a][nt][3]);
; DI void phase_resid(char* smem, const Params& p, int layer, const bf16_t* A, int K, const bf16_t* W, int gate_idx, bool first) {
;     ...
;   auto ep = [&](int row, int col, float v0, float v1, float v2, float v3) {
;     const int b = row / TT, t = row - b * TT;
;     const float4 g = *(const float4*)(p.mod + (size_t)(layer * 5 + (t < CTXL ? 4 : b)) * 6144 + gate_idx * 1024 + col);
;     const float4 xo = *(const float4*)(xsrc_row(p, first, row) + col);
;     *(float4*)(xdst_row(p, row) + col) = make_float4(xo.x + g.x * v0, xo.y + g.y * v1, xo.z + g.z * v2, xo.w + g.w * v3);
;   };
	v_pk_fma_f32 v[110:111], v[110:111], v[156:157], v[198:199]
	v_pk_fma_f32 v[112:113], v[112:113], v[158:159], v[200:201]
	v_pk_fma_f32 v[106:107], v[106:107], v[160:161], v[202:203]
	v_pk_fma_f32 v[108:109], v[108:109], v[162:163], v[204:205]
	v_pk_fma_f32 v[102:103], v[102:103], v[164:165], v[206:207]
	v_pk_fma_f32 v[104:105], v[104:105], v[166:167], v[208:209]
	v_pk_fma_f32 v[98:99], v[98:99], v[168:169], v[210:211]
	v_pk_fma_f32 v[100:101], v[100:101], v[170:171], v[212:213]
	global_store_dwordx4 v[140:141], v[110:113], off
	global_store_dwordx4 v[140:141], v[106:109], off offset:64
	global_store_dwordx4 v[140:141], v[102:105], off offset:128
	global_store_dwordx4 v[140:141], v[98:101], off offset:192
	v_add_co_u32_e32 v140, vcc, 0x10000, v140
	s_nop 1
	v_addc_co_u32_e32 v141, vcc, 0, v141, vcc
	global_load_dwordx4 v[198:201], v[138:139], off
	global_load_dwordx4 v[202:205], v[138:139], off offset:64
	global_load_dwordx4 v[206:209], v[138:139], off offset:128
	global_load_dwordx4 v[210:213], v[138:139], off offset:192
	v_add_co_u32_e32 v138, vcc, 0x10000, v138
	s_nop 1
	v_addc_co_u32_e32 v139, vcc, 0, v139, vcc
	s_waitcnt vmcnt(16)
	v_pk_fma_f32 v[94:95], v[94:95], v[156:157], v[214:215]
	v_pk_fma_f32 v[96:97], v[96:97], v[158:159], v[216:217]
	v_pk_fma_f32 v[90:91], v[90:91], v[160:161], v[218:219]
	v_pk_fma_f32 v[92:93], v[92:93], v[162:163], v[220:221]
	v_pk_fma_f32 v[86:87], v[86:87], v[164:165], v[222:223]
	v_pk_fma_f32 v[88:89], v[88:89], v[166:167], v[224:225]
	v_pk_fma_f32 v[82:83], v[82:83], v[168:169], v[142:143]
	v_pk_fma_f32 v[84:85], v[84:85], v[170:171], v[144:145]
	global_store_dwordx4 v[140:141], v[94:97], off
	global_store_dwordx4 v[140:141], v[90:93], off offset:64
	global_store_dwordx4 v[140:141], v[86:89], off offset:128
	global_store_dwordx4 v[140:141], v[82:85], off offset:192
	v_add_co_u32_e32 v140, vcc, 0x10000, v140
	s_nop 1
	v_addc_co_u32_e32 v141, vcc, 0, v141, vcc
	global_load_dwordx4 v[214:217], v[138:139], off
	global_load_dwordx4 v[218:221], v[138:139], off offset:64
	global_load_dwordx4 v[222:225], v[138:139], off offset:128
	global_load_dwordx4 v[142:145], v[138:139], off offset:192
	v_add_co_u32_e32 v138, vcc, 0x10000, v138
	s_nop 1
	v_addc_co_u32_e32 v139, vcc, 0, v139, vcc
	s_waitcnt vmcnt(16)
	v_pk_fma_f32 v[78:79], v[78:79], v[156:157], v[172:173]
	v_pk_fma_f32 v[80:81], v[80:81], v[158:159], v[174:175]
	v_pk_fma_f32 v[74:75], v[74:75], v[160:161], v[176:177]
	v_pk_fma_f32 v[76:77], v[76:77], v[162:163], v[178:179]
	v_pk_fma_f32 v[70:71], v[70:71], v[164:165], v[180:181]
	v_pk_fma_f32 v[72:73], v[72:73], v[166:167], v[182:183]
	v_pk_fma_f32 v[66:67], v[66:67], v[168:169], v[184:185]
	v_pk_fma_f32 v[68:69], v[68:69], v[170:171], v[186:187]
	global_store_dwordx4 v[140:141], v[78:81], off
	global_store_dwordx4 v[140:141], v[74:77], off offset:64
	global_store_dwordx4 v[140:141], v[70:73], off offset:128
	global_store_dwordx4 v[140:141], v[66:69], off offset:192
	v_add_co_u32_e32 v140, vcc, 0x10000, v140
	s_nop 1
	v_addc_co_u32_e32 v141, vcc, 0, v141, vcc
	global_load_dwordx4 v[172:175], v[138:139], off
	global_load_dwordx4 v[176:179], v[138:139], off offset:64
	global_load_dwordx4 v[180:183], v[138:139], off offset:128
	global_load_dwordx4 v[184:187], v[138:139], off offset:192
	v_add_co_u32_e32 v138, vcc, 0x10000, v138
	s_nop 1
	v_addc_co_u32_e32 v139, vcc, 0, v139, vcc
	s_waitcnt vmcnt(16)
	v_pk_fma_f32 v[62:63], v[62:63], v[156:157], v[198:199]
	v_pk_fma_f32 v[64:65], v[64:65], v[158:159], v[200:201]
	v_pk_fma_f32 v[58:59], v[58:59], v[160:161], v[202:203]
	v_pk_fma_f32 v[60:61], v[60:61], v[162:163], v[204:205]
	v_pk_fma_f32 v[54:55], v[54:55], v[164:165], v[206:207]
	v_pk_fma_f32 v[56:57], v[56:57], v[166:167], v[208:209]
	v_pk_fma_f32 v[50:51], v[50:51], v[168:169], v[210:211]
	v_pk_fma_f32 v[52:53], v[52:53], v[170:171], v[212:213]
	global_store_dwordx4 v[140:141], v[62:65], off
	global_store_dwordx4 v[140:141], v[58:61], off offset:64
	global_store_dwordx4 v[140:141], v[54:57], off offset:128
	global_store_dwordx4 v[140:141], v[50:53], off offset:192
	v_add_co_u32_e32 v140, vcc, 0x10000, v140
	s_nop 1
	v_addc_co_u32_e32 v141, vcc, 0, v141, vcc
	global_load_dwordx4 v[198:201], v[138:139], off
	global_load_dwordx4 v[202:205], v[138:139], off offset:64
	global_load_dwordx4 v[206:209], v[138:139], off offset:128
	global_load_dwordx4 v[210:213], v[138:139], off offset:192
	s_waitcnt vmcnt(16)
	v_pk_fma_f32 v[46:47], v[46:47], v[156:157], v[214:215]
	v_pk_fma_f32 v[48:49], v[48:49], v[158:159], v[216:217]
	v_pk_fma_f32 v[42:43], v[42:43], v[160:161], v[218:219]
	v_pk_fma_f32 v[44:45], v[44:45], v[162:163], v[220:221]
	v_pk_fma_f32 v[38:39], v[38:39], v[164:165], v[222:223]
	v_pk_fma_f32 v[40:41], v[40:41], v[166:167], v[224:225]
	v_pk_fma_f32 v[34:35], v[34:35], v[168:169], v[142:143]
	v_pk_fma_f32 v[36:37], v[36:37], v[170:171], v[144:145]
	global_store_dwordx4 v[140:141], v[46:49], off
	global_store_dwordx4 v[140:141], v[42:45], off offset:64
	global_store_dwordx4 v[140:141], v[38:41], off offset:128
	global_store_dwordx4 v[140:141], v[34:37], off offset:192
	v_add_co_u32_e32 v140, vcc, 0x10000, v140
	s_nop 1
	v_addc_co_u32_e32 v141, vcc, 0, v141, vcc
	s_waitcnt vmcnt(12)
	v_pk_fma_f32 v[30:31], v[30:31], v[156:157], v[172:173]
	v_pk_fma_f32 v[32:33], v[32:33], v[158:159], v[174:175]
	v_pk_fma_f32 v[26:27], v[26:27], v[160:161], v[176:177]
	v_pk_fma_f32 v[28:29], v[28:29], v[162:163], v[178:179]
	v_pk_fma_f32 v[22:23], v[22:23], v[164:165], v[180:181]
	v_pk_fma_f32 v[24:25], v[24:25], v[166:167], v[182:183]
	v_pk_fma_f32 v[18:19], v[18:19], v[168:169], v[184:185]
	v_pk_fma_f32 v[20:21], v[20:21], v[170:171], v[186:187]
	global_store_dwordx4 v[140:141], v[30:33], off
	global_store_dwordx4 v[140:141], v[26:29], off offset:64
	global_store_dwordx4 v[140:141], v[22:25], off offset:128
	global_store_dwordx4 v[140:141], v[18:21], off offset:192
	v_add_co_u32_e32 v140, vcc, 0x10000, v140
	s_nop 1
	v_addc_co_u32_e32 v141, vcc, 0, v141, vcc
	s_waitcnt vmcnt(8)
	v_pk_fma_f32 v[14:15], v[14:15], v[156:157], v[198:199]
	v_pk_fma_f32 v[16:17], v[16:17], v[158:159], v[200:201]
	v_pk_fma_f32 v[10:11], v[10:11], v[160:161], v[202:203]
	v_pk_fma_f32 v[12:13], v[12:13], v[162:163], v[204:205]
	v_pk_fma_f32 v[6:7], v[6:7], v[164:165], v[206:207]
	v_pk_fma_f32 v[8:9], v[8:9], v[166:167], v[208:209]
	v_pk_fma_f32 v[2:3], v[2:3], v[168:169], v[210:211]
	v_pk_fma_f32 v[4:5], v[4:5], v[170:171], v[212:213]
	global_store_dwordx4 v[140:141], v[14:17], off
	global_store_dwordx4 v[140:141], v[10:13], off offset:64
	global_store_dwordx4 v[140:141], v[6:9], off offset:128
	global_store_dwordx4 v[140:141], v[2:5], off offset:192

; #define MFMA16(a, b, c) __builtin_amdgcn_mfma_f32_16x16x32_bf16((a), (b), (c), 0, 0, 0)
;     ...
;   for (int kt = 0; kt < nk; ++kt) {
;     const int buf = kt & 1;
;     const char* cA = smem + buf * STAGE + (wm * 32 * MI + r16) * 128;
;     const char* cB = smem + buf * STAGE + 32768 + (wn * 64 + r16) * 128;
; #pragma unroll
;     for (int k2 = 0; k2 < 2; ++k2) {
;       if (k2 == 1 && kt + 1 < nk) STAGE_TILE(buf ^ 1, (kt + 1) * 64)
;       const int po = ((4 * k2 + q4) ^ swz) * 16;
;       bf16x8 bf[4];
; #pragma unroll
;       for (int nt = 0; nt < 4; ++nt) bf[nt] = *(const bf16x8*)(cB + nt * 16 * 128 + po);
;       bf16x8 afc = *(const bf16x8*)(cA + po);
; #pragma unroll
;       for (int a = 0; a < MT; ++a) {
;         bf16x8 afn = afc;
;         if (a + 1 < MT) afn = *(const bf16x8*)(cA + (a + 1) * 16 * 128 + po);
;         __builtin_amdgcn_sched_barrier(0);
; #pragma unroll
;         for (int nt = 0; nt < 4; ++nt) acc[a][nt] = MFMA16(bf[nt], afc, acc[a][nt]);
;         __builtin_amdgcn_sched_barrier(0);
;         afc = afn;
;       }
.LBB0_107:
	s_and_b32 s46, s45, 0x10000
	s_add_i32 s47, s46, 0
	v_add_u32_e32 v174, s47, v147
	v_add_u32_e32 v162, v174, v146
	v_add_u32_e32 v149, s47, v148
	ds_read_b128 v[150:153], v162 offset:32768
	ds_read_b128 v[154:157], v162 offset:34816
	ds_read_b128 v[158:161], v162 offset:36864
	ds_read_b128 v[162:165], v162 offset:38912
	v_add_u32_e32 v175, v149, v146
	ds_read_b128 v[166:169], v175
	ds_read_b128 v[170:173], v175 offset:2048
	s_waitcnt lgkmcnt(1)
	v_mfma_f32_16x16x32_bf16 v[126:129], v[150:153], v[166:169], v[126:129]
	v_mfma_f32_16x16x32_bf16 v[122:125], v[154:157], v[166:169], v[122:125]
	v_mfma_f32_16x16x32_bf16 v[118:121], v[158:161], v[166:169], v[118:121]
	v_mfma_f32_16x16x32_bf16 v[114:117], v[162:165], v[166:169], v[114:117]
	ds_read_b128 v[166:169], v175 offset:4096
	s_waitcnt lgkmcnt(1)
	v_mfma_f32_16x16x32_bf16 v[110:113], v[150:153], v[170:173], v[110:113]
	v_mfma_f32_16x16x32_bf16 v[106:109], v[154:157], v[170:173], v[106:109]
	v_mfma_f32_16x16x32_bf16 v[102:105], v[158:161], v[170:173], v[102:105]
	v_mfma_f32_16x16x32_bf16 v[98:101], v[162:165], v[170:173], v[98:101]
	ds_read_b128 v[170:173], v175 offset:6144
	s_waitcnt lgkmcnt(1)
	v_mfma_f32_16x16x32_bf16 v[94:97], v[150:153], v[166:169], v[94:97]
	v_mfma_f32_16x16x32_bf16 v[90:93], v[154:157], v[166:169], v[90:93]
	v_mfma_f32_16x16x32_bf16 v[86:89], v[158:161], v[166:169], v[86:89]
	v_mfma_f32_16x16x32_bf16 v[82:85], v[162:165], v[166:169], v[82:85]
	ds_read_b128 v[166:169], v175 offset:8192
	s_waitcnt lgkmcnt(1)
	v_mfma_f32_16x16x32_bf16 v[78:81], v[150:153], v[170:173], v[78:81]
	v_mfma_f32_16x16x32_bf16 v[74:77], v[154:157], v[170:173], v[74:77]
	v_mfma_f32_16x16x32_bf16 v[70:73], v[158:161], v[170:173], v[70:73]
	v_mfma_f32_16x16x32_bf16 v[66:69], v[162:165], v[170:173], v[66:69]
	ds_read_b128 v[170:173], v175 offset:10240
	s_waitcnt lgkmcnt(1)
	v_mfma_f32_16x16x32_bf16 v[62:65], v[150:153], v[166:169], v[62:65]
	v_mfma_f32_16x16x32_bf16 v[58:61], v[154:157], v[166:169], v[58:61]
	v_mfma_f32_16x16x32_bf16 v[54:57], v[158:161], v[166:169], v[54:57]
	v_mfma_f32_16x16x32_bf16 v[50:53], v[162:165], v[166:169], v[50:53]
	ds_read_b128 v[166:169], v175 offset:12288
	s_waitcnt lgkmcnt(1)
	v_mfma_f32_16x16x32_bf16 v[46:49], v[150:153], v[170:173], v[46:49]
	v_mfma_f32_16x16x32_bf16 v[42:45], v[154:157], v[170:173], v[42:45]
	v_mfma_f32_16x16x32_bf16 v[38:41], v[158:161], v[170:173], v[38:41]
	v_mfma_f32_16x16x32_bf16 v[34:37], v[162:165], v[170:173], v[34:37]
	ds_read_b128 v[170:173], v175 offset:14336
	s_waitcnt lgkmcnt(1)
	v_mfma_f32_16x16x32_bf16 v[30:33], v[150:153], v[166:169], v[30:33]
	v_mfma_f32_16x16x32_bf16 v[26:29], v[154:157], v[166:169], v[26:29]
	v_mfma_f32_16x16x32_bf16 v[22:25], v[158:161], v[166:169], v[22:25]
	v_mfma_f32_16x16x32_bf16 v[18:21], v[162:165], v[166:169], v[18:21]
	s_waitcnt lgkmcnt(0)
; #define MFMA16(a, b, c) __builtin_amdgcn_mfma_f32_16x16x32_bf16((a), (b), (c), 0, 0, 0)
;     ...
;   for (int kt = 0; kt < nk; ++kt) {
;     const int buf = kt & 1;
;     const char* cA = smem + buf * STAGE + (wm * 32 * MI + r16) * 128;
;     const char* cB = smem + buf * STAGE + 32768 + (wn * 64 + r16) * 128;
; #pragma unroll
;     for (int k2 = 0; k2 < 2; ++k2) {
;       if (k2 == 1 && kt + 1 < nk) STAGE_TILE(buf ^ 1, (kt + 1) * 64)
;       const int po = ((4 * k2 + q4) ^ swz) * 16;
;       bf16x8 bf[4];
; #pragma unroll
;       for (int nt = 0; nt < 4; ++nt) bf[nt] = *(const bf16x8*)(cB + nt * 16 * 128 + po);
;       bf16x8 afc = *(const bf16x8*)(cA + po);
; #pragma unroll
;       for (int a = 0; a < MT; ++a) {
;         bf16x8 afn = afc;
;         if (a + 1 < MT) afn = *(const bf16x8*)(cA + (a + 1) * 16 * 128 + po);
;         __builtin_amdgcn_sched_barrier(0);
; #pragma unroll
;         for (int nt = 0; nt < 4; ++nt) acc[a][nt] = MFMA16(bf[nt], afc, acc[a][nt]);
;         __builtin_amdgcn_sched_barrier(0);
;         afc = afn;
;       }
;     }
;     asm volatile("s_waitcnt vmcnt(0)" ::: "memory");
;     __syncthreads();
;   }
	v_mfma_f32_16x16x32_bf16 v[14:17], v[150:153], v[170:173], v[14:17]
	v_mfma_f32_16x16x32_bf16 v[10:13], v[154:157], v[170:173], v[10:13]
	v_mfma_f32_16x16x32_bf16 v[6:9], v[158:161], v[170:173], v[6:9]
	v_mfma_f32_16x16x32_bf16 v[2:5], v[162:165], v[170:173], v[2:5]
	s_xor_b32 s46, s46, 0x10000
	v_add_u32_e32 v166, s46, v145
	v_lshl_add_u64 v[158:159], v[130:131], 0, s[22:23]
	v_add_u32_e32 v173, 0x2000, v166
	v_readfirstlane_b32 s46, v166
	v_lshl_add_u64 v[160:161], v[158:159], 0, s[18:19]
	v_add_u32_e32 v172, 0x4000, v166
	v_lshl_add_u64 v[162:163], v[158:159], 0, s[28:29]
	v_lshl_add_u64 v[164:165], v[158:159], 0, s[84:85]
	v_lshl_add_u64 v[158:159], v[158:159], 0, s[24:25]
	s_mov_b32 m0, s46
	v_readfirstlane_b32 s46, v173
	v_add_u32_e32 v171, 0x6000, v166
	global_load_lds_dwordx4 v[158:159], off
	s_mov_b32 m0, s46
	v_readfirstlane_b32 s46, v172
	v_add_u32_e32 v170, 0x8000, v166
	global_load_lds_dwordx4 v[164:165], off
	s_mov_b32 m0, s46
	v_readfirstlane_b32 s46, v171
	v_add_u32_e32 v169, 0xa000, v166
	global_load_lds_dwordx4 v[162:163], off
	s_mov_b32 m0, s46
	v_readfirstlane_b32 s46, v170
	v_add_u32_e32 v168, 0xc000, v166
	v_lshl_add_u64 v[156:157], v[138:139], 0, s[22:23]
	global_load_lds_dwordx4 v[160:161], off
	s_mov_b32 m0, s46
	v_readfirstlane_b32 s46, v169
	v_add_u32_e32 v167, 0xe000, v166
	v_lshl_add_u64 v[154:155], v[136:137], 0, s[22:23]
	global_load_lds_dwordx4 v[156:157], off
	s_mov_b32 m0, s46
	v_readfirstlane_b32 s46, v168
	v_lshl_add_u64 v[152:153], v[134:135], 0, s[22:23]
	global_load_lds_dwordx4 v[154:155], off
	s_mov_b32 m0, s46
	v_readfirstlane_b32 s46, v167
	v_lshl_add_u64 v[150:151], v[132:133], 0, s[22:23]
	global_load_lds_dwordx4 v[152:153], off
	s_mov_b32 m0, s46
	v_add_u32_e32 v162, v174, v144
	global_load_lds_dwordx4 v[150:151], off
	ds_read_b128 v[150:153], v162 offset:32768
	ds_read_b128 v[154:157], v162 offset:34816
	ds_read_b128 v[158:161], v162 offset:36864
	ds_read_b128 v[162:165], v162 offset:38912
	v_add_u32_e32 v149, v149, v144
	ds_read_b128 v[166:169], v149
	ds_read_b128 v[170:173], v149 offset:2048
	s_waitcnt lgkmcnt(0)
	v_mfma_f32_16x16x32_bf16 v[126:129], v[150:153], v[166:169], v[126:129]
	v_mfma_f32_16x16x32_bf16 v[122:125], v[154:157], v[166:169], v[122:125]
	v_mfma_f32_16x16x32_bf16 v[118:121], v[158:161], v[166:169], v[118:121]
	v_mfma_f32_16x16x32_bf16 v[114:117], v[162:165], v[166:169], v[114:117]
	ds_read_b128 v[166:169], v149 offset:4096
	v_mfma_f32_16x16x32_bf16 v[110:113], v[150:153], v[170:173], v[110:113]
	v_mfma_f32_16x16x32_bf16 v[106:109], v[154:157], v[170:173], v[106:109]
	v_mfma_f32_16x16x32_bf16 v[102:105], v[158:161], v[170:173], v[102:105]
	v_mfma_f32_16x16x32_bf16 v[98:101], v[162:165], v[170:173], v[98:101]
	ds_read_b128 v[170:173], v149 offset:6144
	s_waitcnt lgkmcnt(0)
	v_mfma_f32_16x16x32_bf16 v[94:97], v[150:153], v[166:169], v[94:97]
	v_mfma_f32_16x16x32_bf16 v[90:93], v[154:157], v[166:169], v[90:93]
	v_mfma_f32_16x16x32_bf16 v[86:89], v[158:161], v[166:169], v[86:89]
	v_mfma_f32_16x16x32_bf16 v[82:85], v[162:165], v[166:169], v[82:85]
	ds_read_b128 v[166:169], v149 offset:8192
	v_mfma_f32_16x16x32_bf16 v[78:81], v[150:153], v[170:173], v[78:81]
	v_mfma_f32_16x16x32_bf16 v[74:77], v[154:157], v[170:173], v[74:77]
	v_mfma_f32_16x16x32_bf16 v[70:73], v[158:161], v[170:173], v[70:73]
	v_mfma_f32_16x16x32_bf16 v[66:69], v[162:165], v[170:173], v[66:69]
	ds_read_b128 v[170:173], v149 offset:10240
	s_waitcnt lgkmcnt(0)
	v_mfma_f32_16x16x32_bf16 v[62:65], v[150:153], v[166:169], v[62:65]
	v_mfma_f32_16x16x32_bf16 v[58:61], v[154:157], v[166:169], v[58:61]
	v_mfma_f32_16x16x32_bf16 v[54:57], v[158:161], v[166:169], v[54:57]
	v_mfma_f32_16x16x32_bf16 v[50:53], v[162:165], v[166:169], v[50:53]
	ds_read_b128 v[166:169], v149 offset:12288
	v_mfma_f32_16x16x32_bf16 v[46:49], v[150:153], v[170:173], v[46:49]
	v_mfma_f32_16x16x32_bf16 v[42:45], v[154:157], v[170:173], v[42:45]
	v_mfma_f32_16x16x32_bf16 v[38:41], v[158:161], v[170:173], v[38:41]
	v_mfma_f32_16x16x32_bf16 v[34:37], v[162:165], v[170:173], v[34:37]
	ds_read_b128 v[170:173], v149 offset:14336
	s_waitcnt lgkmcnt(0)
	v_mfma_f32_16x16x32_bf16 v[30:33], v[150:153], v[166:169], v[30:33]
	v_mfma_f32_16x16x32_bf16 v[26:29], v[154:157], v[166:169], v[26:29]
	v_mfma_f32_16x16x32_bf16 v[22:25], v[158:161], v[166:169], v[22:25]
	v_mfma_f32_16x16x32_bf16 v[18:21], v[162:165], v[166:169], v[18:21]
	v_mfma_f32_16x16x32_bf16 v[14:17], v[150:153], v[170:173], v[14:17]
	v_mfma_f32_16x16x32_bf16 v[10:13], v[154:157], v[170:173], v[10:13]
	v_mfma_f32_16x16x32_bf16 v[6:9], v[158:161], v[170:173], v[6:9]
	v_mfma_f32_16x16x32_bf16 v[2:5], v[162:165], v[170:173], v[2:5]
	s_waitcnt vmcnt(0)
	s_add_u32 s22, s22, 0x80
	s_addc_u32 s23, s23, 0
	s_add_i32 s45, s45, 0x10000
	s_cmpk_eq_i32 s22, 0x780
	s_waitcnt vmcnt(0)
	s_barrier
	s_cbranch_scc0 .LBB0_107
	s_branch .LBB0_99

; #define MFMA16(a, b, c) __builtin_amdgcn_mfma_f32_16x16x32_bf16((a), (b), (c), 0, 0, 0)
;     ...
;   for (int kt = 0; kt < nk; ++kt) {
;     const int buf = kt & 1;
;     const char* cA = smem + buf * STAGE + (wm * 32 * MI + r16) * 128;
;     const char* cB = smem + buf * STAGE + 32768 + (wn * 64 + r16) * 128;
; #pragma unroll
;     for (int k2 = 0; k2 < 2; ++k2) {
;       if (k2 == 1 && kt + 1 < nk) STAGE_TILE(buf ^ 1, (kt + 1) * 64)
;       const int po = ((4 * k2 + q4) ^ swz) * 16;
;       bf16x8 bf[4];
; #pragma unroll
;       for (int nt = 0; nt < 4; ++nt) bf[nt] = *(const bf16x8*)(cB + nt * 16 * 128 + po);
;       bf16x8 afc = *(const bf16x8*)(cA + po);
; #pragma unroll
;       for (int a = 0; a < MT; ++a) {
;         bf16x8 afn = afc;
;         if (a + 1 < MT) afn = *(const bf16x8*)(cA + (a + 1) * 16 * 128 + po);
;         __builtin_amdgcn_sched_barrier(0);
; #pragma unroll
;         for (int nt = 0; nt < 4; ++nt) acc[a][nt] = MFMA16(bf[nt], afc, acc[a][nt]);
;         __builtin_amdgcn_sched_barrier(0);
;         afc = afn;
;       }
;     }
;     asm volatile("s_waitcnt vmcnt(0)" ::: "memory");
;     __syncthreads();
;   }
; DI void phase_resid(char* smem, const Params& p, int layer, const bf16_t* A, int K, const bf16_t* W, int gate_idx, bool first) {
;     ...
;   auto ep = [&](int row, int col, float v0, float v1, float v2, float v3) {
;     const int b = row / TT, t = row - b * TT;
;     const float4 g = *(const float4*)(p.mod + (size_t)(layer * 5 + (t < CTXL ? 4 : b)) * 6144 + gate_idx * 1024 + col);
;     const float4 xo = *(const float4*)(xsrc_row(p, first, row) + col);
.LBB0_115:
	s_and_b32 s35, s34, 0x10000
	s_add_i32 s36, s35, 0
	v_add_u32_e32 v78, s36, v51
	v_add_u32_e32 v66, v78, v50
	v_add_u32_e32 v53, s36, v52
	ds_read_b128 v[54:57], v66 offset:32768
	ds_read_b128 v[58:61], v66 offset:34816
	ds_read_b128 v[62:65], v66 offset:36864
	ds_read_b128 v[66:69], v66 offset:38912
	v_add_u32_e32 v74, v53, v50
	ds_read_b128 v[70:73], v74
	ds_read_b128 v[74:77], v74 offset:2048
	s_waitcnt lgkmcnt(1)
	v_mfma_f32_16x16x32_bf16 v[30:33], v[54:57], v[70:73], v[30:33]
	v_mfma_f32_16x16x32_bf16 v[26:29], v[58:61], v[70:73], v[26:29]
	v_mfma_f32_16x16x32_bf16 v[22:25], v[62:65], v[70:73], v[22:25]
	v_mfma_f32_16x16x32_bf16 v[18:21], v[66:69], v[70:73], v[18:21]
	s_waitcnt lgkmcnt(0)
	v_mfma_f32_16x16x32_bf16 v[14:17], v[54:57], v[74:77], v[14:17]
	v_mfma_f32_16x16x32_bf16 v[10:13], v[58:61], v[74:77], v[10:13]
	v_mfma_f32_16x16x32_bf16 v[6:9], v[62:65], v[74:77], v[6:9]
	v_mfma_f32_16x16x32_bf16 v[2:5], v[66:69], v[74:77], v[2:5]
	s_xor_b32 s35, s35, 0x10000
	v_add_u32_e32 v64, s35, v48
	v_add_u32_e32 v68, 0x8000, v64
	v_readfirstlane_b32 s35, v64
	v_add_u32_e32 v67, 0xa000, v64
	v_lshl_add_u64 v[62:63], v[42:43], 0, s[14:15]
	s_mov_b32 m0, s35
	v_readfirstlane_b32 s35, v68
	v_add_u32_e32 v66, 0xc000, v64
	v_lshl_add_u64 v[60:61], v[40:41], 0, s[14:15]
	global_load_lds_dwordx4 v[62:63], off
	s_mov_b32 m0, s35
	v_readfirstlane_b32 s35, v67
	v_add_u32_e32 v65, 0xe000, v64
	v_lshl_add_u64 v[58:59], v[38:39], 0, s[14:15]
	global_load_lds_dwordx4 v[60:61], off
	s_mov_b32 m0, s35
	v_readfirstlane_b32 s35, v66
	v_lshl_add_u64 v[56:57], v[36:37], 0, s[14:15]
	global_load_lds_dwordx4 v[58:59], off
	s_mov_b32 m0, s35
	v_readfirstlane_b32 s35, v65
	v_lshl_add_u64 v[54:55], v[34:35], 0, s[14:15]
	global_load_lds_dwordx4 v[56:57], off
	s_mov_b32 m0, s35
	v_add_u32_e32 v66, v78, v49
	global_load_lds_dwordx4 v[54:55], off
	ds_read_b128 v[54:57], v66 offset:32768
	ds_read_b128 v[58:61], v66 offset:34816
	ds_read_b128 v[62:65], v66 offset:36864
	ds_read_b128 v[66:69], v66 offset:38912
	v_add_u32_e32 v53, v53, v49
	ds_read_b128 v[70:73], v53
	ds_read_b128 v[74:77], v53 offset:2048
	s_waitcnt lgkmcnt(0)
	v_mfma_f32_16x16x32_bf16 v[30:33], v[54:57], v[70:73], v[30:33]
	v_mfma_f32_16x16x32_bf16 v[26:29], v[58:61], v[70:73], v[26:29]
	v_mfma_f32_16x16x32_bf16 v[22:25], v[62:65], v[70:73], v[22:25]
	v_mfma_f32_16x16x32_bf16 v[18:21], v[66:69], v[70:73], v[18:21]
	v_mfma_f32_16x16x32_bf16 v[14:17], v[54:57], v[74:77], v[14:17]
	v_mfma_f32_16x16x32_bf16 v[10:13], v[58:61], v[74:77], v[10:13]
	v_mfma_f32_16x16x32_bf16 v[6:9], v[62:65], v[74:77], v[6:9]
	v_mfma_f32_16x16x32_bf16 v[2:5], v[66:69], v[74:77], v[2:5]
	s_waitcnt vmcnt(0)
	s_add_u32 s14, s14, 0x80
	s_addc_u32 s15, s15, 0
	s_add_i32 s34, s34, 0x10000
	s_cmpk_eq_i32 s14, 0x780
	s_waitcnt vmcnt(0)
	s_barrier
	s_cbranch_scc0 .LBB0_115
	s_add_i32 s14, 0, 0x10000
	v_add_u32_e32 v42, s14, v52
	v_readlane_b32 s14, v254, 18
	s_nop 1
	v_add_u32_e32 v43, s14, v51
	v_add_u32_e32 v48, v43, v50
	ds_read_b128 v[34:37], v48
	ds_read_b128 v[38:41], v48 offset:2048
	ds_read_b128 v[52:55], v48 offset:4096
	ds_read_b128 v[56:59], v48 offset:6144
	v_add_u32_e32 v48, v42, v50
	ds_read_b128 v[60:63], v48
	ds_read_b128 v[64:67], v48 offset:2048
	s_waitcnt lgkmcnt(1)
	v_mfma_f32_16x16x32_bf16 v[30:33], v[34:37], v[60:63], v[30:33]
	v_mfma_f32_16x16x32_bf16 v[26:29], v[38:41], v[60:63], v[26:29]
	v_mfma_f32_16x16x32_bf16 v[22:25], v[52:55], v[60:63], v[22:25]
	v_mfma_f32_16x16x32_bf16 v[18:21], v[56:59], v[60:63], v[18:21]
	s_waitcnt lgkmcnt(0)
	v_mfma_f32_16x16x32_bf16 v[14:17], v[34:37], v[64:67], v[14:17]
	v_mfma_f32_16x16x32_bf16 v[10:13], v[38:41], v[64:67], v[10:13]
	v_mfma_f32_16x16x32_bf16 v[6:9], v[52:55], v[64:67], v[6:9]
	v_mfma_f32_16x16x32_bf16 v[2:5], v[56:59], v[64:67], v[2:5]
	v_add_u32_e32 v43, v43, v49
	ds_read_b128 v[34:37], v43
	ds_read_b128 v[38:41], v43 offset:2048
	ds_read_b128 v[50:53], v43 offset:4096
	ds_read_b128 v[54:57], v43 offset:6144
	v_add_u32_e32 v42, v42, v49
	ds_read_b128 v[58:61], v42
	ds_read_b128 v[62:65], v42 offset:2048
	s_waitcnt lgkmcnt(1)
	v_mfma_f32_16x16x32_bf16 v[30:33], v[34:37], v[58:61], v[30:33]
	v_mfma_f32_16x16x32_bf16 v[26:29], v[38:41], v[58:61], v[26:29]
	v_mfma_f32_16x16x32_bf16 v[22:25], v[50:53], v[58:61], v[22:25]
	v_mfma_f32_16x16x32_bf16 v[18:21], v[54:57], v[58:61], v[18:21]
	s_waitcnt lgkmcnt(0)
	v_mfma_f32_16x16x32_bf16 v[14:17], v[34:37], v[62:65], v[14:17]
	v_mfma_f32_16x16x32_bf16 v[10:13], v[38:41], v[62:65], v[10:13]
	v_mfma_f32_16x16x32_bf16 v[6:9], v[50:53], v[62:65], v[6:9]
	v_mfma_f32_16x16x32_bf16 v[2:5], v[54:57], v[62:65], v[2:5]
	v_or_b32_e32 v35, s23, v46
	v_lshlrev_b32_e32 v34, 6, v47
	v_lshl_add_u32 v54, v44, 5, v35
	v_lshlrev_b32_e32 v35, 2, v45
	v_or3_b32 v38, v34, v35, s22
	v_mul_hi_i32 v34, v54, s1
	v_lshrrev_b32_e32 v35, 31, v34
	v_ashrrev_i32_e32 v34, 11, v34
	v_add_u32_e32 v34, v34, v35
	v_mad_i32_i24 v35, v34, s90, v54
	s_movk_i32 s34, 0x100
	v_cmp_gt_i32_e32 vcc, s34, v35
	v_mov_b32_e32 v55, s20
	v_mov_b32_e32 v56, s21
	v_readlane_b32 s22, v252, 1
	v_cndmask_b32_e32 v190, v55, v56, vcc
	v_readlane_b32 s23, v252, 2
	s_waitcnt vmcnt(0)
	s_barrier
;     ...
;   const int row0 = m0 + wm * 32 * MI + r16, cbw = n0 + wn * 64;
;   if constexpr (std::is_invocable_v<EP, int, int, int, const f32x4&, const f32x4&, const f32x4&, const f32x4&>) {
; #pragma unroll
;     for (int a = 0; a < MT; ++a) ep(row0 + 16 * a, cbw, q4, acc[a][0], acc[a][1], acc[a][2], acc[a][3]);
;   } else {
; #pragma unroll
;     for (int a = 0; a < MT; ++a)
; #pragma unroll
;       for (int nt = 0; nt < 4; ++nt)
;         ep(row0 + 16 * a, cbw + 16 * nt + 4 * q4, acc[a][nt][0], acc[a][nt][1], acc[a][nt][2], acc[a][nt][3]);
; DI void phase_resid(char* smem, const Params& p, int layer, const bf16_t* A, int K, const bf16_t* W, int gate_idx, bool first) {
;     ...
;   auto ep = [&](int row, int col, float v0, float v1, float v2, float v3) {
;     const int b = row / TT, t = row - b * TT;
;     const float4 g = *(const float4*)(p.mod + (size_t)(layer * 5 + (t < CTXL ? 4 : b)) * 6144 + gate_idx * 1024 + col);
;     const float4 xo = *(const float4*)(xsrc_row(p, first, row) + col);
;     *(float4*)(xdst_row(p, row) + col) = make_float4(xo.x + g.x * v0, xo.y + g.y * v1, xo.z + g.z * v2, xo.w + g.w * v3);
;   };
	s_nop 0
	v_lshl_add_u64 v[42:43], s[22:23], 0, v[190:191]
	global_load_dwordx2 v[42:43], v[42:43], off
	v_add_u32_e32 v36, 0xffffff00, v35
	v_ashrrev_i32_e32 v37, 31, v35
	v_readlane_b32 s36, v254, 1
	v_cndmask_b32_e64 v39, v34, 4, vcc
	v_cndmask_b32_e32 v37, 0, v37, vcc
	v_cndmask_b32_e32 v36, v36, v35, vcc
	v_ashrrev_i32_e32 v35, 31, v34
	v_cndmask_b32_e64 v40, 25, 20, vcc
	v_readlane_b32 s37, v254, 2
	v_readlane_b32 s68, v252, 5
	v_lshlrev_b64 v[44:45], v40, v[34:35]
	v_lshlrev_b64 v[46:47], 12, v[36:37]
	v_add_u32_e32 v34, s17, v39
	v_mov_b64_e32 v[36:37], s[36:37]
	s_movk_i32 s35, 0x6000
	v_readlane_b32 s80, v252, 17
	v_readlane_b32 s81, v252, 18
	v_readlane_b32 s82, v252, 19
	v_readlane_b32 s83, v252, 20
	v_mad_i64_i32 v[34:35], s[14:15], v34, s35, v[36:37]
	s_mov_b64 s[36:37], 0x2000
	v_ashrrev_i32_e32 v39, 31, v38
	v_mov_b32_e32 v57, s81
	v_mov_b32_e32 v58, s83
	v_mov_b32_e32 v59, s80
	v_mov_b32_e32 v60, s82
	v_lshl_add_u64 v[40:41], v[34:35], 0, s[36:37]
	v_lshlrev_b64 v[34:35], 2, v[38:39]
	v_cndmask_b32_e32 v51, v57, v58, vcc
	v_cndmask_b32_e32 v50, v59, v60, vcc
	v_lshl_add_u64 v[48:49], v[40:41], 0, v[34:35]
	v_readlane_b32 s38, v254, 3
	v_readlane_b32 s39, v254, 4
	v_readlane_b32 s40, v254, 5
	v_readlane_b32 s41, v254, 6
	v_readlane_b32 s42, v254, 7
	v_readlane_b32 s43, v254, 8
	v_readlane_b32 s44, v254, 9
	v_readlane_b32 s45, v254, 10
	v_readlane_b32 s46, v254, 11
	v_readlane_b32 s47, v254, 12
	v_readlane_b32 s48, v254, 13
	v_readlane_b32 s49, v254, 14
	v_readlane_b32 s50, v254, 15
	v_readlane_b32 s51, v254, 16
	s_add_i32 s30, s30, s27
	s_cmp_ge_i32 s30, s16
	v_readlane_b32 s69, v252, 6
	v_readlane_b32 s70, v252, 7
	v_readlane_b32 s71, v252, 8
	v_readlane_b32 s72, v252, 9
	v_readlane_b32 s73, v252, 10
	v_readlane_b32 s74, v252, 11
	v_readlane_b32 s75, v252, 12
	v_readlane_b32 s76, v252, 13
	v_readlane_b32 s77, v252, 14
	v_readlane_b32 s78, v252, 15
	v_readlane_b32 s79, v252, 16
	s_waitcnt vmcnt(0)
	v_lshl_add_u64 v[42:43], v[42:43], 0, v[44:45]
	v_lshl_add_u64 v[42:43], v[42:43], 0, v[46:47]
	v_lshl_add_u64 v[44:45], v[50:51], 0, v[44:45]
	v_lshl_add_u64 v[42:43], v[42:43], 0, v[34:35]
	v_lshl_add_u64 v[44:45], v[44:45], 0, v[46:47]
	v_lshl_add_u64 v[44:45], v[44:45], 0, v[34:35]
	v_readlane_b32 s36, v255, 12
	v_readlane_b32 s37, v255, 13
	v_readlane_b32 s38, v255, 14
	v_readlane_b32 s39, v255, 15
	v_readlane_b32 s40, v255, 16
	v_readlane_b32 s41, v255, 17
	v_readlane_b32 s42, v255, 18
	v_readlane_b32 s43, v255, 19
	v_readlane_b32 s44, v255, 20
	v_readlane_b32 s45, v255, 21
	v_readlane_b32 s46, v255, 22
	v_readlane_b32 s47, v255, 23
	v_readlane_b32 s48, v255, 24
	v_readlane_b32 s49, v255, 25
	v_readlane_b32 s50, v255, 26
	v_readlane_b32 s51, v255, 27
	global_load_dwordx4 v[156:159], v[48:49], off
	global_load_dwordx4 v[160:163], v[48:49], off offset:64
	global_load_dwordx4 v[164:167], v[48:49], off offset:128
	global_load_dwordx4 v[168:171], v[48:49], off offset:192
	global_load_dwordx4 v[172:175], v[42:43], off
	global_load_dwordx4 v[176:179], v[42:43], off offset:64
	global_load_dwordx4 v[180:183], v[42:43], off offset:128
	global_load_dwordx4 v[184:187], v[42:43], off offset:192
	v_add_co_u32_e32 v42, vcc, 0x10000, v42
	s_nop 1
	v_addc_co_u32_e32 v43, vcc, 0, v43, vcc
	global_load_dwordx4 v[198:201], v[42:43], off
	global_load_dwordx4 v[202:205], v[42:43], off offset:64
	global_load_dwordx4 v[206:209], v[42:43], off offset:128
	global_load_dwordx4 v[210:213], v[42:43], off offset:192
	s_waitcnt vmcnt(4)
	v_pk_fma_f32 v[30:31], v[30:31], v[156:157], v[172:173]
	v_pk_fma_f32 v[32:33], v[32:33], v[158:159], v[174:175]
	v_pk_fma_f32 v[26:27], v[26:27], v[160:161], v[176:177]
	v_pk_fma_f32 v[28:29], v[28:29], v[162:163], v[178:179]
	v_pk_fma_f32 v[22:23], v[22:23], v[164:165], v[180:181]
	v_pk_fma_f32 v[24:25], v[24:25], v[166:167], v[182:183]
	v_pk_fma_f32 v[18:19], v[18:19], v[168:169], v[184:185]
	v_pk_fma_f32 v[20:21], v[20:21], v[170:171], v[186:187]
	global_store_dwordx4 v[44:45], v[30:33], off
	global_store_dwordx4 v[44:45], v[26:29], off offset:64
	global_store_dwordx4 v[44:45], v[22:25], off offset:128
	global_store_dwordx4 v[44:45], v[18:21], off offset:192
	v_add_co_u32_e32 v44, vcc, 0x10000, v44
	s_nop 1
	v_addc_co_u32_e32 v45, vcc, 0, v45, vcc
	s_waitcnt vmcnt(4)
	v_pk_fma_f32 v[14:15], v[14:15], v[156:157], v[198:199]
	v_pk_fma_f32 v[16:17], v[16:17], v[158:159], v[200:201]
	v_pk_fma_f32 v[10:11], v[10:11], v[160:161], v[202:203]
	v_pk_fma_f32 v[12:13], v[12:13], v[162:163], v[204:205]
	v_pk_fma_f32 v[6:7], v[6:7], v[164:165], v[206:207]
	v_pk_fma_f32 v[8:9], v[8:9], v[166:167], v[208:209]
	v_pk_fma_f32 v[2:3], v[2:3], v[168:169], v[210:211]
	v_pk_fma_f32 v[4:5], v[4:5], v[170:171], v[212:213]
	global_store_dwordx4 v[44:45], v[14:17], off
	global_store_dwordx4 v[44:45], v[10:13], off offset:64
	global_store_dwordx4 v[44:45], v[6:9], off offset:128
	global_store_dwordx4 v[44:45], v[2:5], off offset:192
	s_cbranch_scc0 .LBB0_110

; #define MFMA16(a, b, c) __builtin_amdgcn_mfma_f32_16x16x32_bf16((a), (b), (c), 0, 0, 0)
;     ...
;   for (int kt = 0; kt < nk; ++kt) {
;     const int buf = kt & 1;
;     const char* cA = smem + buf * STAGE + (wm * 32 * MI + r16) * 128;
;     const char* cB = smem + buf * STAGE + 32768 + (wn * 64 + r16) * 128;
; #pragma unroll
;     for (int k2 = 0; k2 < 2; ++k2) {
;       if (k2 == 1 && kt + 1 < nk) STAGE_TILE(buf ^ 1, (kt + 1) * 64)
;       const int po = ((4 * k2 + q4) ^ swz) * 16;
;       bf16x8 bf[4];
; #pragma unroll
;       for (int nt = 0; nt < 4; ++nt) bf[nt] = *(const bf16x8*)(cB + nt * 16 * 128 + po);
;       bf16x8 afc = *(const bf16x8*)(cA + po);
; #pragma unroll
;       for (int a = 0; a < MT; ++a) {
;         bf16x8 afn = afc;
;         if (a + 1 < MT) afn = *(const bf16x8*)(cA + (a + 1) * 16 * 128 + po);
;         __builtin_amdgcn_sched_barrier(0);
; #pragma unroll
;         for (int nt = 0; nt < 4; ++nt) acc[a][nt] = MFMA16(bf[nt], afc, acc[a][nt]);
;         __builtin_amdgcn_sched_barrier(0);
;         afc = afn;
;       }
;     }
;     asm volatile("s_waitcnt vmcnt(0)" ::: "memory");
;     __syncthreads();
.LBB0_565:
	s_and_b32 s6, s5, 0x10000
	s_add_i32 s7, s6, 0
	v_add_u32_e32 v190, s7, v146
	v_lshl_add_u64 v[148:149], v[130:131], 0, s[2:3]
	v_add_u32_e32 v164, v190, v145
	v_add_u32_e32 v163, s7, v147
	v_lshl_add_u64 v[160:161], v[148:149], 0, s[24:25]
	v_lshl_add_u64 v[176:177], v[148:149], 0, s[84:85]
	v_lshl_add_u64 v[178:179], v[148:149], 0, s[28:29]
	v_lshl_add_u64 v[180:181], v[148:149], 0, s[18:19]
	ds_read_b128 v[148:151], v164 offset:32768
	ds_read_b128 v[152:155], v164 offset:34816
	ds_read_b128 v[156:159], v164 offset:36864
	ds_read_b128 v[164:167], v164 offset:38912
	v_add_u32_e32 v202, v163, v145
	ds_read_b128 v[168:171], v202
	ds_read_b128 v[172:175], v202 offset:2048
	s_xor_b32 s6, s6, 0x10000
	v_add_u32_e32 v192, s6, v144
	v_add_u32_e32 v193, 0x2000, v192
	v_add_u32_e32 v198, 0x4000, v192
	v_add_u32_e32 v199, 0x6000, v192
	v_lshl_add_u64 v[182:183], v[138:139], 0, s[2:3]
	v_add_u32_e32 v200, 0x8000, v192
	v_lshl_add_u64 v[184:185], v[136:137], 0, s[2:3]
	v_add_u32_e32 v201, 0xa000, v192
	v_lshl_add_u64 v[186:187], v[134:135], 0, s[2:3]
	v_add_u32_e32 v203, 0xc000, v192
	v_lshl_add_u64 v[188:189], v[132:133], 0, s[2:3]
	v_add_u32_e32 v204, 0xe000, v192
	s_waitcnt lgkmcnt(1)
	v_mfma_f32_16x16x32_bf16 v[126:129], v[148:151], v[168:171], v[126:129]
	v_mfma_f32_16x16x32_bf16 v[122:125], v[152:155], v[168:171], v[122:125]
	v_mfma_f32_16x16x32_bf16 v[118:121], v[156:159], v[168:171], v[118:121]
	v_mfma_f32_16x16x32_bf16 v[114:117], v[164:167], v[168:171], v[114:117]
	ds_read_b128 v[168:171], v202 offset:4096
	s_waitcnt lgkmcnt(1)
	v_mfma_f32_16x16x32_bf16 v[110:113], v[148:151], v[172:175], v[110:113]
	v_mfma_f32_16x16x32_bf16 v[106:109], v[152:155], v[172:175], v[106:109]
	v_mfma_f32_16x16x32_bf16 v[102:105], v[156:159], v[172:175], v[102:105]
	v_mfma_f32_16x16x32_bf16 v[98:101], v[164:167], v[172:175], v[98:101]
	ds_read_b128 v[172:175], v202 offset:6144
	s_waitcnt lgkmcnt(1)
	v_mfma_f32_16x16x32_bf16 v[94:97], v[148:151], v[168:171], v[94:97]
	v_mfma_f32_16x16x32_bf16 v[90:93], v[152:155], v[168:171], v[90:93]
	v_mfma_f32_16x16x32_bf16 v[86:89], v[156:159], v[168:171], v[86:89]
	v_mfma_f32_16x16x32_bf16 v[82:85], v[164:167], v[168:171], v[82:85]
	ds_read_b128 v[168:171], v202 offset:8192
	s_waitcnt lgkmcnt(1)
	v_mfma_f32_16x16x32_bf16 v[78:81], v[148:151], v[172:175], v[78:81]
	v_mfma_f32_16x16x32_bf16 v[74:77], v[152:155], v[172:175], v[74:77]
	v_mfma_f32_16x16x32_bf16 v[70:73], v[156:159], v[172:175], v[70:73]
	v_mfma_f32_16x16x32_bf16 v[66:69], v[164:167], v[172:175], v[66:69]
	ds_read_b128 v[172:175], v202 offset:10240
	s_waitcnt lgkmcnt(1)
	v_mfma_f32_16x16x32_bf16 v[62:65], v[148:151], v[168:171], v[62:65]
	v_mfma_f32_16x16x32_bf16 v[58:61], v[152:155], v[168:171], v[58:61]
	v_mfma_f32_16x16x32_bf16 v[54:57], v[156:159], v[168:171], v[54:57]
	v_mfma_f32_16x16x32_bf16 v[50:53], v[164:167], v[168:171], v[50:53]
	ds_read_b128 v[168:171], v202 offset:12288
	s_waitcnt lgkmcnt(1)
	v_mfma_f32_16x16x32_bf16 v[46:49], v[148:151], v[172:175], v[46:49]
	v_mfma_f32_16x16x32_bf16 v[42:45], v[152:155], v[172:175], v[42:45]
	v_mfma_f32_16x16x32_bf16 v[38:41], v[156:159], v[172:175], v[38:41]
	v_mfma_f32_16x16x32_bf16 v[34:37], v[164:167], v[172:175], v[34:37]
	ds_read_b128 v[172:175], v202 offset:14336
	s_waitcnt lgkmcnt(1)
	v_mfma_f32_16x16x32_bf16 v[30:33], v[148:151], v[168:171], v[30:33]
	v_mfma_f32_16x16x32_bf16 v[26:29], v[152:155], v[168:171], v[26:29]
	v_mfma_f32_16x16x32_bf16 v[22:25], v[156:159], v[168:171], v[22:25]
	v_mfma_f32_16x16x32_bf16 v[18:21], v[164:167], v[168:171], v[18:21]
	s_waitcnt lgkmcnt(0)
	v_mfma_f32_16x16x32_bf16 v[14:17], v[148:151], v[172:175], v[14:17]
	v_mfma_f32_16x16x32_bf16 v[10:13], v[152:155], v[172:175], v[10:13]
	v_mfma_f32_16x16x32_bf16 v[6:9], v[156:159], v[172:175], v[6:9]
	v_mfma_f32_16x16x32_bf16 v[2:5], v[164:167], v[172:175], v[2:5]
	v_readfirstlane_b32 s6, v192
	s_mov_b32 m0, s6
	v_readfirstlane_b32 s6, v193
	global_load_lds_dwordx4 v[160:161], off
	s_mov_b32 m0, s6
	v_readfirstlane_b32 s6, v198
	global_load_lds_dwordx4 v[176:177], off
	s_mov_b32 m0, s6
	v_readfirstlane_b32 s6, v199
	global_load_lds_dwordx4 v[178:179], off
	s_mov_b32 m0, s6
	v_readfirstlane_b32 s6, v200
	global_load_lds_dwordx4 v[180:181], off
	s_mov_b32 m0, s6
	v_readfirstlane_b32 s6, v201
	global_load_lds_dwordx4 v[182:183], off
	s_mov_b32 m0, s6
	v_readfirstlane_b32 s6, v203
	global_load_lds_dwordx4 v[184:185], off
	s_mov_b32 m0, s6
	v_readfirstlane_b32 s6, v204
	global_load_lds_dwordx4 v[186:187], off
	s_mov_b32 m0, s6
	v_add_u32_e32 v160, v190, v143
	global_load_lds_dwordx4 v[188:189], off
	ds_read_b128 v[148:151], v160 offset:32768
	ds_read_b128 v[152:155], v160 offset:34816
	ds_read_b128 v[156:159], v160 offset:36864
	ds_read_b128 v[164:167], v160 offset:38912
	v_add_u32_e32 v160, v163, v143
	ds_read_b128 v[168:171], v160
	ds_read_b128 v[172:175], v160 offset:2048
	s_waitcnt lgkmcnt(0)
	v_mfma_f32_16x16x32_bf16 v[126:129], v[148:151], v[168:171], v[126:129]
	v_mfma_f32_16x16x32_bf16 v[122:125], v[152:155], v[168:171], v[122:125]
	v_mfma_f32_16x16x32_bf16 v[118:121], v[156:159], v[168:171], v[118:121]
	v_mfma_f32_16x16x32_bf16 v[114:117], v[164:167], v[168:171], v[114:117]
	ds_read_b128 v[168:171], v160 offset:4096
	v_mfma_f32_16x16x32_bf16 v[110:113], v[148:151], v[172:175], v[110:113]
	v_mfma_f32_16x16x32_bf16 v[106:109], v[152:155], v[172:175], v[106:109]
	v_mfma_f32_16x16x32_bf16 v[102:105], v[156:159], v[172:175], v[102:105]
	v_mfma_f32_16x16x32_bf16 v[98:101], v[164:167], v[172:175], v[98:101]
	ds_read_b128 v[172:175], v160 offset:6144
	s_waitcnt lgkmcnt(0)
; #define MFMA16(a, b, c) __builtin_amdgcn_mfma_f32_16x16x32_bf16((a), (b), (c), 0, 0, 0)
;     ...
;   for (int kt = 0; kt < nk; ++kt) {
;     const int buf = kt & 1;
;     const char* cA = smem + buf * STAGE + (wm * 32 * MI + r16) * 128;
;     const char* cB = smem + buf * STAGE + 32768 + (wn * 64 + r16) * 128;
; #pragma unroll
;     for (int k2 = 0; k2 < 2; ++k2) {
;       if (k2 == 1 && kt + 1 < nk) STAGE_TILE(buf ^ 1, (kt + 1) * 64)
;       const int po = ((4 * k2 + q4) ^ swz) * 16;
;       bf16x8 bf[4];
; #pragma unroll
;       for (int nt = 0; nt < 4; ++nt) bf[nt] = *(const bf16x8*)(cB + nt * 16 * 128 + po);
;       bf16x8 afc = *(const bf16x8*)(cA + po);
; #pragma unroll
;       for (int a = 0; a < MT; ++a) {
;         bf16x8 afn = afc;
;         if (a + 1 < MT) afn = *(const bf16x8*)(cA + (a + 1) * 16 * 128 + po);
;         __builtin_amdgcn_sched_barrier(0);
; #pragma unroll
;         for (int nt = 0; nt < 4; ++nt) acc[a][nt] = MFMA16(bf[nt], afc, acc[a][nt]);
;         __builtin_amdgcn_sched_barrier(0);
;         afc = afn;
;       }
;     }
;     asm volatile("s_waitcnt vmcnt(0)" ::: "memory");
;     __syncthreads();
;   }
	v_mfma_f32_16x16x32_bf16 v[94:97], v[148:151], v[168:171], v[94:97]
	v_mfma_f32_16x16x32_bf16 v[90:93], v[152:155], v[168:171], v[90:93]
	v_mfma_f32_16x16x32_bf16 v[86:89], v[156:159], v[168:171], v[86:89]
	v_mfma_f32_16x16x32_bf16 v[82:85], v[164:167], v[168:171], v[82:85]
	ds_read_b128 v[168:171], v160 offset:8192
	v_mfma_f32_16x16x32_bf16 v[78:81], v[148:151], v[172:175], v[78:81]
	v_mfma_f32_16x16x32_bf16 v[74:77], v[152:155], v[172:175], v[74:77]
	v_mfma_f32_16x16x32_bf16 v[70:73], v[156:159], v[172:175], v[70:73]
	v_mfma_f32_16x16x32_bf16 v[66:69], v[164:167], v[172:175], v[66:69]
	ds_read_b128 v[172:175], v160 offset:10240
	s_waitcnt lgkmcnt(0)
	v_mfma_f32_16x16x32_bf16 v[62:65], v[148:151], v[168:171], v[62:65]
	v_mfma_f32_16x16x32_bf16 v[58:61], v[152:155], v[168:171], v[58:61]
	v_mfma_f32_16x16x32_bf16 v[54:57], v[156:159], v[168:171], v[54:57]
	v_mfma_f32_16x16x32_bf16 v[50:53], v[164:167], v[168:171], v[50:53]
	ds_read_b128 v[168:171], v160 offset:12288
	v_mfma_f32_16x16x32_bf16 v[46:49], v[148:151], v[172:175], v[46:49]
	v_mfma_f32_16x16x32_bf16 v[42:45], v[152:155], v[172:175], v[42:45]
	v_mfma_f32_16x16x32_bf16 v[38:41], v[156:159], v[172:175], v[38:41]
	v_mfma_f32_16x16x32_bf16 v[34:37], v[164:167], v[172:175], v[34:37]
	ds_read_b128 v[172:175], v160 offset:14336
	s_waitcnt lgkmcnt(0)
	v_mfma_f32_16x16x32_bf16 v[30:33], v[148:151], v[168:171], v[30:33]
	v_mfma_f32_16x16x32_bf16 v[26:29], v[152:155], v[168:171], v[26:29]
	v_mfma_f32_16x16x32_bf16 v[22:25], v[156:159], v[168:171], v[22:25]
	v_mfma_f32_16x16x32_bf16 v[18:21], v[164:167], v[168:171], v[18:21]
	v_mfma_f32_16x16x32_bf16 v[14:17], v[148:151], v[172:175], v[14:17]
	v_mfma_f32_16x16x32_bf16 v[10:13], v[152:155], v[172:175], v[10:13]
	v_mfma_f32_16x16x32_bf16 v[6:9], v[156:159], v[172:175], v[6:9]
	v_mfma_f32_16x16x32_bf16 v[2:5], v[164:167], v[172:175], v[2:5]
	s_waitcnt vmcnt(0)
	s_add_u32 s2, s2, 0x80
	s_addc_u32 s3, s3, 0
	s_add_i32 s5, s5, 0x10000
	s_cmpk_eq_i32 s2, 0x780
	s_waitcnt vmcnt(0)
	s_barrier
	s_cbranch_scc0 .LBB0_565
	s_add_i32 s2, 0, 0x10000
	v_add_u32_e32 v138, s2, v147
	v_readlane_b32 s2, v254, 18
	s_nop 1
	v_add_u32_e32 v139, s2, v146
	v_add_u32_e32 v144, v139, v145
	ds_read_b128 v[130:133], v144
	ds_read_b128 v[134:137], v144 offset:2048
	ds_read_b128 v[146:149], v144 offset:4096
	ds_read_b128 v[150:153], v144 offset:6144
	v_add_u32_e32 v144, v138, v145
	ds_read_b128 v[154:157], v144
	ds_read_b128 v[158:161], v144 offset:2048
	s_waitcnt lgkmcnt(1)
	v_mfma_f32_16x16x32_bf16 v[122:125], v[134:137], v[154:157], v[122:125]
	v_mfma_f32_16x16x32_bf16 v[118:121], v[146:149], v[154:157], v[118:121]
	v_mfma_f32_16x16x32_bf16 v[114:117], v[150:153], v[154:157], v[114:117]
	v_mfma_f32_16x16x32_bf16 v[126:129], v[130:133], v[154:157], v[126:129]
	ds_read_b128 v[154:157], v144 offset:4096
	s_waitcnt lgkmcnt(1)
	v_mfma_f32_16x16x32_bf16 v[110:113], v[130:133], v[158:161], v[110:113]
	v_mfma_f32_16x16x32_bf16 v[106:109], v[134:137], v[158:161], v[106:109]
	v_mfma_f32_16x16x32_bf16 v[102:105], v[146:149], v[158:161], v[102:105]
	v_mfma_f32_16x16x32_bf16 v[98:101], v[150:153], v[158:161], v[98:101]
	ds_read_b128 v[158:161], v144 offset:6144
	s_waitcnt lgkmcnt(1)
	v_mfma_f32_16x16x32_bf16 v[94:97], v[130:133], v[154:157], v[94:97]
	v_mfma_f32_16x16x32_bf16 v[90:93], v[134:137], v[154:157], v[90:93]
	v_mfma_f32_16x16x32_bf16 v[86:89], v[146:149], v[154:157], v[86:89]
	v_mfma_f32_16x16x32_bf16 v[82:85], v[150:153], v[154:157], v[82:85]
	ds_read_b128 v[154:157], v144 offset:8192
	s_waitcnt lgkmcnt(1)
	v_mfma_f32_16x16x32_bf16 v[78:81], v[130:133], v[158:161], v[78:81]
	v_mfma_f32_16x16x32_bf16 v[74:77], v[134:137], v[158:161], v[74:77]
	v_mfma_f32_16x16x32_bf16 v[70:73], v[146:149], v[158:161], v[70:73]
	v_mfma_f32_16x16x32_bf16 v[66:69], v[150:153], v[158:161], v[66:69]
	ds_read_b128 v[158:161], v144 offset:10240
	s_waitcnt lgkmcnt(1)
	v_mfma_f32_16x16x32_bf16 v[62:65], v[130:133], v[154:157], v[62:65]
	v_mfma_f32_16x16x32_bf16 v[58:61], v[134:137], v[154:157], v[58:61]
	v_mfma_f32_16x16x32_bf16 v[54:57], v[146:149], v[154:157], v[54:57]
	v_mfma_f32_16x16x32_bf16 v[50:53], v[150:153], v[154:157], v[50:53]
	ds_read_b128 v[154:157], v144 offset:12288
	s_waitcnt lgkmcnt(1)
	v_mfma_f32_16x16x32_bf16 v[46:49], v[130:133], v[158:161], v[46:49]
	v_mfma_f32_16x16x32_bf16 v[42:45], v[134:137], v[158:161], v[42:45]
	v_mfma_f32_16x16x32_bf16 v[38:41], v[146:149], v[158:161], v[38:41]
	v_mfma_f32_16x16x32_bf16 v[34:37], v[150:153], v[158:161], v[34:37]
	ds_read_b128 v[158:161], v144 offset:14336
	s_waitcnt lgkmcnt(1)
	v_mfma_f32_16x16x32_bf16 v[30:33], v[130:133], v[154:157], v[30:33]
	v_mfma_f32_16x16x32_bf16 v[26:29], v[134:137], v[154:157], v[26:29]
	v_mfma_f32_16x16x32_bf16 v[22:25], v[146:149], v[154:157], v[22:25]
	v_mfma_f32_16x16x32_bf16 v[18:21], v[150:153], v[154:157], v[18:21]
	s_waitcnt lgkmcnt(0)
	v_mfma_f32_16x16x32_bf16 v[14:17], v[130:133], v[158:161], v[14:17]
	v_mfma_f32_16x16x32_bf16 v[10:13], v[134:137], v[158:161], v[10:13]
	v_mfma_f32_16x16x32_bf16 v[6:9], v[146:149], v[158:161], v[6:9]
	v_mfma_f32_16x16x32_bf16 v[2:5], v[150:153], v[158:161], v[2:5]
	v_add_u32_e32 v130, v139, v143
	ds_read_b128 v[134:137], v130
	ds_read_b128 v[144:147], v130 offset:2048
	ds_read_b128 v[148:151], v130 offset:4096
	ds_read_b128 v[152:155], v130 offset:6144
	v_add_u32_e32 v138, v138, v143
	ds_read_b128 v[156:159], v138
	ds_read_b128 v[164:167], v138 offset:2048
	s_waitcnt lgkmcnt(1)
	v_mfma_f32_16x16x32_bf16 v[130:133], v[134:137], v[156:159], v[126:129]
	v_mfma_f32_16x16x32_bf16 v[122:125], v[144:147], v[156:159], v[122:125]
	v_mfma_f32_16x16x32_bf16 v[118:121], v[148:151], v[156:159], v[118:121]
	v_mfma_f32_16x16x32_bf16 v[114:117], v[152:155], v[156:159], v[114:117]
	ds_read_b128 v[126:129], v138 offset:4096
	s_waitcnt lgkmcnt(1)
; DI bf16_t f2bf(float x) { return (bf16_t)(pack2(x, 0.f) & 0xffffu); }
;     ...
;   const int row0 = m0 + wm * 32 * MI + r16, cbw = n0 + wn * 64;
;   if constexpr (std::is_invocable_v<EP, int, int, int, const f32x4&, const f32x4&, const f32x4&, const f32x4&>) {
; #pragma unroll
;     for (int a = 0; a < MT; ++a) ep(row0 + 16 * a, cbw, q4, acc[a][0], acc[a][1], acc[a][2], acc[a][3]);
; DI void phase_win(char* smem, const Params& p, int layer) {
;     ...
;   auto ep = [&](int row, int cbw, int q4, const f32x4& c0, const f32x4& c1, const f32x4& c2, const f32x4& c3) {
;     if (cbw > 2432) return;
;     const int b = row / TT, t = row - b * TT;
;     const bool lat = t >= CTXL;
;     const int pos = t - CTXL;
;     float v[16] = {c0[0], c0[1], c0[2], c0[3], c1[0], c1[1], c1[2], c1[3], c2[0], c2[1], c2[2], c2[3], c3[0], c3[1], c3[2], c3[3]};
;     if (cbw >= 640 && cbw < 768) {
;       bf16_t* vp = p.VsT + ((size_t)(b * 2 + ((cbw - 640) >> 6)) * 64 + q4 * 16) * TT + t;
; #pragma unroll
;       for (int i = 0; i < 16; ++i) vp[(size_t)i * TT] = f2bf(v[i]);
;       return;
;     }
;     const bool r16 = cbw >= 256 && cbw < 640, rkr = cbw == 2432;
;     if (rkr && q4 >= 2) return;
;     if (lat && (r16 || rkr)) {
;       const int a = r16 ? (q4 >> 1) : q4;
;       const int pa = a ? (pos & 63) : (pos >> 6);
	v_mfma_f32_16x16x32_bf16 v[110:113], v[134:137], v[164:167], v[110:113]
	v_mfma_f32_16x16x32_bf16 v[106:109], v[144:147], v[164:167], v[106:109]
	v_mfma_f32_16x16x32_bf16 v[102:105], v[148:151], v[164:167], v[102:105]
	v_mfma_f32_16x16x32_bf16 v[98:101], v[152:155], v[164:167], v[98:101]
	ds_read_b128 v[156:159], v138 offset:6144
	s_waitcnt lgkmcnt(1)
	v_mfma_f32_16x16x32_bf16 v[94:97], v[134:137], v[126:129], v[94:97]
	v_mfma_f32_16x16x32_bf16 v[90:93], v[144:147], v[126:129], v[90:93]
	v_mfma_f32_16x16x32_bf16 v[86:89], v[148:151], v[126:129], v[86:89]
	v_mfma_f32_16x16x32_bf16 v[82:85], v[152:155], v[126:129], v[82:85]
	ds_read_b128 v[126:129], v138 offset:8192
	s_waitcnt lgkmcnt(1)
	v_mfma_f32_16x16x32_bf16 v[78:81], v[134:137], v[156:159], v[78:81]
	v_mfma_f32_16x16x32_bf16 v[74:77], v[144:147], v[156:159], v[74:77]
	v_mfma_f32_16x16x32_bf16 v[70:73], v[148:151], v[156:159], v[70:73]
	v_mfma_f32_16x16x32_bf16 v[66:69], v[152:155], v[156:159], v[66:69]
	ds_read_b128 v[156:159], v138 offset:10240
	s_waitcnt lgkmcnt(1)
	v_mfma_f32_16x16x32_bf16 v[62:65], v[134:137], v[126:129], v[62:65]
	v_mfma_f32_16x16x32_bf16 v[58:61], v[144:147], v[126:129], v[58:61]
	v_mfma_f32_16x16x32_bf16 v[54:57], v[148:151], v[126:129], v[54:57]
	v_mfma_f32_16x16x32_bf16 v[50:53], v[152:155], v[126:129], v[50:53]
	ds_read_b128 v[126:129], v138 offset:12288
	s_waitcnt lgkmcnt(1)
	v_mfma_f32_16x16x32_bf16 v[46:49], v[134:137], v[156:159], v[46:49]
	v_mfma_f32_16x16x32_bf16 v[42:45], v[144:147], v[156:159], v[42:45]
	v_mfma_f32_16x16x32_bf16 v[38:41], v[148:151], v[156:159], v[38:41]
	v_mfma_f32_16x16x32_bf16 v[34:37], v[152:155], v[156:159], v[34:37]
	ds_read_b128 v[156:159], v138 offset:14336
	s_waitcnt lgkmcnt(1)
	v_mfma_f32_16x16x32_bf16 v[30:33], v[134:137], v[126:129], v[30:33]
	v_mfma_f32_16x16x32_bf16 v[26:29], v[144:147], v[126:129], v[26:29]
	v_mfma_f32_16x16x32_bf16 v[22:25], v[148:151], v[126:129], v[22:25]
	v_mfma_f32_16x16x32_bf16 v[18:21], v[152:155], v[126:129], v[18:21]
	s_waitcnt lgkmcnt(0)
	v_mfma_f32_16x16x32_bf16 v[14:17], v[134:137], v[156:159], v[14:17]
	v_mfma_f32_16x16x32_bf16 v[10:13], v[144:147], v[156:159], v[10:13]
	v_mfma_f32_16x16x32_bf16 v[6:9], v[148:151], v[156:159], v[6:9]
	v_mfma_f32_16x16x32_bf16 v[2:5], v[152:155], v[156:159], v[2:5]
	s_waitcnt vmcnt(0)
	v_lshl_or_b32 v190, v142, 6, s22
	s_movk_i32 s2, 0x981
	v_cmp_gt_i32_e32 vcc, s2, v190
	s_barrier
	s_and_saveexec_b64 s[96:97], vcc
	s_cbranch_execz .LBB0_557
	v_or_b32_e32 v126, s4, v162
	v_lshl_add_u32 v136, v141, 7, v126
	v_and_b32_e32 v126, 0xffffff80, v190
	s_movk_i32 s2, 0x280
	v_cmp_ne_u32_e64 s[16:17], s2, v126
	s_movk_i32 s2, 0x27f
	v_cmp_lt_i32_e64 s[4:5], s2, v190
	s_movk_i32 s2, 0x980
	v_cmp_ne_u32_e64 s[8:9], s2, v190
	v_cmp_gt_u32_e64 s[6:7], 2, v140
	v_add_u32_e32 v126, 0xffffff00, v190
	v_cmp_eq_u32_e32 vcc, s2, v190
	s_or_b64 s[2:3], s[8:9], s[6:7]
	s_movk_i32 s6, 0x180
	v_cmp_gt_u32_e64 s[12:13], s6, v126
	s_or_b64 s[86:87], vcc, s[12:13]
	v_lshrrev_b32_e32 v160, 6, v126
	v_cndmask_b32_e64 v127, 0, 1, s[12:13]
	v_lshrrev_b32_e32 v127, v127, v140
	v_cmp_eq_u32_e64 s[14:15], 0, v127
	v_add_u32_e32 v127, 0xfffffe00, v190
	v_mul_hi_i32 v126, v136, s1
	s_cmp_eq_u32 s10, 1
	v_lshrrev_b32_e32 v159, 6, v127
	v_lshrrev_b32_e32 v127, 31, v126
	v_ashrrev_i32_e32 v126, 11, v126
	v_lshlrev_b32_e32 v158, 4, v140
	s_movk_i32 s6, 0x1ff
	s_cselect_b64 s[94:95], -1, 0
	s_movk_i32 s10, 0xff
	s_cmpk_gt_u32 s22, 0x7ff
	v_add_u32_e32 v139, v126, v127
	v_and_b32_e32 v161, 16, v158
	v_cmp_lt_i32_e64 s[6:7], s6, v190
	v_cmp_lt_i32_e64 s[10:11], s10, v190
	s_cselect_b64 s[22:23], -1, 0
	v_ashrrev_i32_e32 v135, 31, v190
	v_mov_b32_e32 v134, v190
	v_mad_i32_i24 v138, v139, s80, v136
	s_and_saveexec_b64 s[30:31], s[16:17]
	s_xor_b64 s[30:31], exec, s[30:31]
	s_cbranch_execz .LBB0_594
; DI void phase_win(char* smem, const Params& p, int layer) {
;     ...
;     const bool r16 = cbw >= 256 && cbw < 640, rkr = cbw == 2432;
;     if (rkr && q4 >= 2) return;
;     if (lat && (r16 || rkr)) {
;       const int a = r16 ? (q4 >> 1) : q4;
;       const int pa = a ? (pos & 63) : (pos >> 6);
;       const float* tab = r16 ? p.ropeS + 2 * (pa * 16 + (q4 & 1) * 8) : p.ropeM + 2 * (pa * 8);
; #pragma unroll
;       for (int k = 0; k < 4; ++k) {
;         const float4 cs = *(const float4*)(tab + 4 * k);
;         const float x0 = v[4 * k], x1 = v[4 * k + 1], x2 = v[4 * k + 2], x3 = v[4 * k + 3];
;         v[4 * k] = x0 * cs.x - x1 * cs.y; v[4 * k + 1] = x1 * cs.x + x0 * cs.y;
;         v[4 * k + 2] = x2 * cs.z - x3 * cs.w; v[4 * k + 3] = x3 * cs.z + x2 * cs.w;
;       }
;     }
	s_and_saveexec_b64 s[52:53], s[2:3]
	s_cbranch_execz .LBB0_593
	s_movk_i32 s45, 0xff
	v_cmp_lt_i32_e32 vcc, s45, v138
	s_and_b64 s[46:47], s[86:87], vcc
	v_mov_b32_e32 v140, v131
	v_mov_b32_e32 v141, v133
	v_mov_b32_e32 v142, v123
	v_mov_b32_e32 v143, v125
	v_mov_b32_e32 v144, v119
	v_mov_b32_e32 v145, v121
	v_mov_b32_e32 v154, v115
	v_mov_b32_e32 v155, v117
	v_mov_b32_e32 v146, v130
	v_mov_b32_e32 v147, v132
	v_mov_b32_e32 v148, v122
	v_mov_b32_e32 v149, v124
	v_mov_b32_e32 v150, v118
	v_mov_b32_e32 v151, v120
	v_mov_b32_e32 v152, v114
	v_mov_b32_e32 v153, v116
	s_and_saveexec_b64 s[54:55], s[46:47]
	s_cbranch_execz .LBB0_571
	v_readlane_b32 s46, v252, 1
	v_cndmask_b32_e64 v128, v238, v240, s[12:13]
	v_mov_b32_e32 v129, v191
	v_readlane_b32 s47, v252, 2
	v_add_u32_e32 v126, 0xffffff00, v138
	v_lshrrev_b32_e32 v126, 6, v126
	v_lshl_add_u64 v[128:129], s[46:47], 0, v[128:129]
	global_load_dwordx2 v[128:129], v[128:129], off
	v_cndmask_b32_e64 v126, v162, v126, s[14:15]
	v_lshlrev_b32_e32 v127, 4, v126
	v_lshl_or_b32 v126, v126, 5, v161
	v_cndmask_b32_e64 v126, v127, v126, s[12:13]
	v_mov_b32_e32 v127, v191
	v_mov_b32_e32 v182, v130
	v_mov_b32_e32 v183, v133
	v_mov_b32_e32 v130, v131
	v_mov_b32_e32 v131, v132
	s_waitcnt vmcnt(0)
	v_lshl_add_u64 v[156:157], v[126:127], 2, v[128:129]
	global_load_dwordx4 v[126:129], v[156:157], off offset:48
	global_load_dwordx4 v[164:167], v[156:157], off offset:32
	global_load_dwordx4 v[168:171], v[156:157], off offset:16
	global_load_dwordx4 v[172:175], v[156:157], off
	s_waitcnt vmcnt(3)
	v_mov_b32_e32 v156, v127
	s_waitcnt vmcnt(2)
	v_mov_b32_e32 v180, v165
	s_waitcnt vmcnt(1)
	v_mov_b32_e32 v178, v169
	s_waitcnt vmcnt(0)
	v_mov_b32_e32 v132, v172
	v_mov_b32_e32 v133, v175
	v_mov_b32_e32 v176, v173
	v_mov_b32_e32 v177, v174
	v_pk_mul_f32 v[130:131], v[130:131], v[132:133]
	v_mov_b32_e32 v132, v173
	v_pk_mul_f32 v[132:133], v[140:141], v[132:133]
	v_pk_fma_f32 v[140:141], v[182:183], v[176:177], v[130:131]
	v_mov_b32_e32 v130, v122
	v_mov_b32_e32 v131, v125
	v_mov_b32_e32 v122, v123
	v_mov_b32_e32 v123, v124
	v_mov_b32_e32 v124, v168
	v_mov_b32_e32 v125, v171
	v_mov_b32_e32 v179, v170
	v_pk_mul_f32 v[122:123], v[122:123], v[124:125]
	v_mov_b32_e32 v124, v169
	v_pk_mul_f32 v[124:125], v[142:143], v[124:125]
	v_pk_fma_f32 v[142:143], v[130:131], v[178:179], v[122:123]
	v_mov_b32_e32 v122, v118
	v_mov_b32_e32 v123, v121
	v_mov_b32_e32 v118, v119
	v_mov_b32_e32 v119, v120
	v_mov_b32_e32 v120, v164
	v_mov_b32_e32 v121, v167
	v_mov_b32_e32 v181, v166
	v_pk_mul_f32 v[118:119], v[118:119], v[120:121]
	v_mov_b32_e32 v120, v165
	v_pk_mul_f32 v[120:121], v[144:145], v[120:121]
	v_pk_fma_f32 v[144:145], v[122:123], v[180:181], v[118:119]
	v_mov_b32_e32 v118, v114
	v_mov_b32_e32 v119, v117
	v_mov_b32_e32 v114, v115
	v_mov_b32_e32 v115, v116
	v_mov_b32_e32 v116, v126
	v_mov_b32_e32 v117, v129
	v_pk_mul_f32 v[114:115], v[114:115], v[116:117]
	v_mov_b32_e32 v116, v127
	v_mov_b32_e32 v157, v128
	v_mov_b32_e32 v173, v174
	v_mov_b32_e32 v169, v170
	v_mov_b32_e32 v165, v166
	v_pk_mul_f32 v[116:117], v[154:155], v[116:117]
	v_mov_b32_e32 v127, v128
	v_pk_fma_f32 v[146:147], v[146:147], v[172:173], v[132:133] neg_lo:[0,0,1] neg_hi:[0,0,1]
	v_pk_fma_f32 v[148:149], v[148:149], v[168:169], v[124:125] neg_lo:[0,0,1] neg_hi:[0,0,1]
	v_pk_fma_f32 v[150:151], v[150:151], v[164:165], v[120:121] neg_lo:[0,0,1] neg_hi:[0,0,1]
	v_pk_fma_f32 v[152:153], v[152:153], v[126:127], v[116:117] neg_lo:[0,0,1] neg_hi:[0,0,1]
	v_pk_fma_f32 v[154:155], v[118:119], v[156:157], v[114:115]

; #define MFMA16(a, b, c) __builtin_amdgcn_mfma_f32_16x16x32_bf16((a), (b), (c), 0, 0, 0)
;     ...
;   for (int kt = 0; kt < nk; ++kt) {
;     const int buf = kt & 1;
;     const char* cA = smem + buf * STAGE + (wm * 32 * MI + r16) * 128;
;     const char* cB = smem + buf * STAGE + 32768 + (wn * 64 + r16) * 128;
; #pragma unroll
;     for (int k2 = 0; k2 < 2; ++k2) {
;       if (k2 == 1 && kt + 1 < nk) STAGE_TILE(buf ^ 1, (kt + 1) * 64)
;       const int po = ((4 * k2 + q4) ^ swz) * 16;
;       bf16x8 bf[4];
; #pragma unroll
;       for (int nt = 0; nt < 4; ++nt) bf[nt] = *(const bf16x8*)(cB + nt * 16 * 128 + po);
;       bf16x8 afc = *(const bf16x8*)(cA + po);
; #pragma unroll
;       for (int a = 0; a < MT; ++a) {
;         bf16x8 afn = afc;
;         if (a + 1 < MT) afn = *(const bf16x8*)(cA + (a + 1) * 16 * 128 + po);
;         __builtin_amdgcn_sched_barrier(0);
; #pragma unroll
;         for (int nt = 0; nt < 4; ++nt) acc[a][nt] = MFMA16(bf[nt], afc, acc[a][nt]);
;         __builtin_amdgcn_sched_barrier(0);
;         afc = afn;
;       }
;     }
;     asm volatile("s_waitcnt vmcnt(0)" ::: "memory");
;     __syncthreads();
;   }
.LBB0_807:
	s_and_b32 s8, s7, 0x10000
	s_add_i32 s9, s8, 0
	v_add_u32_e32 v88, s9, v51
	v_add_u32_e32 v66, v88, v50
	v_add_u32_e32 v53, s9, v52
	ds_read_b128 v[54:57], v66 offset:32768
	ds_read_b128 v[58:61], v66 offset:34816
	ds_read_b128 v[62:65], v66 offset:36864
	ds_read_b128 v[66:69], v66 offset:38912
	v_add_u32_e32 v74, v53, v50
	ds_read_b128 v[70:73], v74
	ds_read_b128 v[74:77], v74 offset:2048
	s_xor_b32 s8, s8, 0x10000
	v_add_u32_e32 v89, s8, v48
	v_lshl_add_u64 v[78:79], v[42:43], 0, s[4:5]
	v_lshl_add_u64 v[80:81], v[40:41], 0, s[4:5]
	v_add_u32_e32 v90, 0x8000, v89
	v_lshl_add_u64 v[82:83], v[38:39], 0, s[4:5]
	v_add_u32_e32 v91, 0xa000, v89
	v_lshl_add_u64 v[84:85], v[36:37], 0, s[4:5]
	v_add_u32_e32 v92, 0xc000, v89
	v_lshl_add_u64 v[86:87], v[34:35], 0, s[4:5]
	v_add_u32_e32 v93, 0xe000, v89
	s_waitcnt lgkmcnt(1)
	v_mfma_f32_16x16x32_bf16 v[30:33], v[54:57], v[70:73], v[30:33]
	v_mfma_f32_16x16x32_bf16 v[26:29], v[58:61], v[70:73], v[26:29]
	v_mfma_f32_16x16x32_bf16 v[22:25], v[62:65], v[70:73], v[22:25]
	v_mfma_f32_16x16x32_bf16 v[18:21], v[66:69], v[70:73], v[18:21]
	s_waitcnt lgkmcnt(0)
	v_mfma_f32_16x16x32_bf16 v[14:17], v[54:57], v[74:77], v[14:17]
	v_mfma_f32_16x16x32_bf16 v[10:13], v[58:61], v[74:77], v[10:13]
	v_mfma_f32_16x16x32_bf16 v[6:9], v[62:65], v[74:77], v[6:9]
	v_mfma_f32_16x16x32_bf16 v[2:5], v[66:69], v[74:77], v[2:5]
	v_readfirstlane_b32 s8, v89
	s_mov_b32 m0, s8
	v_readfirstlane_b32 s8, v90
	global_load_lds_dwordx4 v[78:79], off
	s_mov_b32 m0, s8
	v_readfirstlane_b32 s8, v91
	global_load_lds_dwordx4 v[80:81], off
	s_mov_b32 m0, s8
	v_readfirstlane_b32 s8, v92
	global_load_lds_dwordx4 v[82:83], off
	s_mov_b32 m0, s8
	v_readfirstlane_b32 s8, v93
	global_load_lds_dwordx4 v[84:85], off
	s_mov_b32 m0, s8
	v_add_u32_e32 v66, v88, v49
	global_load_lds_dwordx4 v[86:87], off
	ds_read_b128 v[54:57], v66 offset:32768
	ds_read_b128 v[58:61], v66 offset:34816
	ds_read_b128 v[62:65], v66 offset:36864
	ds_read_b128 v[66:69], v66 offset:38912
	v_add_u32_e32 v53, v53, v49
	ds_read_b128 v[70:73], v53
	ds_read_b128 v[74:77], v53 offset:2048
	s_waitcnt lgkmcnt(0)
	v_mfma_f32_16x16x32_bf16 v[30:33], v[54:57], v[70:73], v[30:33]
	v_mfma_f32_16x16x32_bf16 v[26:29], v[58:61], v[70:73], v[26:29]
	v_mfma_f32_16x16x32_bf16 v[22:25], v[62:65], v[70:73], v[22:25]
	v_mfma_f32_16x16x32_bf16 v[18:21], v[66:69], v[70:73], v[18:21]
	v_mfma_f32_16x16x32_bf16 v[14:17], v[54:57], v[74:77], v[14:17]
	v_mfma_f32_16x16x32_bf16 v[10:13], v[58:61], v[74:77], v[10:13]
	v_mfma_f32_16x16x32_bf16 v[6:9], v[62:65], v[74:77], v[6:9]
	v_mfma_f32_16x16x32_bf16 v[2:5], v[66:69], v[74:77], v[2:5]
	s_waitcnt vmcnt(0)
	s_add_u32 s4, s4, 0x80
	s_addc_u32 s5, s5, 0
	s_add_i32 s7, s7, 0x10000
	s_cmpk_eq_i32 s4, 0x780
	s_waitcnt vmcnt(0)
	s_barrier
	s_cbranch_scc0 .LBB0_807
	s_add_i32 s4, 0, 0x10000
	v_add_u32_e32 v42, s4, v52
	v_readlane_b32 s4, v254, 18
	v_add_u32_e32 v48, v42, v50
	s_nop 0
	v_add_u32_e32 v43, s4, v51
	v_add_u32_e32 v54, v43, v50
	ds_read_b128 v[34:37], v54 offset:6144
	ds_read_b128 v[38:41], v54 offset:4096
	ds_read_b128 v[50:53], v54 offset:2048
	ds_read_b128 v[54:57], v54
	ds_read_b128 v[58:61], v48
	ds_read_b128 v[62:65], v48 offset:2048
	s_waitcnt lgkmcnt(1)
	v_mfma_f32_16x16x32_bf16 v[26:29], v[50:53], v[58:61], v[26:29]
	v_mfma_f32_16x16x32_bf16 v[22:25], v[38:41], v[58:61], v[22:25]
	v_mfma_f32_16x16x32_bf16 v[18:21], v[34:37], v[58:61], v[18:21]
	v_mfma_f32_16x16x32_bf16 v[30:33], v[54:57], v[58:61], v[30:33]
	s_waitcnt lgkmcnt(0)
	v_mfma_f32_16x16x32_bf16 v[14:17], v[54:57], v[62:65], v[14:17]
	v_mfma_f32_16x16x32_bf16 v[10:13], v[50:53], v[62:65], v[10:13]
	v_mfma_f32_16x16x32_bf16 v[6:9], v[38:41], v[62:65], v[6:9]
	v_mfma_f32_16x16x32_bf16 v[2:5], v[34:37], v[62:65], v[2:5]
	v_add_u32_e32 v35, v43, v49
	v_add_u32_e32 v34, v42, v49
	ds_read_b128 v[38:41], v35 offset:6144
	ds_read_b128 v[48:51], v35 offset:4096
	ds_read_b128 v[52:55], v35 offset:2048
	ds_read_b128 v[56:59], v35
	ds_read_b128 v[60:63], v34
	ds_read_b128 v[64:67], v34 offset:2048
	s_waitcnt lgkmcnt(1)
	v_mfma_f32_16x16x32_bf16 v[34:37], v[56:59], v[60:63], v[30:33]
	v_mfma_f32_16x16x32_bf16 v[26:29], v[52:55], v[60:63], v[26:29]
	v_mfma_f32_16x16x32_bf16 v[22:25], v[48:51], v[60:63], v[22:25]
	v_mfma_f32_16x16x32_bf16 v[18:21], v[38:41], v[60:63], v[18:21]
	s_waitcnt lgkmcnt(0)
	v_mfma_f32_16x16x32_bf16 v[14:17], v[56:59], v[64:67], v[14:17]
	v_mfma_f32_16x16x32_bf16 v[10:13], v[52:55], v[64:67], v[10:13]
	v_mfma_f32_16x16x32_bf16 v[6:9], v[48:51], v[64:67], v[6:9]
	v_mfma_f32_16x16x32_bf16 v[2:5], v[38:41], v[64:67], v[2:5]
	s_waitcnt vmcnt(0)
	v_lshl_or_b32 v190, v47, 6, s30
	s_movk_i32 s4, 0x981
	v_cmp_gt_i32_e32 vcc, s4, v190
	s_barrier
; DI bf16_t f2bf(float x) { return (bf16_t)(pack2(x, 0.f) & 0xffffu); }
; DI void phase_win(char* smem, const Params& p, int layer) {
;     ...
;   auto ep = [&](int row, int cbw, int q4, const f32x4& c0, const f32x4& c1, const f32x4& c2, const f32x4& c3) {
;     if (cbw > 2432) return;
;     const int b = row / TT, t = row - b * TT;
;     const bool lat = t >= CTXL;
;     const int pos = t - CTXL;
;     float v[16] = {c0[0], c0[1], c0[2], c0[3], c1[0], c1[1], c1[2], c1[3], c2[0], c2[1], c2[2], c2[3], c3[0], c3[1], c3[2], c3[3]};
;     if (cbw >= 640 && cbw < 768) {
;       bf16_t* vp = p.VsT + ((size_t)(b * 2 + ((cbw - 640) >> 6)) * 64 + q4 * 16) * TT + t;
; #pragma unroll
;       for (int i = 0; i < 16; ++i) vp[(size_t)i * TT] = f2bf(v[i]);
;       return;
;     }
;     const bool r16 = cbw >= 256 && cbw < 640, rkr = cbw == 2432;
;     if (rkr && q4 >= 2) return;
;     if (lat && (r16 || rkr)) {
;       const int a = r16 ? (q4 >> 1) : q4;
;       const int pa = a ? (pos & 63) : (pos >> 6);
;       const float* tab = r16 ? p.ropeS + 2 * (pa * 16 + (q4 & 1) * 8) : p.ropeM + 2 * (pa * 8);
; #pragma unroll
;       for (int k = 0; k < 4; ++k) {
;         const float4 cs = *(const float4*)(tab + 4 * k);
;         const float x0 = v[4 * k], x1 = v[4 * k + 1], x2 = v[4 * k + 2], x3 = v[4 * k + 3];
;         v[4 * k] = x0 * cs.x - x1 * cs.y; v[4 * k + 1] = x1 * cs.x + x0 * cs.y;
;         v[4 * k + 2] = x2 * cs.z - x3 * cs.w; v[4 * k + 3] = x3 * cs.z + x2 * cs.w;
;       }
;     }
	s_and_saveexec_b64 s[86:87], vcc
	s_cbranch_execz .LBB0_801
	v_or_b32_e32 v30, s6, v46
	s_movk_i32 s6, 0x980
	v_lshl_add_u32 v40, v45, 5, v30
	v_and_b32_e32 v30, 0xffffff80, v190
	s_movk_i32 s4, 0x280
	v_cmp_eq_u32_e32 vcc, s6, v190
	v_cmp_ne_u32_e64 s[8:9], s6, v190
	v_cmp_gt_u32_e64 s[6:7], 2, v44
	v_cmp_ne_u32_e64 s[16:17], s4, v30
	v_add_u32_e32 v30, 0xffffff00, v190
	s_or_b64 s[96:97], s[8:9], s[6:7]
	s_movk_i32 s6, 0x180
	v_cmp_gt_u32_e64 s[12:13], s6, v30
	s_or_b64 s[94:95], vcc, s[12:13]
	v_lshrrev_b32_e32 v64, 6, v30
	v_cndmask_b32_e64 v31, 0, 1, s[12:13]
	v_lshrrev_b32_e32 v31, v31, v44
	v_cmp_eq_u32_e64 s[14:15], 0, v31
	v_add_u32_e32 v31, 0xfffffe00, v190
	v_mul_hi_i32 v30, v40, s1
	s_cmp_eq_u32 s10, 1
	v_lshrrev_b32_e32 v63, 6, v31
	v_lshrrev_b32_e32 v31, 31, v30
	v_ashrrev_i32_e32 v30, 11, v30
	s_movk_i32 s4, 0x27f
	v_lshlrev_b32_e32 v62, 4, v44
	s_movk_i32 s6, 0x1ff
	s_cselect_b64 s[92:93], -1, 0
	s_movk_i32 s10, 0xff
	s_cmpk_gt_u32 s30, 0x7ff
	s_movk_i32 s30, 0xdf00
	v_add_u32_e32 v41, v30, v31
	v_cmp_lt_i32_e64 s[4:5], s4, v190
	v_and_b32_e32 v65, 16, v62
	v_cmp_lt_i32_e64 s[6:7], s6, v190
	v_cmp_lt_i32_e64 s[10:11], s10, v190
	s_cselect_b64 s[90:91], -1, 0
	v_ashrrev_i32_e32 v39, 31, v190
	v_mov_b32_e32 v38, v190
	s_movk_i32 s38, 0xdf00
	v_mad_i32_i24 v42, v41, s30, v40
	s_and_saveexec_b64 s[30:31], s[16:17]
	s_xor_b64 s[30:31], exec, s[30:31]
	s_cbranch_execz .LBB0_836
	s_and_saveexec_b64 s[52:53], s[96:97]
	s_cbranch_execz .LBB0_835
	s_movk_i32 s37, 0xff
	v_cmp_lt_i32_e32 vcc, s37, v42
	s_and_b64 s[40:41], s[94:95], vcc
	v_mov_b32_e32 v44, v35
	v_mov_b32_e32 v45, v37
	v_mov_b32_e32 v46, v27
	v_mov_b32_e32 v47, v29
	v_mov_b32_e32 v48, v23
	v_mov_b32_e32 v49, v25
	v_mov_b32_e32 v58, v19
	v_mov_b32_e32 v59, v21
	v_mov_b32_e32 v50, v34
	v_mov_b32_e32 v51, v36
	v_mov_b32_e32 v52, v26
	v_mov_b32_e32 v53, v28
	v_mov_b32_e32 v54, v22
	v_mov_b32_e32 v55, v24
	v_mov_b32_e32 v56, v18
	v_mov_b32_e32 v57, v20
	s_and_saveexec_b64 s[54:55], s[40:41]
	s_cbranch_execz .LBB0_813
	v_readlane_b32 s40, v252, 1
	v_cndmask_b32_e64 v32, v238, v240, s[12:13]
	v_mov_b32_e32 v33, v191
	v_readlane_b32 s41, v252, 2
	v_add_u32_e32 v30, 0xffffff00, v42
	v_and_b32_e32 v31, 47, v40
	v_lshl_add_u64 v[32:33], s[40:41], 0, v[32:33]
	global_load_dwordx2 v[32:33], v[32:33], off
	v_lshrrev_b32_e32 v30, 6, v30
	v_cndmask_b32_e64 v30, v31, v30, s[14:15]
	v_lshlrev_b32_e32 v31, 4, v30
	v_lshl_or_b32 v30, v30, 5, v65
	v_cndmask_b32_e64 v30, v31, v30, s[12:13]
	v_mov_b32_e32 v31, v191
	v_mov_b32_e32 v84, v34
	v_mov_b32_e32 v85, v37
	v_mov_b32_e32 v34, v35
	v_mov_b32_e32 v35, v36
	s_waitcnt vmcnt(0)
	v_lshl_add_u64 v[60:61], v[30:31], 2, v[32:33]
	global_load_dwordx4 v[30:33], v[60:61], off offset:48
	global_load_dwordx4 v[66:69], v[60:61], off offset:32
	global_load_dwordx4 v[70:73], v[60:61], off offset:16
	global_load_dwordx4 v[74:77], v[60:61], off
	s_waitcnt vmcnt(3)
	v_mov_b32_e32 v60, v31
	s_waitcnt vmcnt(2)
	v_mov_b32_e32 v82, v67
	s_waitcnt vmcnt(1)
	v_mov_b32_e32 v80, v71
	s_waitcnt vmcnt(0)
	v_mov_b32_e32 v36, v74
	v_mov_b32_e32 v37, v77
	v_mov_b32_e32 v78, v75
	v_mov_b32_e32 v79, v76
	v_pk_mul_f32 v[34:35], v[34:35], v[36:37]
	v_mov_b32_e32 v36, v75
	v_pk_mul_f32 v[36:37], v[44:45], v[36:37]
	v_pk_fma_f32 v[44:45], v[84:85], v[78:79], v[34:35]
	v_mov_b32_e32 v34, v26
	v_mov_b32_e32 v35, v29
	v_mov_b32_e32 v26, v27
	v_mov_b32_e32 v27, v28
	v_mov_b32_e32 v28, v70
	v_mov_b32_e32 v29, v73
	v_mov_b32_e32 v81, v72
	v_pk_mul_f32 v[26:27], v[26:27], v[28:29]
	v_mov_b32_e32 v28, v71
	v_pk_mul_f32 v[28:29], v[46:47], v[28:29]
	v_pk_fma_f32 v[46:47], v[34:35], v[80:81], v[26:27]
	v_mov_b32_e32 v26, v22
	v_mov_b32_e32 v27, v25
	v_mov_b32_e32 v22, v23
	v_mov_b32_e32 v23, v24
	v_mov_b32_e32 v24, v66
	v_mov_b32_e32 v25, v69
	v_mov_b32_e32 v83, v68
	v_pk_mul_f32 v[22:23], v[22:23], v[24:25]
	v_mov_b32_e32 v24, v67
	v_pk_mul_f32 v[24:25], v[48:49], v[24:25]
	v_pk_fma_f32 v[48:49], v[26:27], v[82:83], v[22:23]
	v_mov_b32_e32 v22, v18
	v_mov_b32_e32 v23, v21
	v_mov_b32_e32 v18, v19
	v_mov_b32_e32 v19, v20
	v_mov_b32_e32 v20, v30
	v_mov_b32_e32 v21, v33
	v_pk_mul_f32 v[18:19], v[18:19], v[20:21]
	v_mov_b32_e32 v20, v31
	v_mov_b32_e32 v61, v32
	v_mov_b32_e32 v75, v76
	v_mov_b32_e32 v71, v72
	v_mov_b32_e32 v67, v68
	v_pk_mul_f32 v[20:21], v[58:59], v[20:21]
	v_mov_b32_e32 v31, v32
	v_pk_fma_f32 v[50:51], v[50:51], v[74:75], v[36:37] neg_lo:[0,0,1] neg_hi:[0,0,1]
	v_pk_fma_f32 v[52:53], v[52:53], v[70:71], v[28:29] neg_lo:[0,0,1] neg_hi:[0,0,1]
	v_pk_fma_f32 v[54:55], v[54:55], v[66:67], v[24:25] neg_lo:[0,0,1] neg_hi:[0,0,1]
	v_pk_fma_f32 v[56:57], v[56:57], v[30:31], v[20:21] neg_lo:[0,0,1] neg_hi:[0,0,1]
	v_pk_fma_f32 v[58:59], v[22:23], v[60:61], v[18:19]
